# ring gathers + coalesced META via ds_bpermute + attention row-max via max3/permlane swaps + NaN-canonicalisation v_max removed
# speedup vs baseline: 1.0269x; 1.0245x over previous
; DI int otid_w(int wave) { unsigned z = 0u; asm volatile("" : "+v"(z)); int t = wave * 64 + (int)__builtin_amdgcn_mbcnt_hi(~0u, __builtin_amdgcn_mbcnt_lo(~0u, z)); asm volatile("" : "+v"(t)); return t; }
; #define PEER_META(T, IA, IB, HA, HB) do { const int _t = (T) < TTOK ? (T) : wslot; \
;     IA = *(const u32x4*)(W_IDX(p) + (size_t)_t * 128 + r * 16); IB = *(const u32x4*)(W_IDX(p) + (size_t)_t * 128 + r * 16 + 8); \
;     const u16* _hp = W_H(p) + (size_t)_t * DM + x * 128 + 16 * c; HA = *(const u32x4*)(_hp); HB = *(const u32x4*)(_hp + 8); } while (0)
; #define PEER_GATHER(TAB, IA, IB, RR) do { _Pragma("unroll") for (int g = 0; g < 16; ++g) { \
;     const unsigned _w = (g < 8 ? IA : IB)[(g >> 1) & 3]; RR[g] = *(const u32x4*)((TAB) + row_off(_w, c16, (g & 1) != 0)); } } while (0)
; DI void phase_peer_dots(const Params& p, int layer, int wave) {
;   const int tid = otid_w(wave), lane = tid & 63, wid = wave, c = lane & 7, r = lane >> 3;
;   const int x = blockIdx.x & 7, wslot = (blockIdx.x >> 3) * 8 + wid, nslot = (gridDim.x >> 3) * 8;
;   const unsigned char* ub = W_UB(p) + (size_t)x * (PEER_N * 128);
;   const unsigned c16 = (unsigned)c * 16u;
;   u16* pd = W_Y(p);
;   u32x4 iAa, iBa, iAb, iBb;
;   u32x4 hAa, hBa, hAb, hBb, rrA[16], rrB[16];
;   int xq[4];
;   float xscale;
;     ...
;   int t = wslot;
;   PEER_META(t, iAa, iBa, hAa, hBa);
;   PEER_META(t + nslot, iAb, iBb, hAb, hBb);
;   PEER_GATHER(ub, iAa, iBa, rrA);
.LBB0_125:
	s_and_b64 vcc, exec, s[0:1]
	s_cbranch_vccz .LBB0_133
	s_cmp_gt_i32 s96, 4
	s_mov_b64 s[56:57], -1
	s_cbranch_scc0 .LBB0_133
	s_waitcnt vmcnt(0)
	v_mov_b32_e32 v0, v177
	v_readlane_b32 s0, v253, 51
	v_mbcnt_lo_u32_b32 v0, -1, v0
	v_mbcnt_hi_u32_b32 v0, -1, v0
	v_add_u32_e32 v88, s64, v0
	v_readlane_b32 s1, v253, 52
	v_lshlrev_b32_e32 v0, 1, v88
	v_and_b32_e32 v0, 0x70, v0
	v_lshlrev_b32_e32 v176, 1, v0
	s_waitcnt lgkmcnt(0)
	s_nop 0
	global_load_dwordx4 v[4:7], v176, s[0:1]
	global_load_dwordx4 v[10:13], v176, s[0:1] offset:16
	v_readlane_b32 s0, v253, 56
	v_readlane_b32 s1, v253, 57
	v_and_b32_e32 v89, 7, v88
	s_andn2_b64 vcc, exec, s[0:1]
	v_lshlrev_b32_e32 v160, 4, v89
	s_waitcnt vmcnt(1)
	v_mad_u32_u16 v0, v4, v195, v160
	v_mad_u32_u16 v1, v4, v195, v160 op_sel:[1,0,0,0]
	v_mad_u32_u16 v2, v5, v195, v160
	v_mad_u32_u16 v3, v5, v195, v160 op_sel:[1,0,0,0]
	v_mad_u32_u16 v4, v6, v195, v160
	v_mad_u32_u16 v5, v6, v195, v160 op_sel:[1,0,0,0]
	v_mad_u32_u16 v6, v7, v195, v160
	v_mad_u32_u16 v7, v7, v195, v160 op_sel:[1,0,0,0]
	s_waitcnt vmcnt(0)
	v_mad_u32_u16 v8, v10, v195, v160
	v_mad_u32_u16 v9, v10, v195, v160 op_sel:[1,0,0,0]
	v_mad_u32_u16 v10, v11, v195, v160
	v_mad_u32_u16 v11, v11, v195, v160 op_sel:[1,0,0,0]
	v_mad_u32_u16 v16, v12, v195, v160
	v_mad_u32_u16 v12, v12, v195, v160 op_sel:[1,0,0,0]
	v_mad_u32_u16 v52, v13, v195, v160
	v_mad_u32_u16 v64, v13, v195, v160 op_sel:[1,0,0,0]
	s_cbranch_vccnz .LBB0_132
	global_load_dwordx4 v[12:15], v12, s[14:15]
	s_nop 0
	global_load_dwordx4 v[20:23], v16, s[14:15]
	global_load_dwordx4 v[24:27], v11, s[14:15]
	global_load_dwordx4 v[28:31], v10, s[14:15]
	global_load_dwordx4 v[32:35], v9, s[14:15]
	global_load_dwordx4 v[36:39], v8, s[14:15]
	global_load_dwordx4 v[40:43], v7, s[14:15]
	global_load_dwordx4 v[44:47], v6, s[14:15]
	global_load_dwordx4 v[48:51], v5, s[14:15]
	global_load_dwordx4 v[56:59], v4, s[14:15]
	global_load_dwordx4 v[60:63], v3, s[14:15]
	global_load_dwordx4 v[68:71], v2, s[14:15]
	global_load_dwordx4 v[72:75], v1, s[14:15]
	global_load_dwordx4 v[76:79], v0, s[14:15]
	v_readlane_b32 s0, v253, 60
	v_lshlrev_b32_e32 v90, 1, v160
	v_readlane_b32 s1, v253, 61
	s_nop 4
	global_load_dwordx4 v[0:3], v90, s[0:1] offset:16
	global_load_dwordx4 v[4:7], v90, s[0:1]
	v_readlane_b32 s0, v253, 62
	v_readlane_b32 s1, v253, 63
	s_nop 4
	global_load_dwordx4 v[80:83], v176, s[0:1] offset:16
	global_load_dwordx4 v[84:87], v176, s[0:1]
	v_readlane_b32 s0, v254, 2
	v_readlane_b32 s1, v254, 3
	s_nop 4
	global_load_dwordx4 v[8:11], v90, s[0:1] offset:16
	global_load_dwordx4 v[16:19], v90, s[0:1]
	s_nop 0
	global_load_dwordx4 v[52:55], v52, s[14:15]
	s_nop 0
	global_load_dwordx4 v[64:67], v64, s[14:15]
	v_readlane_b32 s0, v253, 54
	v_mov_b32_e32 v91, v177
	v_readlane_b32 s1, v253, 55
	v_readlane_b32 s12, v254, 4
	v_readlane_b32 s13, v254, 5
	v_lshl_add_u64 v[164:165], s[0:1], 0, v[90:91]
	v_and_b32_e32 v90, 2, v88
	v_cmp_eq_u32_e64 s[4:5], 0, v90
	v_and_b32_e32 v90, 1, v88
	v_lshl_add_u64 v[162:163], s[66:67], 0, v[176:177]
	v_cmp_eq_u32_e64 s[6:7], 0, v90
	v_lshl_add_u64 v[90:91], s[12:13], 0, v[176:177]
	v_lshlrev_b32_e32 v176, 1, v89
	v_lshlrev_b32_e32 v88, 2, v88
	s_movk_i32 s12, 0xe0
	v_lshl_add_u64 v[166:167], v[90:91], 0, v[176:177]
	v_and_or_b32 v176, v88, s12, v176
	v_readlane_b32 s12, v255, 14
	v_readlane_b32 s13, v255, 15
	v_cmp_lt_u32_e64 s[0:1], 3, v89
	s_nop 0
	v_lshl_add_u64 v[168:169], s[12:13], 0, v[176:177]
	s_mov_b32 s12, s38
	v_mbcnt_lo_u32_b32 v230, -1, 0
	v_mbcnt_hi_u32_b32 v230, -1, v230
	v_readlane_b32 s100, v253, 54
	v_readlane_b32 s101, v253, 55
	v_lshlrev_b32_e32 v228, 2, v230
	v_mov_b32_e32 v229, 0
	s_nop 1
	v_lshl_add_u64 v[226:227], s[100:101], 0, v[228:229]
	v_and_b32_e32 v231, 7, v230
	v_lshlrev_b32_e32 v231, 5, v231
	v_and_b32_e32 v230, 56, v230
	v_lshlrev_b32_e32 v230, 2, v230
	v_lshrrev_b32_e32 v228, 2, v160
	v_lshl_add_u64 v[224:225], v[162:163], 0, v[228:229]
	s_waitcnt vmcnt(0)
	s_branch .LBB0_130

; #define PEER_META(T, IA, IB, HA, HB) do { const int _t = (T) < TTOK ? (T) : wslot; \
;     IA = *(const u32x4*)(W_IDX(p) + (size_t)_t * 128 + r * 16); IB = *(const u32x4*)(W_IDX(p) + (size_t)_t * 128 + r * 16 + 8); \
;     const u16* _hp = W_H(p) + (size_t)_t * DM + x * 128 + 16 * c; HA = *(const u32x4*)(_hp); HB = *(const u32x4*)(_hp + 8); } while (0)
; #define PEER_GATHER(TAB, IA, IB, RR) do { _Pragma("unroll") for (int g = 0; g < 16; ++g) { \
;     const unsigned _w = (g < 8 ? IA : IB)[(g >> 1) & 3]; RR[g] = *(const u32x4*)((TAB) + row_off(_w, c16, (g & 1) != 0)); } } while (0)
; DI void phase_peer_dots(const Params& p, int layer, int wave) {
;     ...
;   for (; t < TTOK; t += 2 * nslot) {
;     DOTS_QUANT(hAa, hBa);
;     PEER_META(t + 2 * nslot, iAa, iBa, hAa, hBa);
;     PEER_GATHER(ub, iAb, iBb, rrB);
.LBB0_130:
	s_add_i32 s100, s12, s88
	s_cmp_lt_i32 s100, 0x10200
	s_cselect_b32 s100, s100, s38
	s_ashr_i32 s101, s100, 31
	s_lshl_b64 s[100:101], s[100:101], 8
	v_lshl_add_u64 v[222:223], v[224:225], 0, s[100:101]
	global_load_dword v232, v[222:223], off
	s_lshl_b64 s[100:101], s[100:101], 3
	v_lshl_add_u64 v[222:223], v[226:227], 0, s[100:101]
	global_load_dword v233, v[222:223], off
	s_waitcnt lgkmcnt(0)
	v_mad_u32_u16 v206, v84, v195, v160
	v_mad_u32_u16 v207, v84, v195, v160 op_sel:[1,0,0,0]
	v_mad_u32_u16 v208, v85, v195, v160
	v_mad_u32_u16 v209, v85, v195, v160 op_sel:[1,0,0,0]
	v_mad_u32_u16 v210, v86, v195, v160
	v_mad_u32_u16 v211, v86, v195, v160 op_sel:[1,0,0,0]
	v_mad_u32_u16 v212, v87, v195, v160
	v_mad_u32_u16 v213, v87, v195, v160 op_sel:[1,0,0,0]
	v_mad_u32_u16 v214, v80, v195, v160
	v_mad_u32_u16 v215, v80, v195, v160 op_sel:[1,0,0,0]
	v_mad_u32_u16 v216, v81, v195, v160
	v_mad_u32_u16 v217, v81, v195, v160 op_sel:[1,0,0,0]
	v_mad_u32_u16 v218, v82, v195, v160
	v_mad_u32_u16 v219, v82, v195, v160 op_sel:[1,0,0,0]
	v_mad_u32_u16 v220, v83, v195, v160
	v_mad_u32_u16 v221, v83, v195, v160 op_sel:[1,0,0,0]
	v_lshlrev_b32_e32 v88, 16, v16
	v_and_b32_e32 v16, 0xffff0000, v16
	v_lshlrev_b32_e32 v90, 16, v17
	v_and_b32_e32 v17, 0xffff0000, v17
	v_max3_f32 v96, |v88|, 0, |v16|
	v_lshlrev_b32_e32 v92, 16, v18
	v_and_b32_e32 v18, 0xffff0000, v18
	global_load_dwordx4 v[148:151], v206, s[14:15]
	v_max3_f32 v96, v96, |v90|, |v17|
	v_lshlrev_b32_e32 v94, 16, v19
	v_and_b32_e32 v19, 0xffff0000, v19
	v_max3_f32 v96, v96, |v92|, |v18|
	v_lshlrev_b32_e32 v89, 16, v8
	v_and_b32_e32 v8, 0xffff0000, v8
	v_max3_f32 v96, v96, |v94|, |v19|
	v_lshlrev_b32_e32 v91, 16, v9
	v_and_b32_e32 v9, 0xffff0000, v9
	v_max3_f32 v96, v96, |v89|, |v8|
	v_lshlrev_b32_e32 v93, 16, v10
	v_and_b32_e32 v10, 0xffff0000, v10
	v_max3_f32 v96, v96, |v91|, |v9|
	v_lshlrev_b32_e32 v95, 16, v11
	v_and_b32_e32 v11, 0xffff0000, v11
	v_max3_f32 v96, v96, |v93|, |v10|
	global_load_dwordx4 v[140:143], v207, s[14:15]
	v_max3_f32 v96, v96, |v95|, |v11|
	s_mov_b32 s13, s12
	s_add_i32 s12, s12, s88
	v_mov_b32_dpp v97, v96 quad_perm:[1,0,3,2] row_mask:0xf bank_mask:0xf bound_ctrl:1
	v_max_f32_e32 v96, v96, v97
	s_cmp_gt_i32 s12, 0x101ff
	s_cselect_b64 s[56:57], -1, 0
	v_mov_b32_dpp v97, v96 quad_perm:[2,3,0,1] row_mask:0xf bank_mask:0xf bound_ctrl:1
	v_max_f32_e32 v96, v96, v97
	s_cmp_lt_i32 s12, 0x10200
	v_lshlrev_b32_e32 v179, 16, v0
	v_mov_b32_dpp v97, v96 row_half_mirror row_mask:0xf bank_mask:0xf bound_ctrl:1
	v_max_f32_e32 v161, v96, v97
	v_div_scale_f32 v96, s[28:29], v161, v161, s63
	v_rcp_f32_e32 v97, v96
	s_cselect_b32 s28, s12, s38
	s_ashr_i32 s29, s28, 31
	s_lshl_b64 s[36:37], s[28:29], 8
	v_fma_f32 v98, -v96, v97, 1.0
	v_fmac_f32_e32 v97, v98, v97
	v_div_scale_f32 v98, vcc, s63, v161, s63
	global_load_dwordx4 v[144:147], v208, s[14:15]
	v_mul_f32_e32 v99, v98, v97
	v_fma_f32 v100, -v96, v99, v98
	v_fmac_f32_e32 v99, v100, v97
	v_fma_f32 v96, -v96, v99, v98
	v_div_fmas_f32 v96, v96, v97, v99
	v_div_fixup_f32 v96, v96, v161, s63
	v_cmp_lt_f32_e32 vcc, 0, v161
	s_lshl_b64 s[28:29], s[28:29], 11
	s_add_i32 s21, s41, s13
	v_cndmask_b32_e32 v96, 0, v96, vcc
	v_mul_f32_e32 v16, v96, v16
	v_mul_f32_e32 v88, v96, v88
	v_rndne_f32_e32 v16, v16
	v_mul_f32_e32 v90, v96, v90
	v_rndne_f32_e32 v88, v88
	v_cvt_i32_f32_e32 v16, v16
	v_rndne_f32_e32 v90, v90
	global_load_dwordx4 v[132:135], v209, s[14:15]
	v_mul_f32_e32 v17, v96, v17
	v_cvt_i32_f32_e32 v88, v88
	v_cvt_i32_f32_sdwa v90, v90 dst_sel:WORD_1 dst_unused:UNUSED_PAD src0_sel:DWORD
	v_rndne_f32_e32 v17, v17
	v_cvt_i32_f32_sdwa v17, v17 dst_sel:BYTE_3 dst_unused:UNUSED_PAD src0_sel:DWORD
	v_lshlrev_b32_e32 v16, 8, v16
	v_perm_b32 v16, v16, v88, s72
	v_and_b32_e32 v88, 0xff0000, v90
	v_or3_b32 v170, v16, v88, v17
	v_mul_f32_e32 v17, v96, v18
	v_mul_f32_e32 v16, v96, v92
	v_rndne_f32_e32 v17, v17
	v_mul_f32_e32 v18, v96, v94
	v_rndne_f32_e32 v16, v16
	v_cvt_i32_f32_e32 v17, v17
	v_rndne_f32_e32 v18, v18
	global_load_dwordx4 v[136:139], v210, s[14:15]
	v_mul_f32_e32 v19, v96, v19
	v_cvt_i32_f32_e32 v16, v16
	v_cvt_i32_f32_sdwa v18, v18 dst_sel:WORD_1 dst_unused:UNUSED_PAD src0_sel:DWORD
	v_rndne_f32_e32 v19, v19
	v_cvt_i32_f32_sdwa v19, v19 dst_sel:BYTE_3 dst_unused:UNUSED_PAD src0_sel:DWORD
	v_lshlrev_b32_e32 v17, 8, v17
	v_perm_b32 v16, v17, v16, s72
	v_and_b32_e32 v17, 0xff0000, v18
	v_mul_f32_e32 v8, v96, v8
	v_or3_b32 v171, v16, v17, v19
	v_mul_f32_e32 v16, v96, v89
	v_rndne_f32_e32 v8, v8
	v_mul_f32_e32 v17, v96, v91
	v_rndne_f32_e32 v16, v16
	v_cvt_i32_f32_e32 v8, v8
	global_load_dwordx4 v[124:127], v211, s[14:15]
	v_rndne_f32_e32 v17, v17
	v_mul_f32_e32 v9, v96, v9
	v_cvt_i32_f32_e32 v16, v16
	v_cvt_i32_f32_sdwa v17, v17 dst_sel:WORD_1 dst_unused:UNUSED_PAD src0_sel:DWORD
	v_rndne_f32_e32 v9, v9
	v_cvt_i32_f32_sdwa v9, v9 dst_sel:BYTE_3 dst_unused:UNUSED_PAD src0_sel:DWORD
	v_lshlrev_b32_e32 v8, 8, v8
	v_perm_b32 v8, v8, v16, s72
	v_and_b32_e32 v16, 0xff0000, v17
	v_or3_b32 v172, v8, v16, v9
	v_mul_f32_e32 v9, v96, v10
	v_mul_f32_e32 v8, v96, v93
	v_rndne_f32_e32 v9, v9
	v_mul_f32_e32 v10, v96, v95
	v_rndne_f32_e32 v8, v8
	v_cvt_i32_f32_e32 v9, v9
	global_load_dwordx4 v[128:131], v212, s[14:15]
	v_rndne_f32_e32 v10, v10
	v_mul_f32_e32 v11, v96, v11
	v_cvt_i32_f32_e32 v8, v8
	v_cvt_i32_f32_sdwa v10, v10 dst_sel:WORD_1 dst_unused:UNUSED_PAD src0_sel:DWORD
	v_rndne_f32_e32 v11, v11
	v_cvt_i32_f32_sdwa v11, v11 dst_sel:BYTE_3 dst_unused:UNUSED_PAD src0_sel:DWORD
	v_lshlrev_b32_e32 v9, 8, v9
	v_perm_b32 v8, v9, v8, s72
	v_and_b32_e32 v9, 0xff0000, v10
	v_or3_b32 v173, v8, v9, v11
	s_nop 0
	v_mov_b32_e32 v80, v177
	s_waitcnt vmcnt(26)
; #define DPP_I(v, ctrl) __builtin_amdgcn_update_dpp(0, (v), (ctrl), 0xf, 0xf, true)
; DI int reduce_scatter8(int d0, int d1, int d2, int d3, int d4, int d5, int d6, int d7, int c) {
;   const bool b2 = c >= 4, b1 = (c & 2) != 0, b0 = (c & 1) != 0;
;   const int e0 = (b2 ? d4 : d0) + DPP_I(b2 ? d0 : d4, 0x141);
;   const int e1 = (b2 ? d5 : d1) + DPP_I(b2 ? d1 : d5, 0x141);
;   const int e2 = (b2 ? d6 : d2) + DPP_I(b2 ? d2 : d6, 0x141);
;   const int e3 = (b2 ? d7 : d3) + DPP_I(b2 ? d3 : d7, 0x141);
;   const int f0 = (b1 ? e2 : e0) + DPP_I(b1 ? e0 : e2, 0x4E);
;   const int f1 = (b1 ? e3 : e1) + DPP_I(b1 ? e1 : e3, 0x4E);
;   return (b0 ? f1 : f0) + DPP_I(b0 ? f0 : f1, 0xB1);
; }
	v_dot4c_i32_i8_e32 v80, v76, v170
	v_mov_b32_e32 v76, v177
	s_waitcnt vmcnt(25)
	v_dot4c_i32_i8_e32 v76, v72, v170
	v_mov_b32_e32 v72, v177
	global_load_dwordx4 v[116:119], v213, s[14:15]
	s_waitcnt vmcnt(25)
	v_dot4c_i32_i8_e32 v72, v68, v170
	v_mov_b32_e32 v68, v177
	s_waitcnt vmcnt(24)
	v_dot4c_i32_i8_e32 v68, v60, v170
	v_mov_b32_e32 v60, v177
	s_waitcnt vmcnt(23)
	v_dot4c_i32_i8_e32 v60, v56, v170
	v_mov_b32_e32 v56, v177
	s_waitcnt vmcnt(22)
	v_dot4c_i32_i8_e32 v56, v48, v170
	v_mov_b32_e32 v48, v177
	s_waitcnt vmcnt(21)
	v_dot4c_i32_i8_e32 v48, v44, v170
	v_mov_b32_e32 v44, v177
	s_waitcnt vmcnt(20)
	v_dot4c_i32_i8_e32 v44, v40, v170
	v_mov_b32_e32 v40, v177
	s_waitcnt vmcnt(19)
	v_dot4c_i32_i8_e32 v40, v36, v170
	v_mov_b32_e32 v36, v177
	s_waitcnt vmcnt(18)
	v_dot4c_i32_i8_e32 v36, v32, v170
	global_load_dwordx4 v[120:123], v214, s[14:15]
	v_mov_b32_e32 v32, v177
	s_waitcnt vmcnt(18)
	v_dot4c_i32_i8_e32 v32, v28, v170
	v_mov_b32_e32 v28, v177
	s_waitcnt vmcnt(17)
	v_dot4c_i32_i8_e32 v28, v24, v170
	v_mov_b32_e32 v24, v177
	s_waitcnt vmcnt(16)
	v_dot4c_i32_i8_e32 v24, v20, v170
	v_mov_b32_e32 v20, v177
	v_dot4c_i32_i8_e32 v80, v77, v171
	v_dot4c_i32_i8_e32 v60, v57, v171
	s_waitcnt vmcnt(15)
	v_dot4c_i32_i8_e32 v20, v12, v170
	v_dot4c_i32_i8_e32 v80, v78, v172
	v_dot4c_i32_i8_e32 v76, v73, v171
	v_dot4c_i32_i8_e32 v60, v58, v172
	v_dot4c_i32_i8_e32 v56, v49, v171
	v_dot4c_i32_i8_e32 v20, v13, v171
	v_dot4c_i32_i8_e32 v80, v79, v173
	global_load_dwordx4 v[108:111], v215, s[14:15]
	v_dot4c_i32_i8_e32 v76, v74, v172
	v_dot4c_i32_i8_e32 v72, v69, v171
	v_dot4c_i32_i8_e32 v60, v59, v173
	v_dot4c_i32_i8_e32 v56, v50, v172
	v_dot4c_i32_i8_e32 v48, v45, v171
	v_dot4c_i32_i8_e32 v20, v14, v172
	v_dot4c_i32_i8_e32 v76, v75, v173
	v_dot4c_i32_i8_e32 v72, v70, v172
	v_dot4c_i32_i8_e32 v68, v61, v171
	v_dot4c_i32_i8_e32 v56, v51, v173
	v_dot4c_i32_i8_e32 v48, v46, v172
	v_dot4c_i32_i8_e32 v44, v41, v171
	v_dot4c_i32_i8_e32 v24, v21, v171
	v_dot4c_i32_i8_e32 v20, v15, v173
	v_cndmask_b32_e64 v15, v80, v60, s[0:1]
	v_cndmask_b32_e64 v21, v60, v80, s[0:1]
	global_load_dwordx4 v[112:115], v216, s[14:15]
	v_dot4c_i32_i8_e32 v72, v71, v173
	v_dot4c_i32_i8_e32 v68, v62, v172
	v_dot4c_i32_i8_e32 v48, v47, v173
	v_dot4c_i32_i8_e32 v44, v42, v172
	v_dot4c_i32_i8_e32 v24, v22, v172
	v_add_u32_dpp v15, v21, v15 row_half_mirror row_mask:0xf bank_mask:0xf bound_ctrl:1
	v_cndmask_b32_e64 v21, v76, v56, s[0:1]
	v_cndmask_b32_e64 v22, v56, v76, s[0:1]
	v_dot4c_i32_i8_e32 v68, v63, v173
	v_dot4c_i32_i8_e32 v44, v43, v173
	v_dot4c_i32_i8_e32 v24, v23, v173
	v_add_u32_dpp v21, v22, v21 row_half_mirror row_mask:0xf bank_mask:0xf bound_ctrl:1
	v_cndmask_b32_e64 v22, v72, v48, s[0:1]
	v_cndmask_b32_e64 v23, v48, v72, s[0:1]
	v_dot4c_i32_i8_e32 v28, v25, v171
	global_load_dwordx4 v[100:103], v217, s[14:15]
	v_cndmask_b32_e64 v25, v44, v68, s[0:1]
	v_add_u32_dpp v22, v23, v22 row_half_mirror row_mask:0xf bank_mask:0xf bound_ctrl:1
	v_cndmask_b32_e64 v23, v68, v44, s[0:1]
	v_dot4c_i32_i8_e32 v40, v37, v171
	v_mov_b32_e32 v12, v177
	v_add_u32_dpp v23, v25, v23 row_half_mirror row_mask:0xf bank_mask:0xf bound_ctrl:1
	v_cndmask_b32_e64 v25, v22, v15, s[4:5]
	v_cndmask_b32_e64 v15, v15, v22, s[4:5]
	v_cndmask_b32_e64 v22, v23, v21, s[4:5]
	v_cndmask_b32_e64 v21, v21, v23, s[4:5]
	v_dot4c_i32_i8_e32 v40, v38, v172
	v_dot4c_i32_i8_e32 v36, v33, v171
	s_waitcnt vmcnt(17)
	v_dot4c_i32_i8_e32 v12, v52, v170
	v_mov_b32_e32 v13, v177
	v_add_u32_dpp v15, v15, v25 quad_perm:[2,3,0,1] row_mask:0xf bank_mask:0xf bound_ctrl:1
	v_add_u32_dpp v21, v21, v22 quad_perm:[2,3,0,1] row_mask:0xf bank_mask:0xf bound_ctrl:1
	global_load_dwordx4 v[104:107], v218, s[14:15]
	v_dot4c_i32_i8_e32 v40, v39, v173
	v_dot4c_i32_i8_e32 v36, v34, v172
	v_dot4c_i32_i8_e32 v32, v29, v171
	v_dot4c_i32_i8_e32 v12, v53, v171
	s_waitcnt vmcnt(17)
	v_dot4c_i32_i8_e32 v13, v64, v170
	v_cndmask_b32_e64 v22, v21, v15, s[6:7]
	v_cndmask_b32_e64 v15, v15, v21, s[6:7]
	v_dot4c_i32_i8_e32 v36, v35, v173
	v_dot4c_i32_i8_e32 v32, v30, v172
	v_dot4c_i32_i8_e32 v12, v54, v172
	v_dot4c_i32_i8_e32 v13, v65, v171
	v_add_u32_dpp v15, v15, v22 quad_perm:[1,0,3,2] row_mask:0xf bank_mask:0xf bound_ctrl:1
	v_cndmask_b32_e64 v21, v40, v24, s[0:1]
	v_cndmask_b32_e64 v22, v24, v40, s[0:1]
	v_dot4c_i32_i8_e32 v32, v31, v173
	global_load_dwordx4 v[92:95], v219, s[14:15]
	v_dot4c_i32_i8_e32 v28, v26, v172
	v_dot4c_i32_i8_e32 v12, v55, v173
	v_dot4c_i32_i8_e32 v13, v66, v172
	v_add_u32_dpp v21, v22, v21 row_half_mirror row_mask:0xf bank_mask:0xf bound_ctrl:1
	v_cndmask_b32_e64 v22, v36, v20, s[0:1]
	v_cndmask_b32_e64 v20, v20, v36, s[0:1]
	v_dot4c_i32_i8_e32 v28, v27, v173
	v_dot4c_i32_i8_e32 v13, v67, v173
	v_add_u32_dpp v20, v20, v22 row_half_mirror row_mask:0xf bank_mask:0xf bound_ctrl:1
	v_cndmask_b32_e64 v22, v32, v12, s[0:1]
	v_cndmask_b32_e64 v12, v12, v32, s[0:1]
	v_cvt_f32_i32_e32 v15, v15
	s_cmp_lt_i32 s21, 0x10200
	v_add_u32_dpp v12, v12, v22 row_half_mirror row_mask:0xf bank_mask:0xf bound_ctrl:1
	v_cndmask_b32_e64 v22, v28, v13, s[0:1]
	v_cndmask_b32_e64 v13, v13, v28, s[0:1]
	v_mul_f32_e32 v14, 0x3c010204, v161
	s_cselect_b32 s28, s21, s38
	global_load_dwordx4 v[96:99], v220, s[14:15]
	v_add_u32_dpp v13, v13, v22 row_half_mirror row_mask:0xf bank_mask:0xf bound_ctrl:1
	v_cndmask_b32_e64 v22, v12, v21, s[4:5]
	v_cndmask_b32_e64 v12, v21, v12, s[4:5]
	v_cndmask_b32_e64 v21, v13, v20, s[4:5]
	v_cndmask_b32_e64 v13, v20, v13, s[4:5]
	v_add_u32_dpp v12, v12, v22 quad_perm:[2,3,0,1] row_mask:0xf bank_mask:0xf bound_ctrl:1
	s_ashr_i32 s29, s28, 31
	v_add_u32_dpp v13, v13, v21 quad_perm:[2,3,0,1] row_mask:0xf bank_mask:0xf bound_ctrl:1
	v_cndmask_b32_e64 v20, v13, v12, s[6:7]
	v_cndmask_b32_e64 v12, v12, v13, s[6:7]
	v_mul_f32_e32 v13, v14, v15
	v_cvt_pk_bf16_f32 v13, v13, s0
	v_add_u32_dpp v12, v12, v20 quad_perm:[1,0,3,2] row_mask:0xf bank_mask:0xf bound_ctrl:1
	v_cvt_f32_i32_e32 v12, v12
	s_lshl_b64 s[36:37], s[28:29], 8
	s_lshl_b64 s[28:29], s[28:29], 11
	s_waitcnt vmcnt(16)
; #define PEER_META(T, IA, IB, HA, HB) do { const int _t = (T) < TTOK ? (T) : wslot; \
;     IA = *(const u32x4*)(W_IDX(p) + (size_t)_t * 128 + r * 16); IB = *(const u32x4*)(W_IDX(p) + (size_t)_t * 128 + r * 16 + 8); \
;     const u16* _hp = W_H(p) + (size_t)_t * DM + x * 128 + 16 * c; HA = *(const u32x4*)(_hp); HB = *(const u32x4*)(_hp + 8); } while (0)
; #define PEER_GATHER(TAB, IA, IB, RR) do { _Pragma("unroll") for (int g = 0; g < 16; ++g) { \
;     const unsigned _w = (g < 8 ? IA : IB)[(g >> 1) & 3]; RR[g] = *(const u32x4*)((TAB) + row_off(_w, c16, (g & 1) != 0)); } } while (0)
; DI void phase_peer_dots(const Params& p, int layer, int wave) {
;     ...
;     PEER_META(t + 2 * nslot, iAa, iBa, hAa, hBa);
;     PEER_GATHER(ub, iAb, iBb, rrB);
;     DOTS_COMPUTE(t, rrA);
;     DOTS_QUANT(hAb, hBb);
;     PEER_META(t + 3 * nslot, iAb, iBb, hAb, hBb);
;     PEER_GATHER(ub, iAa, iBa, rrA);
	ds_bpermute_b32 v156, v230, v232
	ds_bpermute_b32 v157, v230, v232 offset:4
	ds_bpermute_b32 v158, v230, v232 offset:8
	ds_bpermute_b32 v159, v230, v232 offset:12
	ds_bpermute_b32 v152, v230, v232 offset:16
	ds_bpermute_b32 v153, v230, v232 offset:20
	ds_bpermute_b32 v154, v230, v232 offset:24
	ds_bpermute_b32 v155, v230, v232 offset:28
	s_waitcnt vmcnt(15)
	ds_bpermute_b32 v16, v231, v233
	ds_bpermute_b32 v17, v231, v233 offset:4
	ds_bpermute_b32 v18, v231, v233 offset:8
	ds_bpermute_b32 v19, v231, v233 offset:12
	ds_bpermute_b32 v8, v231, v233 offset:16
	ds_bpermute_b32 v9, v231, v233 offset:20
	ds_bpermute_b32 v10, v231, v233 offset:24
	ds_bpermute_b32 v11, v231, v233 offset:28
	global_store_short v[168:169], v13, off
	v_mul_f32_e32 v12, v14, v12
	v_cvt_pk_bf16_f32 v12, v12, s0
	global_store_short v[168:169], v12, off offset:16
	v_lshlrev_b32_e32 v170, 16, v4
	global_load_dwordx4 v[88:91], v221, s[14:15]
	v_and_b32_e32 v172, 0xffff0000, v4
	v_and_b32_e32 v181, 0xffff0000, v0
	v_lshlrev_b32_e32 v171, 16, v5
	v_and_b32_e32 v161, 0xffff0000, v5
	v_lshlrev_b32_e32 v180, 16, v1
	v_and_b32_e32 v178, 0xffff0000, v1
	v_lshl_add_u64 v[222:223], v[224:225], 0, s[36:37]
	global_load_dword v234, v[222:223], off
	v_lshl_add_u64 v[222:223], v[226:227], 0, s[28:29]
	global_load_dword v235, v[222:223], off
	s_waitcnt lgkmcnt(0)
	v_mad_u32_u16 v206, v156, v195, v160
	v_mad_u32_u16 v207, v156, v195, v160 op_sel:[1,0,0,0]
	v_mad_u32_u16 v208, v157, v195, v160
	v_mad_u32_u16 v209, v157, v195, v160 op_sel:[1,0,0,0]
	v_mad_u32_u16 v210, v158, v195, v160
	v_mad_u32_u16 v211, v158, v195, v160 op_sel:[1,0,0,0]
	v_mad_u32_u16 v212, v159, v195, v160
	v_mad_u32_u16 v213, v159, v195, v160 op_sel:[1,0,0,0]
	v_mad_u32_u16 v214, v152, v195, v160
	v_mad_u32_u16 v215, v152, v195, v160 op_sel:[1,0,0,0]
	v_mad_u32_u16 v216, v153, v195, v160
	v_mad_u32_u16 v217, v153, v195, v160 op_sel:[1,0,0,0]
	v_mad_u32_u16 v218, v154, v195, v160
	v_mad_u32_u16 v219, v154, v195, v160 op_sel:[1,0,0,0]
	v_mad_u32_u16 v220, v155, v195, v160
	v_mad_u32_u16 v221, v155, v195, v160 op_sel:[1,0,0,0]
	v_lshlrev_b32_e32 v174, 16, v6
	v_and_b32_e32 v176, 0xffff0000, v6
	v_lshlrev_b32_e32 v183, 16, v2
	v_and_b32_e32 v185, 0xffff0000, v2
	v_lshlrev_b32_e32 v175, 16, v7
	v_and_b32_e32 v173, 0xffff0000, v7
	v_lshlrev_b32_e32 v184, 16, v3
	global_load_dwordx4 v[76:79], v206, s[14:15]
	v_and_b32_e32 v182, 0xffff0000, v3
	s_nop 0
	s_nop 0
	s_nop 0
	s_nop 0
	v_max3_f32 v152, |v170|, 0, |v172|
	v_max3_f32 v152, v152, |v171|, |v161|
	v_max3_f32 v152, v152, |v174|, |v176|
	v_max3_f32 v152, v152, |v175|, |v173|
	v_max3_f32 v152, v152, |v179|, |v181|
	v_max3_f32 v152, v152, |v180|, |v178|
	v_max3_f32 v152, v152, |v183|, |v185|
	v_max3_f32 v152, v152, |v184|, |v182|
	s_add_i32 s84, s53, s13
	s_cmp_gt_i32 s84, 0x101ff
	v_mov_b32_dpp v153, v152 quad_perm:[1,0,3,2] row_mask:0xf bank_mask:0xf bound_ctrl:1
	v_max_f32_e32 v152, v152, v153
	s_nop 1
	v_mov_b32_dpp v153, v152 quad_perm:[2,3,0,1] row_mask:0xf bank_mask:0xf bound_ctrl:1
	global_load_dwordx4 v[72:75], v207, s[14:15]
	v_max_f32_e32 v152, v152, v153
	s_nop 1
	v_mov_b32_dpp v153, v152 row_half_mirror row_mask:0xf bank_mask:0xf bound_ctrl:1
	s_cbranch_scc1 .LBB0_129
	v_max_f32_e32 v152, v152, v153
	v_div_scale_f32 v153, s[28:29], v152, v152, s63
	v_rcp_f32_e32 v154, v153
	s_ashr_i32 s85, s84, 31
	s_lshl_b64 s[28:29], s[84:85], 11
	v_fma_f32 v155, -v153, v154, 1.0
	v_fmac_f32_e32 v154, v155, v154
	v_div_scale_f32 v155, vcc, s63, v152, s63
	v_mul_f32_e32 v156, v155, v154
	v_fma_f32 v157, -v153, v156, v155
	v_fmac_f32_e32 v156, v157, v154
	v_fma_f32 v153, -v153, v156, v155
	v_div_fmas_f32 v153, v153, v154, v156
	global_load_dwordx4 v[68:71], v208, s[14:15]
	v_div_fixup_f32 v153, v153, v152, s63
	v_cmp_lt_f32_e32 vcc, 0, v152
	v_mul_f32_e32 v152, 0x3c010204, v152
	s_nop 0
	v_cndmask_b32_e32 v153, 0, v153, vcc
	v_mul_f32_e32 v154, v153, v185
	v_rndne_f32_e32 v154, v154
	v_mul_f32_e32 v155, v153, v183
	v_mul_f32_e32 v156, v153, v184
	v_cvt_i32_f32_e32 v154, v154
	v_rndne_f32_e32 v155, v155
	v_rndne_f32_e32 v156, v156
	v_mul_f32_e32 v157, v153, v182
	v_cvt_i32_f32_e32 v155, v155
	v_cvt_i32_f32_sdwa v156, v156 dst_sel:WORD_1 dst_unused:UNUSED_PAD src0_sel:DWORD
	global_load_dwordx4 v[60:63], v209, s[14:15]
	v_rndne_f32_e32 v157, v157
	v_cvt_i32_f32_sdwa v157, v157 dst_sel:BYTE_3 dst_unused:UNUSED_PAD src0_sel:DWORD
	v_lshlrev_b32_e32 v154, 8, v154
	v_perm_b32 v154, v154, v155, s72
	v_and_b32_e32 v155, 0xff0000, v156
	v_or3_b32 v154, v154, v155, v157
	v_mul_f32_e32 v155, v153, v181
	v_rndne_f32_e32 v155, v155
	v_mul_f32_e32 v156, v153, v179
	v_mul_f32_e32 v157, v153, v180
	v_cvt_i32_f32_e32 v155, v155
	v_rndne_f32_e32 v156, v156
	v_rndne_f32_e32 v157, v157
	v_mul_f32_e32 v158, v153, v178
	v_cvt_i32_f32_e32 v156, v156
	global_load_dwordx4 v[56:59], v210, s[14:15]
	v_cvt_i32_f32_sdwa v157, v157 dst_sel:WORD_1 dst_unused:UNUSED_PAD src0_sel:DWORD
	v_rndne_f32_e32 v158, v158
	v_cvt_i32_f32_sdwa v158, v158 dst_sel:BYTE_3 dst_unused:UNUSED_PAD src0_sel:DWORD
	v_lshlrev_b32_e32 v155, 8, v155
	v_perm_b32 v155, v155, v156, s72
	v_and_b32_e32 v156, 0xff0000, v157
	v_or3_b32 v155, v155, v156, v158
	v_mul_f32_e32 v156, v153, v176
	v_rndne_f32_e32 v156, v156
	v_mul_f32_e32 v157, v153, v174
	v_mul_f32_e32 v158, v153, v175
	v_cvt_i32_f32_e32 v156, v156
	v_rndne_f32_e32 v157, v157
	v_rndne_f32_e32 v158, v158
	v_mul_f32_e32 v159, v153, v173
	global_load_dwordx4 v[48:51], v211, s[14:15]
	v_cvt_i32_f32_e32 v157, v157
	v_cvt_i32_f32_sdwa v158, v158 dst_sel:WORD_1 dst_unused:UNUSED_PAD src0_sel:DWORD
	v_rndne_f32_e32 v159, v159
	v_cvt_i32_f32_sdwa v159, v159 dst_sel:BYTE_3 dst_unused:UNUSED_PAD src0_sel:DWORD
	v_lshlrev_b32_e32 v156, 8, v156
	v_perm_b32 v156, v156, v157, s72
	v_and_b32_e32 v157, 0xff0000, v158
	v_or3_b32 v156, v156, v157, v159
	v_mul_f32_e32 v157, v153, v172
	v_rndne_f32_e32 v157, v157
	v_mul_f32_e32 v158, v153, v170
	v_mul_f32_e32 v159, v153, v171
	v_cvt_i32_f32_e32 v157, v157
	v_rndne_f32_e32 v158, v158
	global_load_dwordx4 v[44:47], v212, s[14:15]
	v_rndne_f32_e32 v159, v159
	v_mul_f32_e32 v153, v153, v161
	v_cvt_i32_f32_e32 v158, v158
	v_cvt_i32_f32_sdwa v159, v159 dst_sel:WORD_1 dst_unused:UNUSED_PAD src0_sel:DWORD
	v_rndne_f32_e32 v153, v153
	v_cvt_i32_f32_sdwa v153, v153 dst_sel:BYTE_3 dst_unused:UNUSED_PAD src0_sel:DWORD
	v_lshlrev_b32_e32 v157, 8, v157
	v_perm_b32 v157, v157, v158, s72
	v_and_b32_e32 v158, 0xff0000, v159
	v_or3_b32 v153, v157, v158, v153
	v_mov_b32_e32 v157, v177
	s_waitcnt vmcnt(26)
; #define PEER_META(T, IA, IB, HA, HB) do { const int _t = (T) < TTOK ? (T) : wslot; \
;     IA = *(const u32x4*)(W_IDX(p) + (size_t)_t * 128 + r * 16); IB = *(const u32x4*)(W_IDX(p) + (size_t)_t * 128 + r * 16 + 8); \
;     const u16* _hp = W_H(p) + (size_t)_t * DM + x * 128 + 16 * c; HA = *(const u32x4*)(_hp); HB = *(const u32x4*)(_hp + 8); } while (0)
; DI void phase_peer_dots(const Params& p, int layer, int wave) {
;     ...
;     PEER_META(t + 3 * nslot, iAb, iBb, hAb, hBb);
	v_dot4c_i32_i8_e32 v157, v148, v153
	v_mov_b32_e32 v148, v177
	s_waitcnt vmcnt(25)
	v_dot4c_i32_i8_e32 v148, v140, v153
	v_dot4c_i32_i8_e32 v148, v141, v156
	global_load_dwordx4 v[40:43], v213, s[14:15]
	v_mov_b32_e32 v141, v177
	s_waitcnt vmcnt(24)
	v_dot4c_i32_i8_e32 v141, v132, v153
	v_dot4c_i32_i8_e32 v141, v133, v156
	v_mov_b32_e32 v133, v177
	s_waitcnt vmcnt(22)
	v_dot4c_i32_i8_e32 v133, v124, v153
	v_dot4c_i32_i8_e32 v133, v125, v156
	v_mov_b32_e32 v125, v177
	s_waitcnt vmcnt(20)
	v_dot4c_i32_i8_e32 v125, v116, v153
	v_dot4c_i32_i8_e32 v125, v117, v156
	v_mov_b32_e32 v117, v177
	s_waitcnt vmcnt(18)
	v_dot4c_i32_i8_e32 v117, v108, v153
	v_dot4c_i32_i8_e32 v117, v109, v156
	v_mov_b32_e32 v109, v177
	v_mov_b32_e32 v132, v177
	global_load_dwordx4 v[36:39], v214, s[14:15]
	s_waitcnt vmcnt(17)
	v_dot4c_i32_i8_e32 v109, v100, v153
	v_dot4c_i32_i8_e32 v132, v136, v153
	v_dot4c_i32_i8_e32 v109, v101, v156
	v_mov_b32_e32 v101, v177
	v_dot4c_i32_i8_e32 v157, v149, v156
	v_mov_b32_e32 v140, v177
	v_dot4c_i32_i8_e32 v132, v137, v156
	v_mov_b32_e32 v124, v177
	s_waitcnt vmcnt(15)
	v_dot4c_i32_i8_e32 v101, v92, v153
	v_dot4c_i32_i8_e32 v157, v150, v155
	v_dot4c_i32_i8_e32 v140, v144, v153
	v_dot4c_i32_i8_e32 v132, v138, v155
	v_dot4c_i32_i8_e32 v124, v128, v153
	v_dot4c_i32_i8_e32 v101, v93, v156
	v_mov_b32_e32 v93, v177
	global_load_dwordx4 v[32:35], v215, s[14:15]
	v_dot4c_i32_i8_e32 v157, v151, v154
	v_dot4c_i32_i8_e32 v148, v142, v155
	v_dot4c_i32_i8_e32 v140, v145, v156
	v_dot4c_i32_i8_e32 v132, v139, v154
	v_dot4c_i32_i8_e32 v133, v126, v155
	v_dot4c_i32_i8_e32 v124, v129, v156
	s_waitcnt vmcnt(12)
	v_dot4c_i32_i8_e32 v93, v88, v153
	v_dot4c_i32_i8_e32 v148, v143, v154
	v_dot4c_i32_i8_e32 v140, v146, v155
	v_dot4c_i32_i8_e32 v133, v127, v154
	v_dot4c_i32_i8_e32 v124, v130, v155
	v_dot4c_i32_i8_e32 v93, v89, v156
	v_cndmask_b32_e64 v88, v157, v132, s[0:1]
	v_cndmask_b32_e64 v89, v132, v157, s[0:1]
	global_load_dwordx4 v[28:31], v216, s[14:15]
	v_dot4c_i32_i8_e32 v140, v147, v154
	v_dot4c_i32_i8_e32 v141, v134, v155
	v_dot4c_i32_i8_e32 v124, v131, v154
	v_dot4c_i32_i8_e32 v125, v118, v155
	v_dot4c_i32_i8_e32 v93, v90, v155
	v_add_u32_dpp v88, v89, v88 row_half_mirror row_mask:0xf bank_mask:0xf bound_ctrl:1
	v_cndmask_b32_e64 v89, v148, v133, s[0:1]
	v_cndmask_b32_e64 v90, v133, v148, s[0:1]
	v_dot4c_i32_i8_e32 v141, v135, v154
	v_dot4c_i32_i8_e32 v125, v119, v154
	v_dot4c_i32_i8_e32 v93, v91, v154
	v_add_u32_dpp v89, v90, v89 row_half_mirror row_mask:0xf bank_mask:0xf bound_ctrl:1
	v_cndmask_b32_e64 v90, v140, v124, s[0:1]
	v_cndmask_b32_e64 v91, v124, v140, s[0:1]
	v_mov_b32_e32 v116, v177
	global_load_dwordx4 v[24:27], v217, s[14:15]
	v_mov_b32_e32 v100, v177
	v_dot4c_i32_i8_e32 v101, v94, v155
	v_add_u32_dpp v90, v91, v90 row_half_mirror row_mask:0xf bank_mask:0xf bound_ctrl:1
	v_cndmask_b32_e64 v91, v141, v125, s[0:1]
	v_cndmask_b32_e64 v94, v125, v141, s[0:1]
	v_dot4c_i32_i8_e32 v116, v120, v153
	v_dot4c_i32_i8_e32 v100, v104, v153
	v_add_u32_dpp v91, v94, v91 row_half_mirror row_mask:0xf bank_mask:0xf bound_ctrl:1
	v_dot4c_i32_i8_e32 v116, v121, v156
	v_mov_b32_e32 v108, v177
	v_dot4c_i32_i8_e32 v100, v105, v156
	v_mov_b32_e32 v92, v177
	v_cndmask_b32_e64 v94, v90, v88, s[4:5]
	v_cndmask_b32_e64 v88, v88, v90, s[4:5]
	v_cndmask_b32_e64 v90, v91, v89, s[4:5]
	global_load_dwordx4 v[20:23], v218, s[14:15]
	v_cndmask_b32_e64 v89, v89, v91, s[4:5]
	v_dot4c_i32_i8_e32 v116, v122, v155
	v_dot4c_i32_i8_e32 v108, v112, v153
	v_dot4c_i32_i8_e32 v100, v106, v155
	v_dot4c_i32_i8_e32 v92, v96, v153
	v_add_u32_dpp v88, v88, v94 quad_perm:[2,3,0,1] row_mask:0xf bank_mask:0xf bound_ctrl:1
	v_add_u32_dpp v89, v89, v90 quad_perm:[2,3,0,1] row_mask:0xf bank_mask:0xf bound_ctrl:1
	v_dot4c_i32_i8_e32 v116, v123, v154
	v_dot4c_i32_i8_e32 v117, v110, v155
	v_dot4c_i32_i8_e32 v108, v113, v156
	v_dot4c_i32_i8_e32 v100, v107, v154
	v_dot4c_i32_i8_e32 v92, v97, v156
	v_cndmask_b32_e64 v90, v89, v88, s[6:7]
	v_cndmask_b32_e64 v88, v88, v89, s[6:7]
	global_load_dwordx4 v[12:15], v219, s[14:15]
	v_dot4c_i32_i8_e32 v117, v111, v154
	v_dot4c_i32_i8_e32 v108, v114, v155
	v_dot4c_i32_i8_e32 v101, v95, v154
	v_dot4c_i32_i8_e32 v92, v98, v155
	v_add_u32_dpp v88, v88, v90 quad_perm:[1,0,3,2] row_mask:0xf bank_mask:0xf bound_ctrl:1
	v_cndmask_b32_e64 v89, v116, v100, s[0:1]
	v_cndmask_b32_e64 v90, v100, v116, s[0:1]
	v_dot4c_i32_i8_e32 v108, v115, v154
	v_dot4c_i32_i8_e32 v109, v102, v155
	v_dot4c_i32_i8_e32 v92, v99, v154
	v_add_u32_dpp v89, v90, v89 row_half_mirror row_mask:0xf bank_mask:0xf bound_ctrl:1
	v_cndmask_b32_e64 v90, v117, v101, s[0:1]
	v_cndmask_b32_e64 v91, v101, v117, s[0:1]
	v_dot4c_i32_i8_e32 v109, v103, v154
	s_nop 0
	v_add_u32_dpp v90, v91, v90 row_half_mirror row_mask:0xf bank_mask:0xf bound_ctrl:1
	global_load_dwordx4 v[52:55], v220, s[14:15]
	v_cndmask_b32_e64 v91, v108, v92, s[0:1]
	v_cndmask_b32_e64 v92, v92, v108, s[0:1]
	s_nop 1
	v_add_u32_dpp v91, v92, v91 row_half_mirror row_mask:0xf bank_mask:0xf bound_ctrl:1
	v_cndmask_b32_e64 v92, v109, v93, s[0:1]
	v_cndmask_b32_e64 v93, v93, v109, s[0:1]
	s_nop 1
	v_add_u32_dpp v92, v93, v92 row_half_mirror row_mask:0xf bank_mask:0xf bound_ctrl:1
	v_cndmask_b32_e64 v93, v91, v89, s[4:5]
	v_cndmask_b32_e64 v89, v89, v91, s[4:5]
	v_cndmask_b32_e64 v91, v92, v90, s[4:5]
	v_cndmask_b32_e64 v90, v90, v92, s[4:5]
	v_add_u32_dpp v89, v89, v93 quad_perm:[2,3,0,1] row_mask:0xf bank_mask:0xf bound_ctrl:1
	s_nop 0
	v_add_u32_dpp v90, v90, v91 quad_perm:[2,3,0,1] row_mask:0xf bank_mask:0xf bound_ctrl:1
	v_cndmask_b32_e64 v91, v90, v89, s[6:7]
	v_cndmask_b32_e64 v89, v89, v90, s[6:7]
	s_nop 1
	global_load_dwordx4 v[64:67], v221, s[14:15]
	v_add_u32_dpp v90, v89, v91 quad_perm:[1,0,3,2] row_mask:0xf bank_mask:0xf bound_ctrl:1
	v_cvt_f32_i32_e32 v91, v88
	v_cvt_f32_i32_e32 v90, v90
	v_lshl_add_u64 v[88:89], v[166:167], 0, s[28:29]
	v_mul_f32_e32 v91, v152, v91
	v_mul_f32_e32 v90, v152, v90
	v_cvt_pk_bf16_f32 v91, v91, s0
	v_cvt_pk_bf16_f32 v90, v90, s0
	s_waitcnt vmcnt(17)
	ds_bpermute_b32 v84, v230, v234
	ds_bpermute_b32 v85, v230, v234 offset:4
	ds_bpermute_b32 v86, v230, v234 offset:8
	ds_bpermute_b32 v87, v230, v234 offset:12
	ds_bpermute_b32 v80, v230, v234 offset:16
	ds_bpermute_b32 v81, v230, v234 offset:20
	ds_bpermute_b32 v82, v230, v234 offset:24
	ds_bpermute_b32 v83, v230, v234 offset:28
	s_waitcnt vmcnt(16)
	ds_bpermute_b32 v4, v231, v235
	ds_bpermute_b32 v5, v231, v235 offset:4
	ds_bpermute_b32 v6, v231, v235 offset:8
	ds_bpermute_b32 v7, v231, v235 offset:12
	ds_bpermute_b32 v0, v231, v235 offset:16
	ds_bpermute_b32 v1, v231, v235 offset:20
	ds_bpermute_b32 v2, v231, v235 offset:24
	ds_bpermute_b32 v3, v231, v235 offset:28
	global_store_short v[88:89], v91, off
	global_store_short v[88:89], v90, off offset:16
	s_branch .LBB0_129

; DI float shx16(float v) { return __int_as_float(__builtin_amdgcn_ds_swizzle(__float_as_int(v), 0x401F)); }
; DI float shx32(float v, int idx32) { return __int_as_float(__builtin_amdgcn_ds_bpermute(idx32, __float_as_int(v))); }
; DI f32x4 mfma16(bf16x8 a, bf16x8 b, f32x4 c) { return __builtin_amdgcn_mfma_f32_16x16x32_bf16(a, b, c, 0, 0, 0); }
; DI float fast_exp2(float x) { return __builtin_amdgcn_exp2f(x); }
; DI void attn_item(const Params& p, int layer, int b, int hh, int jq, lchar* sm, float lam, float oml, int tid, int w) {
;     ...
;       bf16x8 pb[2][2];
; #pragma unroll
;       for (int m = 0; m < 2; ++m) {
;         float mx = fmaxf(fmaxf(S[m][0][0], S[m][0][1]), fmaxf(S[m][0][2], S[m][0][3]));
; #pragma unroll
;         for (int k16 = 1; k16 < 4; ++k16) mx = fmaxf(fmaxf(mx, fmaxf(S[m][k16][0], S[m][k16][1])), fmaxf(S[m][k16][2], S[m][k16][3]));
;         mx = fmaxf(mx, shx16(mx));
;         mx = fmaxf(mx, shx32(mx, idx32));
;         if (kt == 0 || __builtin_amdgcn_ballot_w64(mx > 8.0f) != 0ull) {
;           const float dlt = kt == 0 ? mx : fmaxf(mx, 0.f);
;           const float alpha = fast_exp2(-dlt);
;           mrun[m] += dlt;
; #pragma unroll
;           for (int dt = 0; dt < 8; ++dt) { O[m][dt][0] *= alpha; O[m][dt][1] *= alpha; O[m][dt][2] *= alpha; O[m][dt][3] *= alpha; }
;           Osum[m][0] *= alpha; Osum[m][1] *= alpha; Osum[m][2] *= alpha; Osum[m][3] *= alpha;
; #pragma unroll
;           for (int k16 = 0; k16 < 4; ++k16)
; #pragma unroll
;             for (int r = 0; r < 4; ++r) S[m][k16][r] -= dlt;
;         }
; #pragma unroll
;         for (int k16 = 0; k16 < 4; ++k16)
; #pragma unroll
;           for (int r = 0; r < 4; ++r) S[m][k16][r] = fast_exp2(S[m][k16][r]);
; #pragma unroll
;         for (int kk = 0; kk < 2; ++kk) {
;           u32x4 t;
;           t[0] = pack2(S[m][2 * kk][0], S[m][2 * kk][1]); t[1] = pack2(S[m][2 * kk][2], S[m][2 * kk][3]);
;           t[2] = pack2(S[m][2 * kk + 1][0], S[m][2 * kk + 1][1]); t[3] = pack2(S[m][2 * kk + 1][2], S[m][2 * kk + 1][3]);
;           pb[m][kk] = __builtin_bit_cast(bf16x8, t);
;           Osum[m] = mfma16(ones, pb[m][kk], Osum[m]);
;         }
.LBB0_166:
	s_nop 2
	v_max_f32_e32 v44, v23, v23
	v_max_f32_e32 v45, v22, v22
	v_max_f32_e32 v44, v45, v44
	v_max_f32_e32 v45, v41, v41
	v_max_f32_e32 v46, v40, v40
	v_max_f32_e32 v45, v46, v45
	v_max_f32_e32 v46, v43, v43
	v_max_f32_e32 v47, v42, v42
	v_max3_f32 v44, v20, v21, v44
	v_max_f32_e32 v46, v47, v46
	v_max3_f32 v44, v44, v45, v46
	v_max_f32_e32 v45, v49, v49
	v_max_f32_e32 v46, v48, v48
	v_max_f32_e32 v45, v46, v45
	v_max_f32_e32 v46, v51, v51
	v_max_f32_e32 v47, v50, v50
	v_max_f32_e32 v46, v47, v46
	v_max3_f32 v44, v44, v45, v46
	v_max_f32_e32 v45, v53, v53
	v_max_f32_e32 v46, v52, v52
	v_max_f32_e32 v45, v46, v45
	v_max_f32_e32 v46, v55, v55
	v_max_f32_e32 v47, v54, v54
	v_max_f32_e32 v46, v47, v46
	v_max3_f32 v44, v44, v45, v46
	ds_swizzle_b32 v45, v44 offset:swizzle(SWAP,16)
	v_add_u32_e32 v68, 0, v153
	s_or_b32 s37, s63, 15
	s_waitcnt lgkmcnt(0)
	v_max_f32_e32 v44, v44, v45
	ds_bpermute_b32 v45, v150, v44
	s_waitcnt lgkmcnt(0)
	v_max_f32_e32 v57, v44, v45
	v_sub_f32_e32 v48, v48, v57
	v_sub_f32_e32 v49, v49, v57
	v_sub_f32_e32 v50, v50, v57
	v_sub_f32_e32 v51, v51, v57
	v_exp_f32_e32 v48, v48
	v_exp_f32_e32 v49, v49
	v_exp_f32_e32 v50, v50
	v_exp_f32_e32 v51, v51
	v_sub_f32_e32 v40, v40, v57
	v_cvt_pk_bf16_f32 v92, v48, v49
	v_max_f32_e32 v48, v27, v27
	v_max_f32_e32 v49, v26, v26
	v_cvt_pk_bf16_f32 v93, v50, v51
	v_max_f32_e32 v48, v49, v48
	v_max_f32_e32 v49, v29, v29
	v_max_f32_e32 v50, v28, v28
	v_max_f32_e32 v49, v50, v49
	v_max_f32_e32 v50, v31, v31
	v_max_f32_e32 v51, v30, v30
	v_max3_f32 v48, v24, v25, v48
	v_max_f32_e32 v50, v51, v50
	v_max3_f32 v48, v48, v49, v50
	v_max_f32_e32 v49, v33, v33
	v_max_f32_e32 v50, v32, v32
	v_max_f32_e32 v49, v50, v49
	v_max_f32_e32 v50, v35, v35
	v_max_f32_e32 v51, v34, v34
	v_max_f32_e32 v50, v51, v50
	v_max3_f32 v48, v48, v49, v50
	v_max_f32_e32 v49, v37, v37
	v_max_f32_e32 v50, v36, v36
	v_max_f32_e32 v49, v50, v49
	v_max_f32_e32 v50, v39, v39
	v_max_f32_e32 v51, v38, v38
	v_max_f32_e32 v50, v51, v50
	v_max3_f32 v48, v48, v49, v50
	ds_swizzle_b32 v49, v48 offset:swizzle(SWAP,16)
	v_sub_f32_e32 v41, v41, v57
	v_exp_f32_e32 v56, v40
	v_exp_f32_e32 v58, v41
	v_sub_f32_e32 v52, v52, v57
	s_waitcnt lgkmcnt(0)
	v_max_f32_e32 v48, v48, v49
	ds_bpermute_b32 v49, v150, v48
	v_sub_f32_e32 v53, v53, v57
	v_sub_f32_e32 v54, v54, v57
	v_sub_f32_e32 v55, v55, v57
	v_exp_f32_e32 v52, v52
	v_exp_f32_e32 v53, v53
	v_exp_f32_e32 v54, v54
	v_exp_f32_e32 v55, v55
	v_sub_f32_e32 v42, v42, v57
	s_waitcnt lgkmcnt(0)
	v_exp_f32_e32 v59, v42
	v_cvt_pk_bf16_f32 v42, v56, v58
	v_max_f32_e32 v56, v48, v49
	v_sub_f32_e32 v28, v28, v56
	v_sub_f32_e32 v29, v29, v56
	v_sub_f32_e32 v30, v30, v56
	v_sub_f32_e32 v31, v31, v56
	v_sub_f32_e32 v48, v24, v56
	v_sub_f32_e32 v49, v25, v56
	v_sub_f32_e32 v50, v26, v56
	v_sub_f32_e32 v51, v27, v56
	v_exp_f32_e64 v24, -v56
	v_cvt_pk_bf16_f32 v94, v52, v53
	v_cvt_pk_bf16_f32 v95, v54, v55
	v_exp_f32_e32 v48, v48
	v_exp_f32_e32 v49, v49
	v_exp_f32_e32 v50, v50
	v_exp_f32_e32 v51, v51
	v_exp_f32_e32 v52, v28
	v_exp_f32_e32 v53, v29
	v_exp_f32_e32 v54, v30
	v_exp_f32_e32 v31, v31
	v_sub_f32_e32 v36, v36, v56
	v_sub_f32_e32 v37, v37, v56
	v_sub_f32_e32 v38, v38, v56
	v_sub_f32_e32 v39, v39, v56
	v_sub_f32_e32 v32, v32, v56
	v_sub_f32_e32 v33, v33, v56
	v_sub_f32_e32 v34, v34, v56
	v_sub_f32_e32 v35, v35, v56
	v_mul_f32_e32 v24, 0, v24
	v_exp_f32_e64 v44, -v57
	v_sub_f32_e32 v43, v43, v57
	v_sub_f32_e32 v20, v20, v57
	v_sub_f32_e32 v21, v21, v57
	v_sub_f32_e32 v22, v22, v57
	v_sub_f32_e32 v23, v23, v57
	v_mov_b32_e32 v25, v24
	v_mov_b32_e32 v26, v24
	v_mov_b32_e32 v27, v24
	v_pk_add_f32 v[140:141], v[56:57], 0 op_sel_hi:[1,0]
	v_exp_f32_e32 v55, v32
	v_exp_f32_e32 v56, v33
	v_exp_f32_e32 v57, v34
	v_exp_f32_e32 v58, v35
	v_exp_f32_e32 v36, v36
	v_exp_f32_e32 v37, v37
	v_exp_f32_e32 v38, v38
	v_exp_f32_e32 v39, v39
	v_cvt_pk_bf16_f32 v28, v48, v49
	v_cvt_pk_bf16_f32 v29, v50, v51
	v_cvt_pk_bf16_f32 v30, v52, v53
	v_cvt_pk_bf16_f32 v31, v54, v31
	v_exp_f32_e32 v43, v43
	v_exp_f32_e32 v20, v20
	v_mfma_f32_16x16x32_bf16 v[32:35], v[0:3], v[28:31], v[24:27]
	v_exp_f32_e32 v21, v21
	v_exp_f32_e32 v22, v22
	v_exp_f32_e32 v23, v23
	v_cvt_pk_bf16_f32 v96, v55, v56
	v_cvt_pk_bf16_f32 v97, v57, v58
	v_cvt_pk_bf16_f32 v98, v36, v37
	v_cvt_pk_bf16_f32 v99, v38, v39
	v_cvt_pk_bf16_f32 v43, v59, v43
	v_mul_f32_e32 v44, 0, v44
	v_mfma_f32_16x16x32_bf16 v[88:91], v[0:3], v[96:99], v[32:35]
	s_nop 2
	ds_read_b128 v[32:35], v68 offset:16384
	ds_read_b128 v[36:39], v68 offset:18432
	ds_read_b128 v[48:51], v68 offset:20480
	ds_read_b128 v[52:55], v68 offset:22528
	ds_read_b128 v[56:59], v68 offset:24576
	ds_read_b128 v[60:63], v68 offset:26624
	ds_read_b128 v[64:67], v68 offset:28672
	ds_read_b128 v[68:71], v68 offset:30720
	v_mov_b32_e32 v45, v44
	v_mov_b32_e32 v46, v44
	v_mov_b32_e32 v47, v44
	v_cvt_pk_bf16_f32 v40, v20, v21
	v_cvt_pk_bf16_f32 v41, v22, v23
	s_nop 1
	v_mfma_f32_16x16x32_bf16 v[20:23], v[0:3], v[40:43], v[44:47]
	v_mfma_f32_16x16x32_bf16 v[20:23], v[0:3], v[92:95], v[20:23]
	s_waitcnt lgkmcnt(0)
; #define LAS __attribute__((address_space(3)))
; DI f32x4 mfma16(bf16x8 a, bf16x8 b, f32x4 c) { return __builtin_amdgcn_mfma_f32_16x16x32_bf16(a, b, c, 0, 0, 0); }
; #define SCHED __builtin_amdgcn_sched_barrier(0)
; DI void attn_item(const Params& p, int layer, int b, int hh, int jq, lchar* sm, float lam, float oml, int tid, int w) {
;     ...
; #pragma unroll
;       for (int kk = 0; kk < 2; ++kk) {
;         bf16x8 vf[8];
; #pragma unroll
;         for (int dt = 0; dt < 8; ++dt) vf[dt] = *(const LAS bf16x8*)(vb + dt * 2048 + voff[kk]);
;         SCHED;
; #pragma unroll
;         for (int dt = 0; dt < 8; ++dt) {
;           O[0][dt] = mfma16(vf[dt], pb[0][kk], O[0][dt]);
;           O[1][dt] = mfma16(vf[dt], pb[1][kk], O[1][dt]);
;         }
;       }
	v_mfma_f32_16x16x32_bf16 v[108:111], v[56:59], v[40:43], v[44:47]
	v_mfma_f32_16x16x32_bf16 v[112:115], v[56:59], v[28:31], v[24:27]
	v_add_u32_e32 v56, 0, v154
	v_mfma_f32_16x16x32_bf16 v[72:75], v[32:35], v[40:43], v[44:47]
	v_mfma_f32_16x16x32_bf16 v[32:35], v[32:35], v[28:31], v[24:27]
	v_mfma_f32_16x16x32_bf16 v[76:79], v[36:39], v[40:43], v[44:47]
	v_mfma_f32_16x16x32_bf16 v[36:39], v[36:39], v[28:31], v[24:27]
	v_mfma_f32_16x16x32_bf16 v[100:103], v[48:51], v[40:43], v[44:47]
	v_mfma_f32_16x16x32_bf16 v[48:51], v[48:51], v[28:31], v[24:27]
	v_mfma_f32_16x16x32_bf16 v[104:107], v[52:55], v[40:43], v[44:47]
	v_mfma_f32_16x16x32_bf16 v[52:55], v[52:55], v[28:31], v[24:27]
	v_mfma_f32_16x16x32_bf16 v[116:119], v[60:63], v[40:43], v[44:47]
	v_mfma_f32_16x16x32_bf16 v[120:123], v[60:63], v[28:31], v[24:27]
	v_mfma_f32_16x16x32_bf16 v[164:167], v[64:67], v[40:43], v[44:47]
	v_mfma_f32_16x16x32_bf16 v[168:171], v[64:67], v[28:31], v[24:27]
	v_mfma_f32_16x16x32_bf16 v[172:175], v[68:71], v[40:43], v[44:47]
	v_mfma_f32_16x16x32_bf16 v[28:31], v[68:71], v[28:31], v[24:27]
	s_nop 2
	ds_read_b128 v[24:27], v56 offset:16384
	ds_read_b128 v[40:43], v56 offset:18432
	ds_read_b128 v[44:47], v56 offset:20480
	ds_read_b128 v[60:63], v56 offset:22528
	ds_read_b128 v[178:181], v56 offset:24576
	ds_read_b128 v[182:185], v56 offset:26624
	ds_read_b128 v[186:189], v56 offset:28672
	ds_read_b128 v[190:193], v56 offset:30720
	s_waitcnt lgkmcnt(0)
	v_mfma_f32_16x16x32_bf16 v[80:83], v[24:27], v[92:95], v[72:75]
	s_lshl_b32 s28, s41, 7
	s_addk_i32 s63, 0xff50
	s_mov_b32 s41, 1
	v_mfma_f32_16x16x32_bf16 v[84:87], v[24:27], v[96:99], v[32:35]
	s_mov_b32 s44, 0x18000
	s_mov_b32 s72, 64
	v_mfma_f32_16x16x32_bf16 v[72:75], v[40:43], v[92:95], v[76:79]
	v_mfma_f32_16x16x32_bf16 v[76:79], v[40:43], v[96:99], v[36:39]
	v_mfma_f32_16x16x32_bf16 v[64:67], v[44:47], v[92:95], v[100:103]
	v_mfma_f32_16x16x32_bf16 v[68:71], v[44:47], v[96:99], v[48:51]
	v_mfma_f32_16x16x32_bf16 v[56:59], v[60:63], v[92:95], v[104:107]
	v_mfma_f32_16x16x32_bf16 v[60:63], v[60:63], v[96:99], v[52:55]
	v_mfma_f32_16x16x32_bf16 v[48:51], v[178:181], v[92:95], v[108:111]
	v_mfma_f32_16x16x32_bf16 v[52:55], v[178:181], v[96:99], v[112:115]
	v_mfma_f32_16x16x32_bf16 v[40:43], v[182:185], v[92:95], v[116:119]
	v_mfma_f32_16x16x32_bf16 v[44:47], v[182:185], v[96:99], v[120:123]
	v_mfma_f32_16x16x32_bf16 v[36:39], v[186:189], v[92:95], v[164:167]
	v_mfma_f32_16x16x32_bf16 v[32:35], v[186:189], v[96:99], v[168:171]
	s_nop 1
	v_subrev_u32_e32 v164, s28, v162
	v_mfma_f32_16x16x32_bf16 v[24:27], v[190:193], v[92:95], v[172:175]
	v_mfma_f32_16x16x32_bf16 v[28:31], v[190:193], v[96:99], v[28:31]
	s_branch .LBB0_169

; DI float shx16(float v) { return __int_as_float(__builtin_amdgcn_ds_swizzle(__float_as_int(v), 0x401F)); }
; DI float shx32(float v, int idx32) { return __int_as_float(__builtin_amdgcn_ds_bpermute(idx32, __float_as_int(v))); }
; DI f32x4 mfma16(bf16x8 a, bf16x8 b, f32x4 c) { return __builtin_amdgcn_mfma_f32_16x16x32_bf16(a, b, c, 0, 0, 0); }
; DI float fast_exp2(float x) { return __builtin_amdgcn_exp2f(x); }
; DI void attn_item(const Params& p, int layer, int b, int hh, int jq, lchar* sm, float lam, float oml, int tid, int w) {
;     ...
;       for (int m = 0; m < 2; ++m) {
;         float mx = fmaxf(fmaxf(S[m][0][0], S[m][0][1]), fmaxf(S[m][0][2], S[m][0][3]));
; #pragma unroll
;         for (int k16 = 1; k16 < 4; ++k16) mx = fmaxf(fmaxf(mx, fmaxf(S[m][k16][0], S[m][k16][1])), fmaxf(S[m][k16][2], S[m][k16][3]));
;         mx = fmaxf(mx, shx16(mx));
;         mx = fmaxf(mx, shx32(mx, idx32));
;         if (kt == 0 || __builtin_amdgcn_ballot_w64(mx > 8.0f) != 0ull) {
;           const float dlt = kt == 0 ? mx : fmaxf(mx, 0.f);
;           const float alpha = fast_exp2(-dlt);
;           mrun[m] += dlt;
; #pragma unroll
;           for (int dt = 0; dt < 8; ++dt) { O[m][dt][0] *= alpha; O[m][dt][1] *= alpha; O[m][dt][2] *= alpha; O[m][dt][3] *= alpha; }
;           Osum[m][0] *= alpha; Osum[m][1] *= alpha; Osum[m][2] *= alpha; Osum[m][3] *= alpha;
; #pragma unroll
;           for (int k16 = 0; k16 < 4; ++k16)
; #pragma unroll
;             for (int r = 0; r < 4; ++r) S[m][k16][r] -= dlt;
;         }
; #pragma unroll
;         for (int k16 = 0; k16 < 4; ++k16)
; #pragma unroll
;           for (int r = 0; r < 4; ++r) S[m][k16][r] = fast_exp2(S[m][k16][r]);
; #pragma unroll
;         for (int kk = 0; kk < 2; ++kk) {
;           u32x4 t;
;           t[0] = pack2(S[m][2 * kk][0], S[m][2 * kk][1]); t[1] = pack2(S[m][2 * kk][2], S[m][2 * kk][3]);
;           t[2] = pack2(S[m][2 * kk + 1][0], S[m][2 * kk + 1][1]); t[3] = pack2(S[m][2 * kk + 1][2], S[m][2 * kk + 1][3]);
;           pb[m][kk] = __builtin_bit_cast(bf16x8, t);
;           Osum[m] = mfma16(ones, pb[m][kk], Osum[m]);
.LBB0_172:
	v_max3_f32 v165, v108, v109, v110
	v_max3_f32 v166, v111, v112, v113
	v_max_f32_e32 v167, v114, v115
	v_max3_f32 v165, v165, v166, v167
	v_max3_f32 v166, v120, v121, v122
	v_max3_f32 v167, v123, v116, v117
	v_max3_f32 v168, v118, v119, v165
	v_max3_f32 v165, v166, v167, v168
	v_mov_b32_e32 v166, v165
	s_nop 1
	v_permlane16_swap_b32_e32 v165, v166
	v_max_f32_e32 v165, v165, v166
	v_mov_b32_e32 v166, v165
	s_nop 1
	v_permlane32_swap_b32_e32 v165, v166
	v_max_f32_e32 v165, v165, v166
	v_cmp_lt_f32_e32 vcc, s22, v165
	s_cbranch_vccz .LBB0_174
	v_max_f32_e32 v166, 0, v165
	v_exp_f32_e64 v168, -v166
	v_add_f32_e32 v141, v141, v166
	v_pk_add_f32 v[108:109], v[108:109], v[166:167] op_sel_hi:[1,0] neg_lo:[0,1] neg_hi:[0,1]
	v_pk_add_f32 v[110:111], v[110:111], v[166:167] op_sel_hi:[1,0] neg_lo:[0,1] neg_hi:[0,1]
	v_pk_mul_f32 v[82:83], v[82:83], v[168:169] op_sel_hi:[1,0]
	v_pk_mul_f32 v[80:81], v[80:81], v[168:169] op_sel_hi:[1,0]
	v_pk_mul_f32 v[74:75], v[74:75], v[168:169] op_sel_hi:[1,0]
	v_pk_mul_f32 v[72:73], v[72:73], v[168:169] op_sel_hi:[1,0]
	v_pk_mul_f32 v[66:67], v[66:67], v[168:169] op_sel_hi:[1,0]
	v_pk_mul_f32 v[64:65], v[64:65], v[168:169] op_sel_hi:[1,0]
	v_pk_mul_f32 v[58:59], v[58:59], v[168:169] op_sel_hi:[1,0]
	v_pk_mul_f32 v[56:57], v[56:57], v[168:169] op_sel_hi:[1,0]
	v_pk_mul_f32 v[50:51], v[50:51], v[168:169] op_sel_hi:[1,0]
	v_pk_mul_f32 v[48:49], v[48:49], v[168:169] op_sel_hi:[1,0]
	v_pk_mul_f32 v[42:43], v[42:43], v[168:169] op_sel_hi:[1,0]
	v_pk_mul_f32 v[40:41], v[40:41], v[168:169] op_sel_hi:[1,0]
	v_pk_mul_f32 v[38:39], v[38:39], v[168:169] op_sel_hi:[1,0]
	v_pk_mul_f32 v[36:37], v[36:37], v[168:169] op_sel_hi:[1,0]
	v_pk_mul_f32 v[26:27], v[26:27], v[168:169] op_sel_hi:[1,0]
	v_pk_mul_f32 v[24:25], v[24:25], v[168:169] op_sel_hi:[1,0]
	v_pk_mul_f32 v[22:23], v[22:23], v[168:169] op_sel_hi:[1,0]
	v_pk_mul_f32 v[20:21], v[20:21], v[168:169] op_sel_hi:[1,0]
	v_pk_add_f32 v[112:113], v[112:113], v[166:167] op_sel_hi:[1,0] neg_lo:[0,1] neg_hi:[0,1]
	v_pk_add_f32 v[114:115], v[114:115], v[166:167] op_sel_hi:[1,0] neg_lo:[0,1] neg_hi:[0,1]
	v_pk_add_f32 v[120:121], v[120:121], v[166:167] op_sel_hi:[1,0] neg_lo:[0,1] neg_hi:[0,1]
	v_pk_add_f32 v[122:123], v[122:123], v[166:167] op_sel_hi:[1,0] neg_lo:[0,1] neg_hi:[0,1]
	v_pk_add_f32 v[116:117], v[116:117], v[166:167] op_sel_hi:[1,0] neg_lo:[0,1] neg_hi:[0,1]
	v_pk_add_f32 v[118:119], v[118:119], v[166:167] op_sel_hi:[1,0] neg_lo:[0,1] neg_hi:[0,1]
.LBB0_174:
	v_exp_f32_e32 v110, v110
	v_exp_f32_e32 v111, v111
	v_exp_f32_e32 v116, v116
	v_exp_f32_e32 v117, v117
	v_exp_f32_e32 v118, v118
	v_exp_f32_e32 v119, v119
	v_exp_f32_e32 v166, v113
	v_cvt_pk_bf16_f32 v113, v110, v111
	v_cvt_pk_bf16_f32 v110, v116, v117
	v_max3_f32 v116, v92, v93, v94
	v_max3_f32 v117, v95, v96, v97
	v_cvt_pk_bf16_f32 v111, v118, v119
	v_max3_f32 v118, v98, v99, v100
	v_max3_f32 v119, v101, v102, v103
	v_max3_f32 v116, v116, v104, v105
	v_max3_f32 v117, v117, v106, v107
	v_max3_f32 v116, v116, v117, v118
	v_max_f32_e32 v116, v116, v119
	v_mov_b32_e32 v117, v116
	v_exp_f32_e32 v108, v108
	v_exp_f32_e32 v109, v109
	v_permlane16_swap_b32_e32 v116, v117
	v_exp_f32_e32 v165, v112
	v_max_f32_e32 v116, v116, v117
	v_mov_b32_e32 v117, v116
	v_exp_f32_e32 v167, v114
	v_exp_f32_e32 v115, v115
	v_permlane32_swap_b32_e32 v116, v117
	v_exp_f32_e32 v120, v120
	v_exp_f32_e32 v121, v121
	v_exp_f32_e32 v122, v122
	v_exp_f32_e32 v123, v123
	v_cvt_pk_bf16_f32 v112, v108, v109
	v_cvt_pk_bf16_f32 v114, v165, v166
	v_cvt_pk_bf16_f32 v115, v167, v115
	v_max_f32_e32 v116, v116, v117
	v_cmp_lt_f32_e32 vcc, s22, v116
	v_mfma_f32_16x16x32_bf16 v[20:23], v[0:3], v[112:115], v[20:23]
	v_cvt_pk_bf16_f32 v108, v120, v121
	v_cvt_pk_bf16_f32 v109, v122, v123
	s_nop 1
	v_mfma_f32_16x16x32_bf16 v[20:23], v[0:3], v[108:111], v[20:23]
	s_cbranch_vccz .LBB0_167
	v_max_f32_e32 v116, 0, v116
	v_exp_f32_e64 v118, -v116
	v_add_f32_e32 v140, v140, v116
	v_pk_add_f32 v[96:97], v[96:97], v[116:117] op_sel_hi:[1,0] neg_lo:[0,1] neg_hi:[0,1]
	v_pk_add_f32 v[98:99], v[98:99], v[116:117] op_sel_hi:[1,0] neg_lo:[0,1] neg_hi:[0,1]
	v_pk_mul_f32 v[86:87], v[86:87], v[118:119] op_sel_hi:[1,0]
	v_pk_mul_f32 v[84:85], v[84:85], v[118:119] op_sel_hi:[1,0]
	v_pk_mul_f32 v[78:79], v[78:79], v[118:119] op_sel_hi:[1,0]
	v_pk_mul_f32 v[76:77], v[76:77], v[118:119] op_sel_hi:[1,0]
	v_pk_mul_f32 v[70:71], v[70:71], v[118:119] op_sel_hi:[1,0]
	v_pk_mul_f32 v[68:69], v[68:69], v[118:119] op_sel_hi:[1,0]
	v_pk_mul_f32 v[62:63], v[62:63], v[118:119] op_sel_hi:[1,0]
	v_pk_mul_f32 v[60:61], v[60:61], v[118:119] op_sel_hi:[1,0]
	v_pk_mul_f32 v[54:55], v[54:55], v[118:119] op_sel_hi:[1,0]
	v_pk_mul_f32 v[52:53], v[52:53], v[118:119] op_sel_hi:[1,0]
	v_pk_mul_f32 v[46:47], v[46:47], v[118:119] op_sel_hi:[1,0]
	v_pk_mul_f32 v[44:45], v[44:45], v[118:119] op_sel_hi:[1,0]
	v_pk_mul_f32 v[34:35], v[34:35], v[118:119] op_sel_hi:[1,0]
	v_pk_mul_f32 v[32:33], v[32:33], v[118:119] op_sel_hi:[1,0]
	v_pk_mul_f32 v[30:31], v[30:31], v[118:119] op_sel_hi:[1,0]
	v_pk_mul_f32 v[28:29], v[28:29], v[118:119] op_sel_hi:[1,0]
	v_pk_mul_f32 v[90:91], v[90:91], v[118:119] op_sel_hi:[1,0]
	v_pk_mul_f32 v[88:89], v[88:89], v[118:119] op_sel_hi:[1,0]
	v_pk_add_f32 v[92:93], v[92:93], v[116:117] op_sel_hi:[1,0] neg_lo:[0,1] neg_hi:[0,1]
	v_pk_add_f32 v[94:95], v[94:95], v[116:117] op_sel_hi:[1,0] neg_lo:[0,1] neg_hi:[0,1]
	v_pk_add_f32 v[100:101], v[100:101], v[116:117] op_sel_hi:[1,0] neg_lo:[0,1] neg_hi:[0,1]
	v_pk_add_f32 v[102:103], v[102:103], v[116:117] op_sel_hi:[1,0] neg_lo:[0,1] neg_hi:[0,1]
	v_pk_add_f32 v[104:105], v[104:105], v[116:117] op_sel_hi:[1,0] neg_lo:[0,1] neg_hi:[0,1]
	v_pk_add_f32 v[106:107], v[106:107], v[116:117] op_sel_hi:[1,0] neg_lo:[0,1] neg_hi:[0,1]
	s_branch .LBB0_167

; DI int otid_w(int wave) { unsigned z = 0u; asm volatile("" : "+v"(z)); int t = wave * 64 + (int)__builtin_amdgcn_mbcnt_hi(~0u, __builtin_amdgcn_mbcnt_lo(~0u, z)); asm volatile("" : "+v"(t)); return t; }
; #define PEER_GATHER(TAB, IA, IB, RR) do { _Pragma("unroll") for (int g = 0; g < 16; ++g) { \
;     const unsigned _w = (g < 8 ? IA : IB)[(g >> 1) & 3]; RR[g] = *(const u32x4*)((TAB) + row_off(_w, c16, (g & 1) != 0)); } } while (0)
; DI void phase_peer_v(const Params& p, int layer, int wave) {
;   const int tid = otid_w(wave), lane = tid & 63, wid = wave, c = lane & 7, r = lane >> 3;
;   const int x = blockIdx.x & 7, wslot = (blockIdx.x >> 3) * 8 + wid, nslot = (gridDim.x >> 3) * 8;
;   const unsigned char* vb = W_VB(p) + (size_t)x * (PEER_N * 128);
;   const unsigned c16 = (unsigned)c * 16u;
;   u16* y2 = W_Y(p);
;   const int ocol = x * 128 + 16 * c + 4 * ((lane >> 4) & 1) + 8 * (lane >> 5);
;   u32x4 iAa, iBa, iAb, iBb;
;   u32x4 wAa, wBa, wAb, wBb, wA, wB;
;   u32x2 hRa, hRb, hR;
;   u32x4 rrA[16], rrB[16];
;     ...
;   int t = wslot;
;   PEER_META_V(t, iAa, iBa, wAa, wBa, hRa);
;   PEER_META_V(t + nslot, iAb, iBb, wAb, wBb, hRb);
;   PEER_GATHER(vb, iAa, iBa, rrA);
.LBB0_184:
	s_and_b64 vcc, exec, s[78:79]
	s_cbranch_vccz .LBB0_195
	s_waitcnt vmcnt(0)
	v_mov_b32_e32 v0, v177
	v_readlane_b32 s0, v253, 51
	v_mbcnt_lo_u32_b32 v0, -1, v0
	v_mbcnt_hi_u32_b32 v0, -1, v0
	v_add_u32_e32 v0, s64, v0
	v_readlane_b32 s1, v253, 52
	v_lshlrev_b32_e32 v1, 1, v0
	v_and_b32_e32 v1, 0x70, v1
	v_lshlrev_b32_e32 v176, 1, v1
	s_waitcnt lgkmcnt(0)
	s_nop 0
	global_load_dwordx4 v[6:9], v176, s[0:1]
	global_load_dwordx4 v[12:15], v176, s[0:1] offset:16
	v_readlane_b32 s0, v253, 56
	v_readlane_b32 s1, v253, 57
	v_lshlrev_b32_e32 v1, 4, v0
	s_andn2_b64 vcc, exec, s[0:1]
	v_and_b32_e32 v205, 0x70, v1
	s_waitcnt vmcnt(1)
	v_mad_u32_u16 v2, v6, v195, v205
	v_mad_u32_u16 v3, v6, v195, v205 op_sel:[1,0,0,0]
	v_mad_u32_u16 v4, v7, v195, v205
	v_mad_u32_u16 v5, v7, v195, v205 op_sel:[1,0,0,0]
	v_mad_u32_u16 v6, v8, v195, v205
	v_mad_u32_u16 v7, v8, v195, v205 op_sel:[1,0,0,0]
	v_mad_u32_u16 v8, v9, v195, v205
	v_mad_u32_u16 v9, v9, v195, v205 op_sel:[1,0,0,0]
	s_waitcnt vmcnt(0)
	v_mad_u32_u16 v10, v12, v195, v205
	v_mad_u32_u16 v11, v12, v195, v205 op_sel:[1,0,0,0]
	v_mad_u32_u16 v16, v13, v195, v205
	v_mad_u32_u16 v17, v13, v195, v205 op_sel:[1,0,0,0]
	v_mad_u32_u16 v18, v14, v195, v205
	v_mad_u32_u16 v19, v14, v195, v205 op_sel:[1,0,0,0]
	v_mad_u32_u16 v12, v15, v195, v205
	v_mad_u32_u16 v1, v15, v195, v205 op_sel:[1,0,0,0]
	s_cbranch_vccnz .LBB0_194
	v_lshrrev_b32_e32 v13, 2, v0
	v_and_b32_e32 v38, 12, v13
	v_readlane_b32 s4, v253, 53
	v_readlane_b32 s0, v254, 28
	v_readlane_b32 s1, v254, 29
	v_or3_b32 v13, v38, s4, v205
	v_lshlrev_b32_e32 v36, 1, v13
	global_load_dwordx4 v[12:15], v12, s[80:81]
	s_nop 0
	global_load_dwordx4 v[20:23], v19, s[80:81]
	global_load_dwordx4 v[24:27], v18, s[80:81]
	global_load_dwordx4 v[28:31], v17, s[80:81]
	global_load_dwordx4 v[32:35], v16, s[80:81]
	global_load_dwordx4 v[40:43], v11, s[80:81]
	global_load_dwordx4 v[52:55], v10, s[80:81]
	global_load_dwordx4 v[60:63], v9, s[80:81]
	global_load_dwordx4 v[68:71], v8, s[80:81]
	global_load_dwordx4 v[80:83], v7, s[80:81]
	global_load_dwordx4 v[88:91], v6, s[80:81]
	global_load_dwordx4 v[96:99], v5, s[80:81]
	global_load_dwordx4 v[104:107], v4, s[80:81]
	global_load_dwordx4 v[112:115], v3, s[80:81]
	global_load_dwordx4 v[120:123], v2, s[80:81]
	v_lshl_add_u64 v[180:181], s[0:1], 0, v[176:177]
	v_readlane_b32 s0, v253, 58
	v_readlane_b32 s1, v253, 59
	v_and_b32_e32 v0, 8, v0
	v_lshl_add_u64 v[178:179], s[66:67], 0, v[176:177]
	v_mov_b32_e32 v37, v177
	v_lshl_add_u64 v[182:183], s[76:77], 0, v[36:37]
	v_lshl_add_u64 v[184:185], s[50:51], 0, v[36:37]
	global_load_dwordx2 v[186:187], v36, s[0:1]
	v_readlane_b32 s0, v254, 26
	v_readlane_b32 s1, v254, 27
	s_nop 4
	global_load_dwordx4 v[8:11], v176, s[0:1] offset:16
	global_load_dwordx4 v[72:75], v176, s[0:1]
	v_readlane_b32 s0, v253, 62
	v_readlane_b32 s1, v253, 63
	s_nop 4
	global_load_dwordx4 v[128:131], v176, s[0:1] offset:16
	global_load_dwordx4 v[140:143], v176, s[0:1]
	v_readlane_b32 s0, v254, 0
	v_readlane_b32 s1, v254, 1
	s_mov_b32 s8, s38
	s_nop 3
	global_load_dwordx2 v[160:161], v36, s[0:1]
	v_readlane_b32 s0, v254, 30
	v_readlane_b32 s1, v254, 31
	s_nop 4
	global_load_dwordx4 v[168:171], v176, s[0:1] offset:16
	global_load_dwordx4 v[172:175], v176, s[0:1]
	global_load_dwordx4 v[16:19], v1, s[80:81]
	v_cmp_eq_u32_e64 s[0:1], 0, v0
	v_add_u32_e32 v0, s4, v205
	v_readlane_b32 s4, v255, 20
	v_add_lshl_u32 v176, v0, v38, 1
	v_readlane_b32 s5, v255, 21
	s_nop 1
	v_lshl_add_u64 v[188:189], s[4:5], 0, v[176:177]
	v_lshrrev_b32_e32 v228, 2, v205
	v_mov_b32_e32 v229, 0
	v_lshl_add_u64 v[224:225], v[178:179], 0, v[228:229]
	v_lshl_add_u64 v[226:227], v[180:181], 0, v[228:229]
	v_mbcnt_lo_u32_b32 v230, -1, 0
	v_mbcnt_hi_u32_b32 v230, -1, v230
	v_and_b32_e32 v230, 56, v230
	v_lshlrev_b32_e32 v230, 2, v230
	s_waitcnt vmcnt(0)
	s_branch .LBB0_189

; #define PEER_GATHER(TAB, IA, IB, RR) do { _Pragma("unroll") for (int g = 0; g < 16; ++g) { \
;     const unsigned _w = (g < 8 ? IA : IB)[(g >> 1) & 3]; RR[g] = *(const u32x4*)((TAB) + row_off(_w, c16, (g & 1) != 0)); } } while (0)
; DI void phase_peer_v(const Params& p, int layer, int wave) {
;     ...
;   for (; t < TTOK; t += 2 * nslot) {
;     wA = wAa; wB = wBa; hR = hRa;
;     PEER_META_V(t + 2 * nslot, iAa, iBa, wAa, wBa, hRa);
;     PEER_GATHER(vb, iAb, iBb, rrB);
.LBB0_188:
	s_waitcnt lgkmcnt(0)
	v_mov_b64_e32 v[174:175], v[6:7]
	v_mov_b64_e32 v[170:171], v[2:3]
	v_mov_b64_e32 v[72:73], v[164:165]
	v_mov_b64_e32 v[8:9], v[160:161]
	v_lshl_add_u64 v[188:189], v[188:189], 0, s[60:61]
	s_and_b64 vcc, exec, s[4:5]
	v_mov_b64_e32 v[172:173], v[4:5]
	v_mov_b64_e32 v[168:169], v[0:1]
	v_mov_b64_e32 v[74:75], v[166:167]
	v_mov_b64_e32 v[10:11], v[162:163]
	v_mov_b64_e32 v[160:161], v[190:191]
	s_waitcnt vmcnt(17)
	v_mov_b64_e32 v[186:187], v[192:193]
	s_mov_b32 s8, s10
	s_cbranch_vccnz .LBB0_194
.LBB0_189:
	s_add_i32 s10, s8, s88
	s_cmp_gt_i32 s10, 0x101ff
	s_cselect_b64 s[4:5], -1, 0
	s_cmp_lt_i32 s10, 0x10200
	s_cselect_b32 s6, s10, s38
	s_ashr_i32 s7, s6, 31
	s_lshl_b64 s[12:13], s[6:7], 8
	s_lshl_b64 s[6:7], s[6:7], 11
	v_lshl_add_u64 v[222:223], v[224:225], 0, s[12:13]
	global_load_dword v232, v[222:223], off
	v_lshl_add_u64 v[222:223], v[226:227], 0, s[12:13]
	global_load_dword v233, v[222:223], off
	v_lshl_add_u64 v[36:37], v[182:183], 0, s[6:7]
	global_load_dwordx2 v[190:191], v[36:37], off
	v_mad_u32_u16 v206, v140, v195, v205
	v_mad_u32_u16 v207, v140, v195, v205 op_sel:[1,0,0,0]
	v_mad_u32_u16 v208, v141, v195, v205
	v_mad_u32_u16 v209, v141, v195, v205 op_sel:[1,0,0,0]
	v_mad_u32_u16 v210, v142, v195, v205
	v_mad_u32_u16 v211, v142, v195, v205 op_sel:[1,0,0,0]
	v_mad_u32_u16 v212, v143, v195, v205
	v_mad_u32_u16 v213, v143, v195, v205 op_sel:[1,0,0,0]
	v_mad_u32_u16 v214, v128, v195, v205
	v_mad_u32_u16 v215, v128, v195, v205 op_sel:[1,0,0,0]
	v_mad_u32_u16 v216, v129, v195, v205
	v_mad_u32_u16 v217, v129, v195, v205 op_sel:[1,0,0,0]
	v_mad_u32_u16 v218, v130, v195, v205
	v_mad_u32_u16 v219, v130, v195, v205 op_sel:[1,0,0,0]
	v_mad_u32_u16 v220, v131, v195, v205
	v_mad_u32_u16 v221, v131, v195, v205 op_sel:[1,0,0,0]
	global_load_dwordx4 v[148:151], v206, s[80:81]
	s_waitcnt vmcnt(20)
	v_cvt_pk_f32_fp8_e32 v[162:163], v122
	v_cvt_pk_f32_fp8_e32 v[130:131], v120
	v_cvt_pk_f32_fp8_sdwa v[140:141], v120 src0_sel:WORD_1
	v_cvt_pk_f32_fp8_e32 v[142:143], v121
	v_cvt_pk_f32_fp8_sdwa v[120:121], v121 src0_sel:WORD_1
	v_cvt_pk_f32_fp8_sdwa v[164:165], v122 src0_sel:WORD_1
	v_cvt_pk_f32_fp8_e32 v[166:167], v123
	v_cvt_pk_f32_fp8_sdwa v[122:123], v123 src0_sel:WORD_1
	global_load_dwordx4 v[144:147], v207, s[80:81]
	s_waitcnt vmcnt(20)
	v_cvt_pk_f32_fp8_e32 v[192:193], v112
	v_lshlrev_b32_e32 v128, 16, v172
	v_pk_fma_f32 v[130:131], v[128:129], v[130:131], 0 op_sel_hi:[0,1,0]
	v_pk_fma_f32 v[140:141], v[128:129], v[140:141], 0 op_sel_hi:[0,1,0]
	v_pk_fma_f32 v[142:143], v[128:129], v[142:143], 0 op_sel_hi:[0,1,0]
	v_pk_fma_f32 v[120:121], v[128:129], v[120:121], 0 op_sel_hi:[0,1,0]
	v_pk_fma_f32 v[162:163], v[128:129], v[162:163], 0 op_sel_hi:[0,1,0]
	v_pk_fma_f32 v[164:165], v[128:129], v[164:165], 0 op_sel_hi:[0,1,0]
	v_pk_fma_f32 v[166:167], v[128:129], v[166:167], 0 op_sel_hi:[0,1,0]
	v_pk_fma_f32 v[122:123], v[128:129], v[122:123], 0 op_sel_hi:[0,1,0]
	v_and_b32_e32 v128, 0xffff0000, v172
	v_cvt_pk_f32_fp8_sdwa v[202:203], v112 src0_sel:WORD_1
	v_pk_fma_f32 v[130:131], v[128:129], v[192:193], v[130:131] op_sel_hi:[0,1,1]
	v_cvt_pk_f32_fp8_e32 v[192:193], v113
	v_cvt_pk_f32_fp8_sdwa v[112:113], v113 src0_sel:WORD_1
	v_pk_fma_f32 v[140:141], v[128:129], v[202:203], v[140:141] op_sel_hi:[0,1,1]
	v_pk_fma_f32 v[142:143], v[128:129], v[192:193], v[142:143] op_sel_hi:[0,1,1]
	v_pk_fma_f32 v[112:113], v[128:129], v[112:113], v[120:121] op_sel_hi:[0,1,1]
	v_cvt_pk_f32_fp8_e32 v[120:121], v114
	v_cvt_pk_f32_fp8_sdwa v[192:193], v114 src0_sel:WORD_1
	v_pk_fma_f32 v[120:121], v[128:129], v[120:121], v[162:163] op_sel_hi:[0,1,1]
	v_pk_fma_f32 v[162:163], v[128:129], v[192:193], v[164:165] op_sel_hi:[0,1,1]
	v_cvt_pk_f32_fp8_e32 v[164:165], v115
	v_cvt_pk_f32_fp8_sdwa v[114:115], v115 src0_sel:WORD_1
	v_pk_fma_f32 v[164:165], v[128:129], v[164:165], v[166:167] op_sel_hi:[0,1,1]
	v_pk_fma_f32 v[114:115], v[128:129], v[114:115], v[122:123] op_sel_hi:[0,1,1]
	global_load_dwordx4 v[136:139], v208, s[80:81]
	s_waitcnt vmcnt(20)
	v_cvt_pk_f32_fp8_e32 v[128:129], v104
	v_cvt_pk_f32_fp8_sdwa v[166:167], v104 src0_sel:WORD_1
	v_lshlrev_b32_e32 v122, 16, v173
	v_pk_fma_f32 v[128:129], v[122:123], v[128:129], v[130:131] op_sel_hi:[0,1,1]
	v_pk_fma_f32 v[130:131], v[122:123], v[166:167], v[140:141] op_sel_hi:[0,1,1]
	v_cvt_pk_f32_fp8_e32 v[140:141], v105
	v_cvt_pk_f32_fp8_sdwa v[104:105], v105 src0_sel:WORD_1
	v_pk_fma_f32 v[140:141], v[122:123], v[140:141], v[142:143] op_sel_hi:[0,1,1]
	v_pk_fma_f32 v[104:105], v[122:123], v[104:105], v[112:113] op_sel_hi:[0,1,1]
	v_cvt_pk_f32_fp8_e32 v[112:113], v106
	v_cvt_pk_f32_fp8_sdwa v[142:143], v106 src0_sel:WORD_1
	v_pk_fma_f32 v[112:113], v[122:123], v[112:113], v[120:121] op_sel_hi:[0,1,1]
	v_pk_fma_f32 v[120:121], v[122:123], v[142:143], v[162:163] op_sel_hi:[0,1,1]
	v_cvt_pk_f32_fp8_e32 v[142:143], v107
	v_cvt_pk_f32_fp8_sdwa v[106:107], v107 src0_sel:WORD_1
	global_load_dwordx4 v[132:135], v209, s[80:81]
	s_waitcnt vmcnt(20)
	v_cvt_pk_f32_fp8_sdwa v[162:163], v96 src0_sel:WORD_1
	v_pk_fma_f32 v[142:143], v[122:123], v[142:143], v[164:165] op_sel_hi:[0,1,1]
	v_pk_fma_f32 v[106:107], v[122:123], v[106:107], v[114:115] op_sel_hi:[0,1,1]
	v_cvt_pk_f32_fp8_e32 v[122:123], v96
	v_and_b32_e32 v114, 0xffff0000, v173
	v_pk_fma_f32 v[122:123], v[114:115], v[122:123], v[128:129] op_sel_hi:[0,1,1]
	v_pk_fma_f32 v[128:129], v[114:115], v[162:163], v[130:131] op_sel_hi:[0,1,1]
	v_cvt_pk_f32_fp8_e32 v[130:131], v97
	v_cvt_pk_f32_fp8_sdwa v[96:97], v97 src0_sel:WORD_1
	v_pk_fma_f32 v[130:131], v[114:115], v[130:131], v[140:141] op_sel_hi:[0,1,1]
	v_pk_fma_f32 v[96:97], v[114:115], v[96:97], v[104:105] op_sel_hi:[0,1,1]
	v_cvt_pk_f32_fp8_e32 v[104:105], v98
	v_cvt_pk_f32_fp8_sdwa v[140:141], v98 src0_sel:WORD_1
	v_pk_fma_f32 v[104:105], v[114:115], v[104:105], v[112:113] op_sel_hi:[0,1,1]
	v_pk_fma_f32 v[112:113], v[114:115], v[140:141], v[120:121] op_sel_hi:[0,1,1]
	v_cvt_pk_f32_fp8_e32 v[120:121], v99
	v_cvt_pk_f32_fp8_sdwa v[98:99], v99 src0_sel:WORD_1
	global_load_dwordx4 v[124:127], v210, s[80:81]
	s_waitcnt vmcnt(20)
	v_cvt_pk_f32_fp8_sdwa v[140:141], v88 src0_sel:WORD_1
	v_pk_fma_f32 v[120:121], v[114:115], v[120:121], v[142:143] op_sel_hi:[0,1,1]
	v_pk_fma_f32 v[98:99], v[114:115], v[98:99], v[106:107] op_sel_hi:[0,1,1]
	v_cvt_pk_f32_fp8_e32 v[114:115], v88
	v_lshlrev_b32_e32 v106, 16, v174
	v_pk_fma_f32 v[114:115], v[106:107], v[114:115], v[122:123] op_sel_hi:[0,1,1]
	v_pk_fma_f32 v[122:123], v[106:107], v[140:141], v[128:129] op_sel_hi:[0,1,1]
	v_cvt_pk_f32_fp8_e32 v[128:129], v89
	v_cvt_pk_f32_fp8_sdwa v[88:89], v89 src0_sel:WORD_1
	v_pk_fma_f32 v[128:129], v[106:107], v[128:129], v[130:131] op_sel_hi:[0,1,1]
	v_pk_fma_f32 v[88:89], v[106:107], v[88:89], v[96:97] op_sel_hi:[0,1,1]
	v_cvt_pk_f32_fp8_e32 v[96:97], v90
	v_cvt_pk_f32_fp8_sdwa v[130:131], v90 src0_sel:WORD_1
	v_pk_fma_f32 v[96:97], v[106:107], v[96:97], v[104:105] op_sel_hi:[0,1,1]
	v_pk_fma_f32 v[104:105], v[106:107], v[130:131], v[112:113] op_sel_hi:[0,1,1]
	v_cvt_pk_f32_fp8_e32 v[112:113], v91
	v_cvt_pk_f32_fp8_sdwa v[90:91], v91 src0_sel:WORD_1
	v_pk_fma_f32 v[112:113], v[106:107], v[112:113], v[120:121] op_sel_hi:[0,1,1]
	v_pk_fma_f32 v[90:91], v[106:107], v[90:91], v[98:99] op_sel_hi:[0,1,1]
	global_load_dwordx4 v[116:119], v211, s[80:81]
	s_waitcnt vmcnt(20)
	v_cvt_pk_f32_fp8_e32 v[106:107], v80
	v_cvt_pk_f32_fp8_sdwa v[120:121], v80 src0_sel:WORD_1
	v_and_b32_e32 v98, 0xffff0000, v174
	v_pk_fma_f32 v[106:107], v[98:99], v[106:107], v[114:115] op_sel_hi:[0,1,1]
	v_pk_fma_f32 v[114:115], v[98:99], v[120:121], v[122:123] op_sel_hi:[0,1,1]
	v_cvt_pk_f32_fp8_e32 v[120:121], v81
	v_cvt_pk_f32_fp8_sdwa v[80:81], v81 src0_sel:WORD_1
	v_cvt_pk_f32_fp8_sdwa v[122:123], v82 src0_sel:WORD_1
	v_pk_fma_f32 v[120:121], v[98:99], v[120:121], v[128:129] op_sel_hi:[0,1,1]
	v_pk_fma_f32 v[80:81], v[98:99], v[80:81], v[88:89] op_sel_hi:[0,1,1]
	v_cvt_pk_f32_fp8_e32 v[88:89], v82
	v_pk_fma_f32 v[88:89], v[98:99], v[88:89], v[96:97] op_sel_hi:[0,1,1]
	v_pk_fma_f32 v[96:97], v[98:99], v[122:123], v[104:105] op_sel_hi:[0,1,1]
	v_cvt_pk_f32_fp8_e32 v[104:105], v83
	v_cvt_pk_f32_fp8_sdwa v[82:83], v83 src0_sel:WORD_1
	v_pk_fma_f32 v[104:105], v[98:99], v[104:105], v[112:113] op_sel_hi:[0,1,1]
	v_pk_fma_f32 v[82:83], v[98:99], v[82:83], v[90:91] op_sel_hi:[0,1,1]
	global_load_dwordx4 v[108:111], v212, s[80:81]
	s_waitcnt vmcnt(20)
	v_cvt_pk_f32_fp8_e32 v[98:99], v68
	v_cvt_pk_f32_fp8_sdwa v[112:113], v68 src0_sel:WORD_1
	v_lshlrev_b32_e32 v90, 16, v175
	v_pk_fma_f32 v[98:99], v[90:91], v[98:99], v[106:107] op_sel_hi:[0,1,1]
	v_pk_fma_f32 v[106:107], v[90:91], v[112:113], v[114:115] op_sel_hi:[0,1,1]
	v_cvt_pk_f32_fp8_e32 v[112:113], v69
	v_cvt_pk_f32_fp8_sdwa v[68:69], v69 src0_sel:WORD_1
	v_cvt_pk_f32_fp8_sdwa v[114:115], v70 src0_sel:WORD_1
	v_pk_fma_f32 v[112:113], v[90:91], v[112:113], v[120:121] op_sel_hi:[0,1,1]
	v_pk_fma_f32 v[68:69], v[90:91], v[68:69], v[80:81] op_sel_hi:[0,1,1]
	v_cvt_pk_f32_fp8_e32 v[80:81], v70
	v_pk_fma_f32 v[80:81], v[90:91], v[80:81], v[88:89] op_sel_hi:[0,1,1]
	v_pk_fma_f32 v[88:89], v[90:91], v[114:115], v[96:97] op_sel_hi:[0,1,1]
	v_cvt_pk_f32_fp8_e32 v[96:97], v71
	v_cvt_pk_f32_fp8_sdwa v[70:71], v71 src0_sel:WORD_1
	v_pk_fma_f32 v[96:97], v[90:91], v[96:97], v[104:105] op_sel_hi:[0,1,1]
	v_pk_fma_f32 v[70:71], v[90:91], v[70:71], v[82:83] op_sel_hi:[0,1,1]
	global_load_dwordx4 v[100:103], v213, s[80:81]
	s_waitcnt vmcnt(20)
	v_cvt_pk_f32_fp8_e32 v[90:91], v60
	v_cvt_pk_f32_fp8_sdwa v[104:105], v60 src0_sel:WORD_1
	v_and_b32_e32 v82, 0xffff0000, v175
	v_pk_fma_f32 v[90:91], v[82:83], v[90:91], v[98:99] op_sel_hi:[0,1,1]
	v_pk_fma_f32 v[98:99], v[82:83], v[104:105], v[106:107] op_sel_hi:[0,1,1]
	v_cvt_pk_f32_fp8_e32 v[104:105], v61
	v_cvt_pk_f32_fp8_sdwa v[60:61], v61 src0_sel:WORD_1
	v_cvt_pk_f32_fp8_sdwa v[106:107], v62 src0_sel:WORD_1
	v_pk_fma_f32 v[104:105], v[82:83], v[104:105], v[112:113] op_sel_hi:[0,1,1]
	v_pk_fma_f32 v[60:61], v[82:83], v[60:61], v[68:69] op_sel_hi:[0,1,1]
	v_cvt_pk_f32_fp8_e32 v[68:69], v62
	v_pk_fma_f32 v[68:69], v[82:83], v[68:69], v[80:81] op_sel_hi:[0,1,1]
	v_pk_fma_f32 v[80:81], v[82:83], v[106:107], v[88:89] op_sel_hi:[0,1,1]
	v_cvt_pk_f32_fp8_e32 v[88:89], v63
	v_cvt_pk_f32_fp8_sdwa v[62:63], v63 src0_sel:WORD_1
	v_pk_fma_f32 v[88:89], v[82:83], v[88:89], v[96:97] op_sel_hi:[0,1,1]
	v_pk_fma_f32 v[62:63], v[82:83], v[62:63], v[70:71] op_sel_hi:[0,1,1]
	global_load_dwordx4 v[92:95], v214, s[80:81]
	s_waitcnt vmcnt(20)
	v_cvt_pk_f32_fp8_e32 v[82:83], v52
	v_cvt_pk_f32_fp8_sdwa v[96:97], v52 src0_sel:WORD_1
	v_lshlrev_b32_e32 v70, 16, v168
	v_pk_fma_f32 v[82:83], v[70:71], v[82:83], v[90:91] op_sel_hi:[0,1,1]
	v_pk_fma_f32 v[90:91], v[70:71], v[96:97], v[98:99] op_sel_hi:[0,1,1]
	v_cvt_pk_f32_fp8_e32 v[96:97], v53
	v_cvt_pk_f32_fp8_sdwa v[52:53], v53 src0_sel:WORD_1
	v_cvt_pk_f32_fp8_sdwa v[98:99], v54 src0_sel:WORD_1
	v_pk_fma_f32 v[96:97], v[70:71], v[96:97], v[104:105] op_sel_hi:[0,1,1]
	v_pk_fma_f32 v[52:53], v[70:71], v[52:53], v[60:61] op_sel_hi:[0,1,1]
	v_cvt_pk_f32_fp8_e32 v[60:61], v54
	v_pk_fma_f32 v[60:61], v[70:71], v[60:61], v[68:69] op_sel_hi:[0,1,1]
	v_pk_fma_f32 v[68:69], v[70:71], v[98:99], v[80:81] op_sel_hi:[0,1,1]
	v_cvt_pk_f32_fp8_e32 v[80:81], v55
	v_cvt_pk_f32_fp8_sdwa v[54:55], v55 src0_sel:WORD_1
	v_pk_fma_f32 v[80:81], v[70:71], v[80:81], v[88:89] op_sel_hi:[0,1,1]
	v_pk_fma_f32 v[54:55], v[70:71], v[54:55], v[62:63] op_sel_hi:[0,1,1]
	global_load_dwordx4 v[84:87], v215, s[80:81]
	s_waitcnt vmcnt(20)
	v_cvt_pk_f32_fp8_e32 v[70:71], v40
	v_cvt_pk_f32_fp8_sdwa v[88:89], v40 src0_sel:WORD_1
	v_and_b32_e32 v62, 0xffff0000, v168
	v_pk_fma_f32 v[70:71], v[62:63], v[70:71], v[82:83] op_sel_hi:[0,1,1]
	v_pk_fma_f32 v[82:83], v[62:63], v[88:89], v[90:91] op_sel_hi:[0,1,1]
	v_cvt_pk_f32_fp8_e32 v[88:89], v41
	v_cvt_pk_f32_fp8_sdwa v[40:41], v41 src0_sel:WORD_1
	v_cvt_pk_f32_fp8_sdwa v[90:91], v42 src0_sel:WORD_1
	v_pk_fma_f32 v[88:89], v[62:63], v[88:89], v[96:97] op_sel_hi:[0,1,1]
	v_pk_fma_f32 v[40:41], v[62:63], v[40:41], v[52:53] op_sel_hi:[0,1,1]
	v_cvt_pk_f32_fp8_e32 v[52:53], v42
	v_pk_fma_f32 v[52:53], v[62:63], v[52:53], v[60:61] op_sel_hi:[0,1,1]
	v_pk_fma_f32 v[60:61], v[62:63], v[90:91], v[68:69] op_sel_hi:[0,1,1]
	v_cvt_pk_f32_fp8_e32 v[68:69], v43
	v_cvt_pk_f32_fp8_sdwa v[42:43], v43 src0_sel:WORD_1
	v_pk_fma_f32 v[68:69], v[62:63], v[68:69], v[80:81] op_sel_hi:[0,1,1]
	v_pk_fma_f32 v[42:43], v[62:63], v[42:43], v[54:55] op_sel_hi:[0,1,1]
	global_load_dwordx4 v[76:79], v216, s[80:81]
	s_waitcnt vmcnt(20)
	v_cvt_pk_f32_fp8_e32 v[62:63], v32
	v_cvt_pk_f32_fp8_sdwa v[80:81], v32 src0_sel:WORD_1
	v_lshlrev_b32_e32 v54, 16, v169
	v_pk_fma_f32 v[62:63], v[54:55], v[62:63], v[70:71] op_sel_hi:[0,1,1]
	v_pk_fma_f32 v[70:71], v[54:55], v[80:81], v[82:83] op_sel_hi:[0,1,1]
	v_cvt_pk_f32_fp8_e32 v[80:81], v33
	v_cvt_pk_f32_fp8_sdwa v[32:33], v33 src0_sel:WORD_1
	v_cvt_pk_f32_fp8_sdwa v[82:83], v34 src0_sel:WORD_1
	v_pk_fma_f32 v[80:81], v[54:55], v[80:81], v[88:89] op_sel_hi:[0,1,1]
	v_pk_fma_f32 v[32:33], v[54:55], v[32:33], v[40:41] op_sel_hi:[0,1,1]
	v_cvt_pk_f32_fp8_e32 v[40:41], v34
	v_pk_fma_f32 v[40:41], v[54:55], v[40:41], v[52:53] op_sel_hi:[0,1,1]
	v_pk_fma_f32 v[52:53], v[54:55], v[82:83], v[60:61] op_sel_hi:[0,1,1]
	v_cvt_pk_f32_fp8_e32 v[60:61], v35
	v_cvt_pk_f32_fp8_sdwa v[34:35], v35 src0_sel:WORD_1
	v_pk_fma_f32 v[60:61], v[54:55], v[60:61], v[68:69] op_sel_hi:[0,1,1]
	v_pk_fma_f32 v[34:35], v[54:55], v[34:35], v[42:43] op_sel_hi:[0,1,1]
	global_load_dwordx4 v[64:67], v217, s[80:81]
	s_waitcnt vmcnt(20)
	v_cvt_pk_f32_fp8_e32 v[54:55], v28
	v_cvt_pk_f32_fp8_sdwa v[68:69], v28 src0_sel:WORD_1
	v_and_b32_e32 v42, 0xffff0000, v169
	v_pk_fma_f32 v[54:55], v[42:43], v[54:55], v[62:63] op_sel_hi:[0,1,1]
	v_pk_fma_f32 v[62:63], v[42:43], v[68:69], v[70:71] op_sel_hi:[0,1,1]
	v_cvt_pk_f32_fp8_e32 v[68:69], v29
	v_cvt_pk_f32_fp8_sdwa v[28:29], v29 src0_sel:WORD_1
	v_cvt_pk_f32_fp8_sdwa v[70:71], v30 src0_sel:WORD_1
	v_pk_fma_f32 v[68:69], v[42:43], v[68:69], v[80:81] op_sel_hi:[0,1,1]
	v_pk_fma_f32 v[28:29], v[42:43], v[28:29], v[32:33] op_sel_hi:[0,1,1]
	v_cvt_pk_f32_fp8_e32 v[32:33], v30
	v_pk_fma_f32 v[32:33], v[42:43], v[32:33], v[40:41] op_sel_hi:[0,1,1]
	v_pk_fma_f32 v[40:41], v[42:43], v[70:71], v[52:53] op_sel_hi:[0,1,1]
	v_cvt_pk_f32_fp8_e32 v[52:53], v31
	v_cvt_pk_f32_fp8_sdwa v[30:31], v31 src0_sel:WORD_1
	v_pk_fma_f32 v[52:53], v[42:43], v[52:53], v[60:61] op_sel_hi:[0,1,1]
	v_pk_fma_f32 v[30:31], v[42:43], v[30:31], v[34:35] op_sel_hi:[0,1,1]
	global_load_dwordx4 v[56:59], v218, s[80:81]
	s_waitcnt vmcnt(20)
	v_cvt_pk_f32_fp8_e32 v[42:43], v24
	v_cvt_pk_f32_fp8_sdwa v[60:61], v24 src0_sel:WORD_1
	v_lshlrev_b32_e32 v34, 16, v170
	v_pk_fma_f32 v[42:43], v[34:35], v[42:43], v[54:55] op_sel_hi:[0,1,1]
	v_pk_fma_f32 v[54:55], v[34:35], v[60:61], v[62:63] op_sel_hi:[0,1,1]
	v_cvt_pk_f32_fp8_e32 v[60:61], v25
	v_cvt_pk_f32_fp8_sdwa v[24:25], v25 src0_sel:WORD_1
	v_cvt_pk_f32_fp8_sdwa v[62:63], v26 src0_sel:WORD_1
	v_pk_fma_f32 v[60:61], v[34:35], v[60:61], v[68:69] op_sel_hi:[0,1,1]
	v_pk_fma_f32 v[24:25], v[34:35], v[24:25], v[28:29] op_sel_hi:[0,1,1]
	v_cvt_pk_f32_fp8_e32 v[28:29], v26
	v_pk_fma_f32 v[28:29], v[34:35], v[28:29], v[32:33] op_sel_hi:[0,1,1]
	v_pk_fma_f32 v[32:33], v[34:35], v[62:63], v[40:41] op_sel_hi:[0,1,1]
	v_cvt_pk_f32_fp8_e32 v[40:41], v27
	v_cvt_pk_f32_fp8_sdwa v[26:27], v27 src0_sel:WORD_1
	v_pk_fma_f32 v[40:41], v[34:35], v[40:41], v[52:53] op_sel_hi:[0,1,1]
	v_pk_fma_f32 v[26:27], v[34:35], v[26:27], v[30:31] op_sel_hi:[0,1,1]
	global_load_dwordx4 v[48:51], v219, s[80:81]
	s_waitcnt vmcnt(20)
	v_cvt_pk_f32_fp8_e32 v[34:35], v20
	v_cvt_pk_f32_fp8_sdwa v[52:53], v20 src0_sel:WORD_1
	v_and_b32_e32 v30, 0xffff0000, v170
	v_pk_fma_f32 v[34:35], v[30:31], v[34:35], v[42:43] op_sel_hi:[0,1,1]
	v_pk_fma_f32 v[42:43], v[30:31], v[52:53], v[54:55] op_sel_hi:[0,1,1]
	v_cvt_pk_f32_fp8_e32 v[52:53], v21
	v_cvt_pk_f32_fp8_sdwa v[20:21], v21 src0_sel:WORD_1
	v_cvt_pk_f32_fp8_sdwa v[54:55], v22 src0_sel:WORD_1
	v_pk_fma_f32 v[52:53], v[30:31], v[52:53], v[60:61] op_sel_hi:[0,1,1]
	v_pk_fma_f32 v[20:21], v[30:31], v[20:21], v[24:25] op_sel_hi:[0,1,1]
	v_cvt_pk_f32_fp8_e32 v[24:25], v22
	v_pk_fma_f32 v[24:25], v[30:31], v[24:25], v[28:29] op_sel_hi:[0,1,1]
	v_pk_fma_f32 v[28:29], v[30:31], v[54:55], v[32:33] op_sel_hi:[0,1,1]
	v_cvt_pk_f32_fp8_e32 v[32:33], v23
	v_cvt_pk_f32_fp8_sdwa v[22:23], v23 src0_sel:WORD_1
	v_pk_fma_f32 v[32:33], v[30:31], v[32:33], v[40:41] op_sel_hi:[0,1,1]
	v_pk_fma_f32 v[22:23], v[30:31], v[22:23], v[26:27] op_sel_hi:[0,1,1]
	global_load_dwordx4 v[44:47], v220, s[80:81]
	s_waitcnt vmcnt(20)
	v_cvt_pk_f32_fp8_e32 v[30:31], v12
	v_cvt_pk_f32_fp8_sdwa v[40:41], v12 src0_sel:WORD_1
	v_lshlrev_b32_e32 v26, 16, v171
	v_pk_fma_f32 v[30:31], v[26:27], v[30:31], v[34:35] op_sel_hi:[0,1,1]
	v_pk_fma_f32 v[34:35], v[26:27], v[40:41], v[42:43] op_sel_hi:[0,1,1]
	v_cvt_pk_f32_fp8_e32 v[40:41], v13
	v_cvt_pk_f32_fp8_sdwa v[12:13], v13 src0_sel:WORD_1
	v_cvt_pk_f32_fp8_sdwa v[42:43], v14 src0_sel:WORD_1
	v_pk_fma_f32 v[40:41], v[26:27], v[40:41], v[52:53] op_sel_hi:[0,1,1]
	v_pk_fma_f32 v[12:13], v[26:27], v[12:13], v[20:21] op_sel_hi:[0,1,1]
	v_cvt_pk_f32_fp8_e32 v[20:21], v14
	v_pk_fma_f32 v[20:21], v[26:27], v[20:21], v[24:25] op_sel_hi:[0,1,1]
	v_pk_fma_f32 v[24:25], v[26:27], v[42:43], v[28:29] op_sel_hi:[0,1,1]
	v_cvt_pk_f32_fp8_e32 v[28:29], v15
	v_cvt_pk_f32_fp8_sdwa v[14:15], v15 src0_sel:WORD_1
	v_pk_fma_f32 v[28:29], v[26:27], v[28:29], v[32:33] op_sel_hi:[0,1,1]
	v_pk_fma_f32 v[14:15], v[26:27], v[14:15], v[22:23] op_sel_hi:[0,1,1]
	global_load_dwordx4 v[36:39], v221, s[80:81]
	s_waitcnt vmcnt(18)
	ds_bpermute_b32 v156, v230, v232
	ds_bpermute_b32 v157, v230, v232 offset:4
	ds_bpermute_b32 v158, v230, v232 offset:8
	ds_bpermute_b32 v159, v230, v232 offset:12
	ds_bpermute_b32 v152, v230, v232 offset:16
	ds_bpermute_b32 v153, v230, v232 offset:20
	ds_bpermute_b32 v154, v230, v232 offset:24
	ds_bpermute_b32 v155, v230, v232 offset:28
	s_waitcnt vmcnt(17)
	ds_bpermute_b32 v4, v230, v233
	ds_bpermute_b32 v5, v230, v233 offset:4
	ds_bpermute_b32 v6, v230, v233 offset:8
	ds_bpermute_b32 v7, v230, v233 offset:12
	ds_bpermute_b32 v0, v230, v233 offset:16
	ds_bpermute_b32 v1, v230, v233 offset:20
	ds_bpermute_b32 v2, v230, v233 offset:24
	ds_bpermute_b32 v3, v230, v233 offset:28
	v_cvt_pk_f32_fp8_e32 v[26:27], v16
	v_cvt_pk_f32_fp8_sdwa v[32:33], v16 src0_sel:WORD_1
	v_and_b32_e32 v22, 0xffff0000, v171
	v_pk_fma_f32 v[26:27], v[22:23], v[26:27], v[30:31] op_sel_hi:[0,1,1]
	v_pk_fma_f32 v[30:31], v[22:23], v[32:33], v[34:35] op_sel_hi:[0,1,1]
	v_cvt_pk_f32_fp8_e32 v[32:33], v17
	v_cvt_pk_f32_fp8_sdwa v[16:17], v17 src0_sel:WORD_1
	v_cvt_pk_f32_fp8_sdwa v[34:35], v18 src0_sel:WORD_1
	v_pk_fma_f32 v[32:33], v[22:23], v[32:33], v[40:41] op_sel_hi:[0,1,1]
	v_pk_fma_f32 v[12:13], v[22:23], v[16:17], v[12:13] op_sel_hi:[0,1,1]
	v_cvt_pk_f32_fp8_e32 v[16:17], v18
	v_pk_fma_f32 v[16:17], v[22:23], v[16:17], v[20:21] op_sel_hi:[0,1,1]
	v_pk_fma_f32 v[20:21], v[22:23], v[34:35], v[24:25] op_sel_hi:[0,1,1]
	v_cvt_pk_f32_fp8_e32 v[24:25], v19
	v_cvt_pk_f32_fp8_sdwa v[18:19], v19 src0_sel:WORD_1
	v_permlane32_swap_b32_e32 v26, v16
	v_pk_fma_f32 v[24:25], v[22:23], v[24:25], v[28:29] op_sel_hi:[0,1,1]
	v_pk_fma_f32 v[14:15], v[22:23], v[18:19], v[14:15] op_sel_hi:[0,1,1]
	v_permlane32_swap_b32_e32 v27, v17
	v_permlane32_swap_b32_e32 v30, v20
	v_permlane32_swap_b32_e32 v31, v21
	v_permlane32_swap_b32_e32 v32, v24
	v_permlane32_swap_b32_e32 v33, v25
	v_permlane32_swap_b32_e32 v12, v14
	v_permlane32_swap_b32_e32 v13, v15
	v_add_f32_e32 v16, v26, v16
	v_add_f32_e32 v17, v27, v17
	v_add_f32_e32 v18, v30, v20
	v_add_f32_e32 v19, v31, v21
	v_add_f32_e32 v20, v32, v24
	v_add_f32_e32 v21, v33, v25
	v_add_f32_e32 v14, v12, v14
	v_add_f32_e32 v15, v13, v15
	v_permlane16_swap_b32_e32 v16, v20
	v_permlane16_swap_b32_e32 v17, v21
	v_permlane16_swap_b32_e32 v18, v14
	v_permlane16_swap_b32_e32 v19, v15
	v_pk_add_f32 v[12:13], v[16:17], v[20:21]
	v_pk_add_f32 v[14:15], v[18:19], v[14:15]
	s_nop 0
	v_mov_b32_dpp v18, v12 row_ror:8 row_mask:0xf bank_mask:0xf bound_ctrl:1
	v_mov_b32_dpp v19, v13 row_ror:8 row_mask:0xf bank_mask:0xf bound_ctrl:1
	v_mov_b32_dpp v16, v14 row_ror:8 row_mask:0xf bank_mask:0xf bound_ctrl:1
	v_mov_b32_dpp v17, v15 row_ror:8 row_mask:0xf bank_mask:0xf bound_ctrl:1
	s_and_saveexec_b64 s[6:7], s[0:1]
	s_cbranch_execz .LBB0_191
	v_pk_add_f32 v[12:13], v[12:13], v[18:19]
	v_lshlrev_b32_e32 v18, 16, v160
	v_and_b32_e32 v19, 0xffff0000, v160
	v_pk_add_f32 v[14:15], v[14:15], v[16:17]
	v_lshlrev_b32_e32 v16, 16, v161
	v_and_b32_e32 v17, 0xffff0000, v161
	v_pk_fma_f32 v[12:13], v[18:19], s[86:87], v[12:13] op_sel_hi:[1,0,1]
	v_pk_fma_f32 v[14:15], v[16:17], s[86:87], v[14:15] op_sel_hi:[1,0,1]
	v_cvt_pk_bf16_f32 v12, v12, v13
	v_cvt_pk_bf16_f32 v13, v14, v15
	global_store_dwordx2 v[188:189], v[12:13], off
; #define PEER_GATHER(TAB, IA, IB, RR) do { _Pragma("unroll") for (int g = 0; g < 16; ++g) { \
;     const unsigned _w = (g < 8 ? IA : IB)[(g >> 1) & 3]; RR[g] = *(const u32x4*)((TAB) + row_off(_w, c16, (g & 1) != 0)); } } while (0)
; DI void phase_peer_v(const Params& p, int layer, int wave) {
;     ...
;     wA = wAb; wB = wBb; hR = hRb;
;     PEER_META_V(t + 3 * nslot, iAb, iBb, wAb, wBb, hRb);
;     PEER_GATHER(vb, iAa, iBa, rrA);
.LBB0_191:
	s_or_b64 exec, exec, s[6:7]
	s_add_i32 s6, s41, s8
	s_cmp_lt_i32 s6, 0x10200
	s_cselect_b32 s6, s6, s38
	s_ashr_i32 s7, s6, 31
	s_lshl_b64 s[12:13], s[6:7], 8
	v_lshl_add_u64 v[12:13], v[224:225], 0, s[12:13]
	global_load_dword v234, v[12:13], off
	v_lshl_add_u64 v[12:13], v[226:227], 0, s[12:13]
	s_lshl_b64 s[6:7], s[6:7], 11
	global_load_dword v235, v[12:13], off
	v_lshl_add_u64 v[12:13], v[182:183], 0, s[6:7]
	global_load_dwordx2 v[192:193], v[12:13], off
	s_waitcnt lgkmcnt(0)
	v_mad_u32_u16 v206, v156, v195, v205
	v_mad_u32_u16 v207, v156, v195, v205 op_sel:[1,0,0,0]
	v_mad_u32_u16 v208, v157, v195, v205
	v_mad_u32_u16 v209, v157, v195, v205 op_sel:[1,0,0,0]
	v_mad_u32_u16 v210, v158, v195, v205
	v_mad_u32_u16 v211, v158, v195, v205 op_sel:[1,0,0,0]
	v_mad_u32_u16 v212, v159, v195, v205
	v_mad_u32_u16 v213, v159, v195, v205 op_sel:[1,0,0,0]
	v_mad_u32_u16 v214, v152, v195, v205
	v_mad_u32_u16 v215, v152, v195, v205 op_sel:[1,0,0,0]
	v_mad_u32_u16 v216, v153, v195, v205
	v_mad_u32_u16 v217, v153, v195, v205 op_sel:[1,0,0,0]
	v_mad_u32_u16 v218, v154, v195, v205
	v_mad_u32_u16 v219, v154, v195, v205 op_sel:[1,0,0,0]
	v_mad_u32_u16 v220, v155, v195, v205
	v_mad_u32_u16 v221, v155, v195, v205 op_sel:[1,0,0,0]
	s_add_i32 s6, s53, s8
	s_cmp_gt_i32 s6, 0x101ff
	s_cbranch_scc1 .LBB0_188
	global_load_dwordx4 v[120:123], v206, s[80:81]
	s_waitcnt vmcnt(20)
	v_cvt_pk_f32_fp8_e32 v[154:155], v148
	v_cvt_pk_f32_fp8_sdwa v[156:157], v148 src0_sel:WORD_1
	v_cvt_pk_f32_fp8_e32 v[158:159], v149
	v_cvt_pk_f32_fp8_sdwa v[148:149], v149 src0_sel:WORD_1
	v_cvt_pk_f32_fp8_e32 v[168:169], v150
	v_cvt_pk_f32_fp8_sdwa v[170:171], v150 src0_sel:WORD_1
	v_cvt_pk_f32_fp8_e32 v[172:173], v151
	v_cvt_pk_f32_fp8_sdwa v[150:151], v151 src0_sel:WORD_1
	v_lshlrev_b32_e32 v152, 16, v72
	v_pk_fma_f32 v[154:155], v[152:153], v[154:155], 0 op_sel_hi:[0,1,0]
	v_pk_fma_f32 v[156:157], v[152:153], v[156:157], 0 op_sel_hi:[0,1,0]
	v_pk_fma_f32 v[158:159], v[152:153], v[158:159], 0 op_sel_hi:[0,1,0]
	v_pk_fma_f32 v[148:149], v[152:153], v[148:149], 0 op_sel_hi:[0,1,0]
	v_pk_fma_f32 v[168:169], v[152:153], v[168:169], 0 op_sel_hi:[0,1,0]
	v_pk_fma_f32 v[170:171], v[152:153], v[170:171], 0 op_sel_hi:[0,1,0]
	v_pk_fma_f32 v[172:173], v[152:153], v[172:173], 0 op_sel_hi:[0,1,0]
	v_pk_fma_f32 v[150:151], v[152:153], v[150:151], 0 op_sel_hi:[0,1,0]
	global_load_dwordx4 v[112:115], v207, s[80:81]
	s_waitcnt vmcnt(20)
	v_cvt_pk_f32_fp8_e32 v[152:153], v144
	v_cvt_pk_f32_fp8_sdwa v[174:175], v144 src0_sel:WORD_1
	v_and_b32_e32 v72, 0xffff0000, v72
	v_pk_fma_f32 v[152:153], v[72:73], v[152:153], v[154:155] op_sel_hi:[0,1,1]
	v_pk_fma_f32 v[154:155], v[72:73], v[174:175], v[156:157] op_sel_hi:[0,1,1]
	v_cvt_pk_f32_fp8_e32 v[156:157], v145
	v_cvt_pk_f32_fp8_sdwa v[144:145], v145 src0_sel:WORD_1
	v_pk_fma_f32 v[156:157], v[72:73], v[156:157], v[158:159] op_sel_hi:[0,1,1]
	v_pk_fma_f32 v[144:145], v[72:73], v[144:145], v[148:149] op_sel_hi:[0,1,1]
	v_cvt_pk_f32_fp8_e32 v[148:149], v146
	v_cvt_pk_f32_fp8_sdwa v[158:159], v146 src0_sel:WORD_1
	v_pk_fma_f32 v[148:149], v[72:73], v[148:149], v[168:169] op_sel_hi:[0,1,1]
	v_cvt_pk_f32_fp8_e32 v[168:169], v147
	v_cvt_pk_f32_fp8_sdwa v[146:147], v147 src0_sel:WORD_1
	v_pk_fma_f32 v[158:159], v[72:73], v[158:159], v[170:171] op_sel_hi:[0,1,1]
	global_load_dwordx4 v[104:107], v208, s[80:81]
	s_waitcnt vmcnt(20)
	v_cvt_pk_f32_fp8_sdwa v[170:171], v136 src0_sel:WORD_1
	v_pk_fma_f32 v[168:169], v[72:73], v[168:169], v[172:173] op_sel_hi:[0,1,1]
	v_pk_fma_f32 v[146:147], v[72:73], v[146:147], v[150:151] op_sel_hi:[0,1,1]
	v_cvt_pk_f32_fp8_e32 v[150:151], v136
	v_lshlrev_b32_e32 v72, 16, v73
	v_pk_fma_f32 v[150:151], v[72:73], v[150:151], v[152:153] op_sel_hi:[0,1,1]
	v_pk_fma_f32 v[152:153], v[72:73], v[170:171], v[154:155] op_sel_hi:[0,1,1]
	v_cvt_pk_f32_fp8_e32 v[154:155], v137
	v_cvt_pk_f32_fp8_sdwa v[136:137], v137 src0_sel:WORD_1
	v_pk_fma_f32 v[154:155], v[72:73], v[154:155], v[156:157] op_sel_hi:[0,1,1]
	v_pk_fma_f32 v[136:137], v[72:73], v[136:137], v[144:145] op_sel_hi:[0,1,1]
	v_cvt_pk_f32_fp8_e32 v[144:145], v138
	v_cvt_pk_f32_fp8_sdwa v[156:157], v138 src0_sel:WORD_1
	v_pk_fma_f32 v[144:145], v[72:73], v[144:145], v[148:149] op_sel_hi:[0,1,1]
	v_pk_fma_f32 v[148:149], v[72:73], v[156:157], v[158:159] op_sel_hi:[0,1,1]
	v_cvt_pk_f32_fp8_e32 v[156:157], v139
	v_cvt_pk_f32_fp8_sdwa v[138:139], v139 src0_sel:WORD_1
	global_load_dwordx4 v[96:99], v209, s[80:81]
	s_waitcnt vmcnt(20)
	v_cvt_pk_f32_fp8_sdwa v[158:159], v132 src0_sel:WORD_1
	v_pk_fma_f32 v[156:157], v[72:73], v[156:157], v[168:169] op_sel_hi:[0,1,1]
	v_pk_fma_f32 v[138:139], v[72:73], v[138:139], v[146:147] op_sel_hi:[0,1,1]
	v_cvt_pk_f32_fp8_e32 v[146:147], v132
	v_and_b32_e32 v72, 0xffff0000, v73
	v_pk_fma_f32 v[146:147], v[72:73], v[146:147], v[150:151] op_sel_hi:[0,1,1]
	v_pk_fma_f32 v[150:151], v[72:73], v[158:159], v[152:153] op_sel_hi:[0,1,1]
	v_cvt_pk_f32_fp8_e32 v[152:153], v133
	v_cvt_pk_f32_fp8_sdwa v[132:133], v133 src0_sel:WORD_1
	v_pk_fma_f32 v[152:153], v[72:73], v[152:153], v[154:155] op_sel_hi:[0,1,1]
	v_pk_fma_f32 v[132:133], v[72:73], v[132:133], v[136:137] op_sel_hi:[0,1,1]
	v_cvt_pk_f32_fp8_e32 v[136:137], v134
	v_cvt_pk_f32_fp8_sdwa v[154:155], v134 src0_sel:WORD_1
	v_pk_fma_f32 v[136:137], v[72:73], v[136:137], v[144:145] op_sel_hi:[0,1,1]
	v_pk_fma_f32 v[144:145], v[72:73], v[154:155], v[148:149] op_sel_hi:[0,1,1]
	v_cvt_pk_f32_fp8_e32 v[148:149], v135
	v_cvt_pk_f32_fp8_sdwa v[134:135], v135 src0_sel:WORD_1
	global_load_dwordx4 v[88:91], v210, s[80:81]
	s_waitcnt vmcnt(20)
	v_cvt_pk_f32_fp8_sdwa v[154:155], v124 src0_sel:WORD_1
	v_pk_fma_f32 v[148:149], v[72:73], v[148:149], v[156:157] op_sel_hi:[0,1,1]
	v_pk_fma_f32 v[72:73], v[72:73], v[134:135], v[138:139] op_sel_hi:[0,1,1]
	v_cvt_pk_f32_fp8_e32 v[138:139], v124
	v_lshlrev_b32_e32 v134, 16, v74
	v_and_b32_e32 v74, 0xffff0000, v74
	v_pk_fma_f32 v[138:139], v[134:135], v[138:139], v[146:147] op_sel_hi:[0,1,1]
	v_pk_fma_f32 v[146:147], v[134:135], v[154:155], v[150:151] op_sel_hi:[0,1,1]
	v_cvt_pk_f32_fp8_e32 v[150:151], v125
	v_cvt_pk_f32_fp8_sdwa v[124:125], v125 src0_sel:WORD_1
	v_pk_fma_f32 v[150:151], v[134:135], v[150:151], v[152:153] op_sel_hi:[0,1,1]
	v_pk_fma_f32 v[124:125], v[134:135], v[124:125], v[132:133] op_sel_hi:[0,1,1]
	v_cvt_pk_f32_fp8_e32 v[132:133], v126
	v_cvt_pk_f32_fp8_sdwa v[152:153], v126 src0_sel:WORD_1
	v_pk_fma_f32 v[132:133], v[134:135], v[132:133], v[136:137] op_sel_hi:[0,1,1]
	v_pk_fma_f32 v[136:137], v[134:135], v[152:153], v[144:145] op_sel_hi:[0,1,1]
	v_cvt_pk_f32_fp8_e32 v[144:145], v127
	v_cvt_pk_f32_fp8_sdwa v[126:127], v127 src0_sel:WORD_1
	v_pk_fma_f32 v[144:145], v[134:135], v[144:145], v[148:149] op_sel_hi:[0,1,1]
	v_pk_fma_f32 v[72:73], v[134:135], v[126:127], v[72:73] op_sel_hi:[0,1,1]
	global_load_dwordx4 v[80:83], v211, s[80:81]
	s_waitcnt vmcnt(20)
	v_cvt_pk_f32_fp8_e32 v[126:127], v116
	v_cvt_pk_f32_fp8_sdwa v[134:135], v116 src0_sel:WORD_1
	v_pk_fma_f32 v[126:127], v[74:75], v[126:127], v[138:139] op_sel_hi:[0,1,1]
	v_cvt_pk_f32_fp8_e32 v[138:139], v117
	v_cvt_pk_f32_fp8_sdwa v[116:117], v117 src0_sel:WORD_1
	v_pk_fma_f32 v[134:135], v[74:75], v[134:135], v[146:147] op_sel_hi:[0,1,1]
	v_cvt_pk_f32_fp8_sdwa v[146:147], v118 src0_sel:WORD_1
	v_pk_fma_f32 v[138:139], v[74:75], v[138:139], v[150:151] op_sel_hi:[0,1,1]
	v_pk_fma_f32 v[116:117], v[74:75], v[116:117], v[124:125] op_sel_hi:[0,1,1]
	v_cvt_pk_f32_fp8_e32 v[124:125], v118
	v_pk_fma_f32 v[124:125], v[74:75], v[124:125], v[132:133] op_sel_hi:[0,1,1]
	v_pk_fma_f32 v[132:133], v[74:75], v[146:147], v[136:137] op_sel_hi:[0,1,1]
	v_cvt_pk_f32_fp8_e32 v[136:137], v119
	v_cvt_pk_f32_fp8_sdwa v[118:119], v119 src0_sel:WORD_1
	v_pk_fma_f32 v[136:137], v[74:75], v[136:137], v[144:145] op_sel_hi:[0,1,1]
	v_pk_fma_f32 v[72:73], v[74:75], v[118:119], v[72:73] op_sel_hi:[0,1,1]
	global_load_dwordx4 v[68:71], v212, s[80:81]
	s_waitcnt vmcnt(20)
	v_cvt_pk_f32_fp8_e32 v[118:119], v108
	v_cvt_pk_f32_fp8_sdwa v[144:145], v108 src0_sel:WORD_1
	v_lshlrev_b32_e32 v74, 16, v75
	v_pk_fma_f32 v[118:119], v[74:75], v[118:119], v[126:127] op_sel_hi:[0,1,1]
	v_pk_fma_f32 v[126:127], v[74:75], v[144:145], v[134:135] op_sel_hi:[0,1,1]
	v_cvt_pk_f32_fp8_e32 v[134:135], v109
	v_cvt_pk_f32_fp8_sdwa v[108:109], v109 src0_sel:WORD_1
	v_pk_fma_f32 v[134:135], v[74:75], v[134:135], v[138:139] op_sel_hi:[0,1,1]
	v_pk_fma_f32 v[108:109], v[74:75], v[108:109], v[116:117] op_sel_hi:[0,1,1]
	v_cvt_pk_f32_fp8_e32 v[116:117], v110
	v_cvt_pk_f32_fp8_sdwa v[138:139], v110 src0_sel:WORD_1
	v_pk_fma_f32 v[116:117], v[74:75], v[116:117], v[124:125] op_sel_hi:[0,1,1]
	v_pk_fma_f32 v[124:125], v[74:75], v[138:139], v[132:133] op_sel_hi:[0,1,1]
	v_cvt_pk_f32_fp8_e32 v[132:133], v111
	v_cvt_pk_f32_fp8_sdwa v[110:111], v111 src0_sel:WORD_1
	v_pk_fma_f32 v[132:133], v[74:75], v[132:133], v[136:137] op_sel_hi:[0,1,1]
	v_pk_fma_f32 v[72:73], v[74:75], v[110:111], v[72:73] op_sel_hi:[0,1,1]
	global_load_dwordx4 v[60:63], v213, s[80:81]
	s_waitcnt vmcnt(20)
	v_cvt_pk_f32_fp8_e32 v[110:111], v100
	v_cvt_pk_f32_fp8_sdwa v[136:137], v100 src0_sel:WORD_1
	v_and_b32_e32 v74, 0xffff0000, v75
	v_pk_fma_f32 v[110:111], v[74:75], v[110:111], v[118:119] op_sel_hi:[0,1,1]
	v_pk_fma_f32 v[118:119], v[74:75], v[136:137], v[126:127] op_sel_hi:[0,1,1]
	v_cvt_pk_f32_fp8_e32 v[126:127], v101
	v_cvt_pk_f32_fp8_sdwa v[100:101], v101 src0_sel:WORD_1
	v_pk_fma_f32 v[126:127], v[74:75], v[126:127], v[134:135] op_sel_hi:[0,1,1]
	v_pk_fma_f32 v[100:101], v[74:75], v[100:101], v[108:109] op_sel_hi:[0,1,1]
	v_cvt_pk_f32_fp8_e32 v[108:109], v102
	v_cvt_pk_f32_fp8_sdwa v[134:135], v102 src0_sel:WORD_1
	v_pk_fma_f32 v[108:109], v[74:75], v[108:109], v[116:117] op_sel_hi:[0,1,1]
	v_pk_fma_f32 v[116:117], v[74:75], v[134:135], v[124:125] op_sel_hi:[0,1,1]
	v_cvt_pk_f32_fp8_e32 v[124:125], v103
	v_cvt_pk_f32_fp8_sdwa v[102:103], v103 src0_sel:WORD_1
	v_pk_fma_f32 v[124:125], v[74:75], v[124:125], v[132:133] op_sel_hi:[0,1,1]
	v_pk_fma_f32 v[72:73], v[74:75], v[102:103], v[72:73] op_sel_hi:[0,1,1]
	global_load_dwordx4 v[52:55], v214, s[80:81]
	s_waitcnt vmcnt(20)
	v_cvt_pk_f32_fp8_e32 v[102:103], v92
	v_cvt_pk_f32_fp8_sdwa v[132:133], v92 src0_sel:WORD_1
	v_lshlrev_b32_e32 v74, 16, v8
	v_and_b32_e32 v8, 0xffff0000, v8
	v_pk_fma_f32 v[102:103], v[74:75], v[102:103], v[110:111] op_sel_hi:[0,1,1]
	v_pk_fma_f32 v[110:111], v[74:75], v[132:133], v[118:119] op_sel_hi:[0,1,1]
	v_cvt_pk_f32_fp8_e32 v[118:119], v93
	v_cvt_pk_f32_fp8_sdwa v[92:93], v93 src0_sel:WORD_1
	v_pk_fma_f32 v[118:119], v[74:75], v[118:119], v[126:127] op_sel_hi:[0,1,1]
	v_pk_fma_f32 v[92:93], v[74:75], v[92:93], v[100:101] op_sel_hi:[0,1,1]
	v_cvt_pk_f32_fp8_e32 v[100:101], v94
	v_cvt_pk_f32_fp8_sdwa v[126:127], v94 src0_sel:WORD_1
	v_pk_fma_f32 v[100:101], v[74:75], v[100:101], v[108:109] op_sel_hi:[0,1,1]
	v_pk_fma_f32 v[108:109], v[74:75], v[126:127], v[116:117] op_sel_hi:[0,1,1]
	v_cvt_pk_f32_fp8_e32 v[116:117], v95
	v_cvt_pk_f32_fp8_sdwa v[94:95], v95 src0_sel:WORD_1
	v_pk_fma_f32 v[116:117], v[74:75], v[116:117], v[124:125] op_sel_hi:[0,1,1]
	v_pk_fma_f32 v[72:73], v[74:75], v[94:95], v[72:73] op_sel_hi:[0,1,1]
	global_load_dwordx4 v[40:43], v215, s[80:81]
	s_waitcnt vmcnt(20)
	v_cvt_pk_f32_fp8_e32 v[74:75], v84
	v_cvt_pk_f32_fp8_sdwa v[94:95], v84 src0_sel:WORD_1
	v_pk_fma_f32 v[74:75], v[8:9], v[74:75], v[102:103] op_sel_hi:[0,1,1]
	v_cvt_pk_f32_fp8_e32 v[102:103], v85
	v_cvt_pk_f32_fp8_sdwa v[84:85], v85 src0_sel:WORD_1
	v_pk_fma_f32 v[94:95], v[8:9], v[94:95], v[110:111] op_sel_hi:[0,1,1]
	v_cvt_pk_f32_fp8_sdwa v[110:111], v86 src0_sel:WORD_1
	v_pk_fma_f32 v[102:103], v[8:9], v[102:103], v[118:119] op_sel_hi:[0,1,1]
	v_pk_fma_f32 v[84:85], v[8:9], v[84:85], v[92:93] op_sel_hi:[0,1,1]
	v_cvt_pk_f32_fp8_e32 v[92:93], v86
	v_pk_fma_f32 v[92:93], v[8:9], v[92:93], v[100:101] op_sel_hi:[0,1,1]
	v_pk_fma_f32 v[100:101], v[8:9], v[110:111], v[108:109] op_sel_hi:[0,1,1]
	v_cvt_pk_f32_fp8_e32 v[108:109], v87
	v_cvt_pk_f32_fp8_sdwa v[86:87], v87 src0_sel:WORD_1
	global_load_dwordx4 v[32:35], v216, s[80:81]
	s_waitcnt vmcnt(20)
	v_cvt_pk_f32_fp8_sdwa v[110:111], v76 src0_sel:WORD_1
	v_pk_fma_f32 v[108:109], v[8:9], v[108:109], v[116:117] op_sel_hi:[0,1,1]
	v_pk_fma_f32 v[72:73], v[8:9], v[86:87], v[72:73] op_sel_hi:[0,1,1]
	v_cvt_pk_f32_fp8_e32 v[86:87], v76
	v_lshlrev_b32_e32 v8, 16, v9
	v_pk_fma_f32 v[74:75], v[8:9], v[86:87], v[74:75] op_sel_hi:[0,1,1]
	v_pk_fma_f32 v[86:87], v[8:9], v[110:111], v[94:95] op_sel_hi:[0,1,1]
	v_cvt_pk_f32_fp8_e32 v[94:95], v77
	v_cvt_pk_f32_fp8_sdwa v[76:77], v77 src0_sel:WORD_1
	v_pk_fma_f32 v[94:95], v[8:9], v[94:95], v[102:103] op_sel_hi:[0,1,1]
	v_pk_fma_f32 v[76:77], v[8:9], v[76:77], v[84:85] op_sel_hi:[0,1,1]
	v_cvt_pk_f32_fp8_e32 v[84:85], v78
	v_cvt_pk_f32_fp8_sdwa v[102:103], v78 src0_sel:WORD_1
	v_pk_fma_f32 v[84:85], v[8:9], v[84:85], v[92:93] op_sel_hi:[0,1,1]
	v_pk_fma_f32 v[92:93], v[8:9], v[102:103], v[100:101] op_sel_hi:[0,1,1]
	v_cvt_pk_f32_fp8_e32 v[100:101], v79
	v_cvt_pk_f32_fp8_sdwa v[78:79], v79 src0_sel:WORD_1
	global_load_dwordx4 v[28:31], v217, s[80:81]
	s_waitcnt vmcnt(20)
	v_cvt_pk_f32_fp8_sdwa v[102:103], v64 src0_sel:WORD_1
	v_pk_fma_f32 v[100:101], v[8:9], v[100:101], v[108:109] op_sel_hi:[0,1,1]
	v_pk_fma_f32 v[72:73], v[8:9], v[78:79], v[72:73] op_sel_hi:[0,1,1]
	v_cvt_pk_f32_fp8_e32 v[78:79], v64
	v_and_b32_e32 v8, 0xffff0000, v9
	v_pk_fma_f32 v[74:75], v[8:9], v[78:79], v[74:75] op_sel_hi:[0,1,1]
	v_pk_fma_f32 v[78:79], v[8:9], v[102:103], v[86:87] op_sel_hi:[0,1,1]
	v_cvt_pk_f32_fp8_e32 v[86:87], v65
	v_cvt_pk_f32_fp8_sdwa v[64:65], v65 src0_sel:WORD_1
	v_pk_fma_f32 v[86:87], v[8:9], v[86:87], v[94:95] op_sel_hi:[0,1,1]
	v_pk_fma_f32 v[64:65], v[8:9], v[64:65], v[76:77] op_sel_hi:[0,1,1]
	v_cvt_pk_f32_fp8_e32 v[76:77], v66
	v_cvt_pk_f32_fp8_sdwa v[94:95], v66 src0_sel:WORD_1
	v_pk_fma_f32 v[76:77], v[8:9], v[76:77], v[84:85] op_sel_hi:[0,1,1]
	v_pk_fma_f32 v[84:85], v[8:9], v[94:95], v[92:93] op_sel_hi:[0,1,1]
	v_cvt_pk_f32_fp8_e32 v[92:93], v67
	v_cvt_pk_f32_fp8_sdwa v[66:67], v67 src0_sel:WORD_1
	global_load_dwordx4 v[24:27], v218, s[80:81]
	s_waitcnt vmcnt(20)
	v_cvt_pk_f32_fp8_sdwa v[94:95], v56 src0_sel:WORD_1
	v_pk_fma_f32 v[92:93], v[8:9], v[92:93], v[100:101] op_sel_hi:[0,1,1]
	v_pk_fma_f32 v[8:9], v[8:9], v[66:67], v[72:73] op_sel_hi:[0,1,1]
	v_cvt_pk_f32_fp8_e32 v[72:73], v56
	v_lshlrev_b32_e32 v66, 16, v10
	v_and_b32_e32 v10, 0xffff0000, v10
	v_pk_fma_f32 v[72:73], v[66:67], v[72:73], v[74:75] op_sel_hi:[0,1,1]
	v_pk_fma_f32 v[74:75], v[66:67], v[94:95], v[78:79] op_sel_hi:[0,1,1]
	v_cvt_pk_f32_fp8_e32 v[78:79], v57
	v_cvt_pk_f32_fp8_sdwa v[56:57], v57 src0_sel:WORD_1
	v_pk_fma_f32 v[78:79], v[66:67], v[78:79], v[86:87] op_sel_hi:[0,1,1]
	v_pk_fma_f32 v[56:57], v[66:67], v[56:57], v[64:65] op_sel_hi:[0,1,1]
	v_cvt_pk_f32_fp8_e32 v[64:65], v58
	v_cvt_pk_f32_fp8_sdwa v[86:87], v58 src0_sel:WORD_1
	v_pk_fma_f32 v[64:65], v[66:67], v[64:65], v[76:77] op_sel_hi:[0,1,1]
	v_pk_fma_f32 v[76:77], v[66:67], v[86:87], v[84:85] op_sel_hi:[0,1,1]
	v_cvt_pk_f32_fp8_e32 v[84:85], v59
	v_cvt_pk_f32_fp8_sdwa v[58:59], v59 src0_sel:WORD_1
	v_pk_fma_f32 v[84:85], v[66:67], v[84:85], v[92:93] op_sel_hi:[0,1,1]
	v_pk_fma_f32 v[8:9], v[66:67], v[58:59], v[8:9] op_sel_hi:[0,1,1]
	global_load_dwordx4 v[20:23], v219, s[80:81]
	s_waitcnt vmcnt(20)
	v_cvt_pk_f32_fp8_e32 v[58:59], v48
	v_cvt_pk_f32_fp8_sdwa v[66:67], v48 src0_sel:WORD_1
	v_pk_fma_f32 v[58:59], v[10:11], v[58:59], v[72:73] op_sel_hi:[0,1,1]
	v_cvt_pk_f32_fp8_e32 v[72:73], v49
	v_cvt_pk_f32_fp8_sdwa v[48:49], v49 src0_sel:WORD_1
	v_pk_fma_f32 v[66:67], v[10:11], v[66:67], v[74:75] op_sel_hi:[0,1,1]
	v_cvt_pk_f32_fp8_sdwa v[74:75], v50 src0_sel:WORD_1
	v_pk_fma_f32 v[72:73], v[10:11], v[72:73], v[78:79] op_sel_hi:[0,1,1]
	v_pk_fma_f32 v[48:49], v[10:11], v[48:49], v[56:57] op_sel_hi:[0,1,1]
	v_cvt_pk_f32_fp8_e32 v[56:57], v50
	v_pk_fma_f32 v[56:57], v[10:11], v[56:57], v[64:65] op_sel_hi:[0,1,1]
	v_pk_fma_f32 v[64:65], v[10:11], v[74:75], v[76:77] op_sel_hi:[0,1,1]
	v_cvt_pk_f32_fp8_e32 v[74:75], v51
	v_cvt_pk_f32_fp8_sdwa v[50:51], v51 src0_sel:WORD_1
	global_load_dwordx4 v[12:15], v220, s[80:81]
	s_waitcnt vmcnt(20)
	v_cvt_pk_f32_fp8_sdwa v[76:77], v44 src0_sel:WORD_1
	v_pk_fma_f32 v[74:75], v[10:11], v[74:75], v[84:85] op_sel_hi:[0,1,1]
	v_pk_fma_f32 v[8:9], v[10:11], v[50:51], v[8:9] op_sel_hi:[0,1,1]
	v_cvt_pk_f32_fp8_e32 v[50:51], v44
	v_lshlrev_b32_e32 v10, 16, v11
	v_pk_fma_f32 v[50:51], v[10:11], v[50:51], v[58:59] op_sel_hi:[0,1,1]
	v_pk_fma_f32 v[58:59], v[10:11], v[76:77], v[66:67] op_sel_hi:[0,1,1]
	v_cvt_pk_f32_fp8_e32 v[66:67], v45
	v_cvt_pk_f32_fp8_sdwa v[44:45], v45 src0_sel:WORD_1
	v_pk_fma_f32 v[66:67], v[10:11], v[66:67], v[72:73] op_sel_hi:[0,1,1]
	v_pk_fma_f32 v[44:45], v[10:11], v[44:45], v[48:49] op_sel_hi:[0,1,1]
	v_cvt_pk_f32_fp8_e32 v[48:49], v46
	v_cvt_pk_f32_fp8_sdwa v[72:73], v46 src0_sel:WORD_1
	v_pk_fma_f32 v[48:49], v[10:11], v[48:49], v[56:57] op_sel_hi:[0,1,1]
	v_pk_fma_f32 v[56:57], v[10:11], v[72:73], v[64:65] op_sel_hi:[0,1,1]
	v_cvt_pk_f32_fp8_e32 v[64:65], v47
	v_cvt_pk_f32_fp8_sdwa v[46:47], v47 src0_sel:WORD_1
	global_load_dwordx4 v[16:19], v221, s[80:81]
	s_waitcnt vmcnt(18)
	ds_bpermute_b32 v140, v230, v234
	ds_bpermute_b32 v141, v230, v234 offset:4
	ds_bpermute_b32 v142, v230, v234 offset:8
	ds_bpermute_b32 v143, v230, v234 offset:12
	ds_bpermute_b32 v128, v230, v234 offset:16
	ds_bpermute_b32 v129, v230, v234 offset:20
	ds_bpermute_b32 v130, v230, v234 offset:24
	ds_bpermute_b32 v131, v230, v234 offset:28
	s_waitcnt vmcnt(17)
	ds_bpermute_b32 v164, v230, v235
	ds_bpermute_b32 v165, v230, v235 offset:4
	ds_bpermute_b32 v166, v230, v235 offset:8
	ds_bpermute_b32 v167, v230, v235 offset:12
	ds_bpermute_b32 v160, v230, v235 offset:16
	ds_bpermute_b32 v161, v230, v235 offset:20
	ds_bpermute_b32 v162, v230, v235 offset:24
	ds_bpermute_b32 v163, v230, v235 offset:28
	v_cvt_pk_f32_fp8_sdwa v[72:73], v36 src0_sel:WORD_1
	v_pk_fma_f32 v[64:65], v[10:11], v[64:65], v[74:75] op_sel_hi:[0,1,1]
	v_pk_fma_f32 v[8:9], v[10:11], v[46:47], v[8:9] op_sel_hi:[0,1,1]
	v_cvt_pk_f32_fp8_e32 v[46:47], v36
	v_and_b32_e32 v10, 0xffff0000, v11
	v_pk_fma_f32 v[46:47], v[10:11], v[46:47], v[50:51] op_sel_hi:[0,1,1]
	v_pk_fma_f32 v[50:51], v[10:11], v[72:73], v[58:59] op_sel_hi:[0,1,1]
	v_cvt_pk_f32_fp8_e32 v[58:59], v37
	v_cvt_pk_f32_fp8_sdwa v[36:37], v37 src0_sel:WORD_1
	v_pk_fma_f32 v[58:59], v[10:11], v[58:59], v[66:67] op_sel_hi:[0,1,1]
	v_pk_fma_f32 v[36:37], v[10:11], v[36:37], v[44:45] op_sel_hi:[0,1,1]
	v_cvt_pk_f32_fp8_e32 v[44:45], v38
	v_cvt_pk_f32_fp8_sdwa v[66:67], v38 src0_sel:WORD_1
	v_pk_fma_f32 v[44:45], v[10:11], v[44:45], v[48:49] op_sel_hi:[0,1,1]
	v_pk_fma_f32 v[48:49], v[10:11], v[66:67], v[56:57] op_sel_hi:[0,1,1]
	v_cvt_pk_f32_fp8_e32 v[56:57], v39
	v_cvt_pk_f32_fp8_sdwa v[38:39], v39 src0_sel:WORD_1
	v_permlane32_swap_b32_e32 v46, v44
	v_pk_fma_f32 v[56:57], v[10:11], v[56:57], v[64:65] op_sel_hi:[0,1,1]
	v_pk_fma_f32 v[8:9], v[10:11], v[38:39], v[8:9] op_sel_hi:[0,1,1]
	v_permlane32_swap_b32_e32 v47, v45
	v_permlane32_swap_b32_e32 v50, v48
	v_permlane32_swap_b32_e32 v51, v49
	v_permlane32_swap_b32_e32 v58, v56
	v_permlane32_swap_b32_e32 v59, v57
	v_permlane32_swap_b32_e32 v36, v8
	v_permlane32_swap_b32_e32 v37, v9
	v_add_f32_e32 v10, v46, v44
	v_add_f32_e32 v11, v47, v45
	v_add_f32_e32 v38, v50, v48
	v_add_f32_e32 v39, v51, v49
	v_add_f32_e32 v44, v58, v56
	v_add_f32_e32 v45, v59, v57
	v_add_f32_e32 v36, v36, v8
	v_add_f32_e32 v37, v37, v9
	v_permlane16_swap_b32_e32 v10, v44
	v_permlane16_swap_b32_e32 v11, v45
	v_permlane16_swap_b32_e32 v38, v36
	v_permlane16_swap_b32_e32 v39, v37
	v_pk_add_f32 v[8:9], v[10:11], v[44:45]
	v_pk_add_f32 v[10:11], v[38:39], v[36:37]
	s_nop 0
	v_mov_b32_dpp v38, v8 row_ror:8 row_mask:0xf bank_mask:0xf bound_ctrl:1
	v_mov_b32_dpp v39, v9 row_ror:8 row_mask:0xf bank_mask:0xf bound_ctrl:1
	v_mov_b32_dpp v36, v10 row_ror:8 row_mask:0xf bank_mask:0xf bound_ctrl:1
	v_mov_b32_dpp v37, v11 row_ror:8 row_mask:0xf bank_mask:0xf bound_ctrl:1
	s_and_saveexec_b64 s[8:9], s[0:1]
	s_cbranch_execz .LBB0_187
	v_pk_add_f32 v[8:9], v[8:9], v[38:39]
	v_lshlrev_b32_e32 v38, 16, v186
	v_and_b32_e32 v39, 0xffff0000, v186
	v_pk_add_f32 v[10:11], v[10:11], v[36:37]
	v_lshlrev_b32_e32 v36, 16, v187
	v_and_b32_e32 v37, 0xffff0000, v187
	s_ashr_i32 s7, s6, 31
	v_pk_fma_f32 v[8:9], v[38:39], s[86:87], v[8:9] op_sel_hi:[1,0,1]
	v_pk_fma_f32 v[10:11], v[36:37], s[86:87], v[10:11] op_sel_hi:[1,0,1]
	s_lshl_b64 s[6:7], s[6:7], 11
	v_cvt_pk_bf16_f32 v8, v8, v9
	v_cvt_pk_bf16_f32 v9, v10, v11
	v_lshl_add_u64 v[10:11], v[184:185], 0, s[6:7]
	global_store_dwordx2 v[10:11], v[8:9], off
	s_branch .LBB0_187

; DI void ce_desc(float& hi, float& lo) { const float a = hi, b = lo; hi = fmaxf(a, b); lo = fminf(a, b); }
; DI void bitonic_merge16(float (&v)[16]) {
; #pragma unroll
;   for (int j = 8; j > 0; j >>= 1)
; #pragma unroll
;     for (int i = 0; i < 16; ++i) if ((i & j) == 0) ce_desc(v[i], v[i | j]);
; }
; DI void merge_top16(float (&v)[16], const float (&w)[16]) {
; #pragma unroll
;   for (int i = 0; i < 16; ++i) v[i] = fmaxf(v[i], w[15 - i]);
;   bitonic_merge16(v);
; }
.LBB0_219:
	v_max_f32_e32 v140, v140, v170
	v_max_f32_e32 v141, v141, v169
	v_max_f32_e32 v142, v142, v168
	v_max_f32_e32 v143, v143, v167
	v_max_f32_e32 v136, v136, v166
	v_max_f32_e32 v137, v137, v159
	v_max_f32_e32 v138, v138, v158
	v_max_f32_e32 v139, v139, v157
	v_max_f32_e32 v132, v132, v156
	v_max_f32_e32 v133, v133, v155
	v_max_f32_e32 v134, v134, v154
	v_max_f32_e32 v135, v135, v153
	v_max_f32_e32 v128, v128, v152
	v_max_f32_e32 v129, v129, v151
	v_max_f32_e32 v130, v130, v150
	v_max_f32_e32 v131, v131, v149
	v_max_f32_e32 v149, v140, v132
	v_min_f32_e32 v132, v140, v132
	v_max_f32_e32 v140, v141, v133
	v_min_f32_e32 v133, v141, v133
	v_max_f32_e32 v141, v142, v134
	v_min_f32_e32 v134, v142, v134
	v_max_f32_e32 v142, v143, v135
	v_min_f32_e32 v135, v143, v135
	v_max_f32_e32 v143, v136, v128
	v_min_f32_e32 v128, v136, v128
	v_max_f32_e32 v136, v137, v129
	v_min_f32_e32 v129, v137, v129
	v_max_f32_e32 v137, v138, v130
	v_min_f32_e32 v130, v138, v130
	v_max_f32_e32 v138, v139, v131
	v_min_f32_e32 v131, v139, v131
	v_max_f32_e32 v139, v149, v143
	v_min_f32_e32 v143, v149, v143
	v_max_f32_e32 v149, v140, v136
	v_min_f32_e32 v136, v140, v136
	v_max_f32_e32 v140, v141, v137
	v_min_f32_e32 v137, v141, v137
	v_max_f32_e32 v141, v142, v138
	v_min_f32_e32 v138, v142, v138
	v_max_f32_e32 v142, v132, v128
	v_min_f32_e32 v128, v132, v128
	v_max_f32_e32 v132, v133, v129
	v_min_f32_e32 v129, v133, v129
	v_max_f32_e32 v133, v134, v130
	v_min_f32_e32 v130, v134, v130
	v_max_f32_e32 v134, v135, v131
	v_min_f32_e32 v131, v135, v131
	v_max_f32_e32 v135, v139, v140
	v_min_f32_e32 v139, v139, v140
	v_max_f32_e32 v150, v149, v141
	v_min_f32_e32 v149, v149, v141
	v_max_f32_e32 v151, v143, v137
	v_min_f32_e32 v152, v143, v137
	v_max_f32_e32 v137, v136, v138
	v_min_f32_e32 v153, v136, v138
	v_max_f32_e32 v154, v142, v133
	v_min_f32_e32 v155, v142, v133
	v_max_f32_e32 v133, v132, v134
	v_min_f32_e32 v156, v132, v134
	v_max_f32_e32 v157, v128, v130
	v_min_f32_e32 v158, v128, v130
	v_max_f32_e32 v130, v129, v131
	v_min_f32_e32 v131, v129, v131
	v_max_f32_e32 v140, v135, v150
	v_min_f32_e32 v141, v135, v150
	v_max_f32_e32 v142, v139, v149
	v_min_f32_e32 v143, v139, v149
	v_max_f32_e32 v136, v151, v137
	v_min_f32_e32 v137, v151, v137
	v_max_f32_e32 v138, v152, v153
	v_min_f32_e32 v139, v152, v153
	v_max_f32_e32 v132, v154, v133
	v_min_f32_e32 v133, v154, v133
	v_max_f32_e32 v134, v155, v156
	v_min_f32_e32 v135, v155, v156
	v_max_f32_e32 v128, v157, v130
	v_min_f32_e32 v129, v157, v130
	v_max_f32_e32 v130, v158, v131
	v_min_f32_e32 v131, v158, v131

; #define LAS __attribute__((address_space(3)))
; DI void ce_desc(float& hi, float& lo) { const float a = hi, b = lo; hi = fmaxf(a, b); lo = fminf(a, b); }
; DI void bitonic_sort16(float (&v)[16]) {
; #pragma unroll
;   for (int k = 2; k <= 16; k <<= 1)
; #pragma unroll
;     for (int j = k >> 1; j > 0; j >>= 1)
; #pragma unroll
;       for (int i = 0; i < 16; ++i) {
;         const int l = i ^ j;
;         if (l > i) { if ((i & k) == 0 || k == 16) ce_desc(v[i], v[l]); else ce_desc(v[l], v[i]); }
;       }
; }
; DI void gemm256_tile(const Params& p, int mode, int layer, const u16* R, const u16* Cc, int brow, int bcol, lchar* shm, int tid_in, int wid) {
;     ...
;       for (int ch = 0; ch < 4; ++ch) {
;         float wk[16];
; #pragma unroll
;         for (int q = 0; q < 4; ++q) {
;           const int key = kh * 64 + ch * 16 + 4 * q;
;           const f32x4 xv = *(const LAS f32x4*)((lchar*)S + tok * 528 + key * 4);
; #pragma unroll
;           for (int e = 0; e < 4; ++e) wk[4 * q + e] = __uint_as_float((__float_as_uint(xv[e]) & ~127u) | (unsigned)(key + e));
;         }
;         bitonic_sort16(wk);
.LBB0_221:
	ds_read_b128 v[150:153], v148
	ds_read_b128 v[154:157], v148 offset:16
	ds_read_b128 v[166:169], v148 offset:32
	ds_read_b128 v[170:173], v148 offset:48
	s_add_i32 s28, s49, s36
	s_add_i32 s29, s28, 4
	s_waitcnt lgkmcnt(1)
	v_and_b32_e32 v159, 0xffffff80, v168
	v_and_b32_e32 v149, 0xffffff80, v150
	v_and_b32_e32 v150, 0xffffff80, v151
	v_or_b32_e32 v149, s28, v149
	v_or3_b32 v150, s28, v150, 1
	v_and_b32_e32 v151, 0xffffff80, v152
	v_and_b32_e32 v152, 0xffffff80, v153
	v_or3_b32 v151, s28, v151, 2
	v_or3_b32 v152, s28, v152, 3
	v_and_b32_e32 v153, 0xffffff80, v154
	v_and_b32_e32 v154, 0xffffff80, v155
	v_or_b32_e32 v153, s29, v153
	v_or3_b32 v154, s28, v154, 5
	v_and_b32_e32 v155, 0xffffff80, v156
	v_and_b32_e32 v156, 0xffffff80, v157
	s_waitcnt lgkmcnt(0)
	v_and_b32_e32 v168, 0xffffff80, v171
	v_max_f32_e32 v171, v149, v150
	v_min_f32_e32 v149, v149, v150
	v_max_f32_e32 v150, v151, v151
	v_max_f32_e32 v151, v152, v152
	v_or3_b32 v155, s28, v155, 6
	v_or3_b32 v156, s28, v156, 7
	s_add_i32 s29, s28, 8
	v_and_b32_e32 v157, 0xffffff80, v166
	v_and_b32_e32 v158, 0xffffff80, v167
	v_max_f32_e32 v152, v151, v150
	v_min_f32_e32 v150, v151, v150
	v_max_f32_e32 v151, v154, v154
	v_or_b32_e32 v157, s29, v157
	v_or3_b32 v158, s28, v158, 9
	v_and_b32_e32 v166, 0xffffff80, v169
	v_max_f32_e32 v154, v153, v151
	v_min_f32_e32 v151, v153, v151
	v_max_f32_e32 v153, v155, v155
	v_max_f32_e32 v155, v156, v156
	v_or3_b32 v159, s28, v159, 10
	v_or3_b32 v166, s28, v166, 11
	s_add_i32 s29, s28, 12
	v_and_b32_e32 v167, 0xffffff80, v170
	v_max_f32_e32 v156, v155, v153
	v_min_f32_e32 v153, v155, v153
	v_max_f32_e32 v155, v158, v158
	v_or_b32_e32 v167, s29, v167
	v_or3_b32 v168, s28, v168, 13
	v_and_b32_e32 v169, 0xffffff80, v172
	v_and_b32_e32 v170, 0xffffff80, v173
	v_max_f32_e32 v158, v157, v155
	v_min_f32_e32 v155, v157, v155
	v_max_f32_e32 v157, v159, v159
	v_max_f32_e32 v159, v166, v166
	v_or3_b32 v169, s28, v169, 14
	v_or3_b32 v170, s28, v170, 15
	v_max_f32_e32 v166, v159, v157
	v_min_f32_e32 v157, v159, v157
	v_max_f32_e32 v159, v168, v168
	v_max_f32_e32 v168, v167, v159
	v_min_f32_e32 v159, v167, v159
	v_max_f32_e32 v167, v169, v169
	v_max_f32_e32 v169, v170, v170
	v_max_f32_e32 v170, v169, v167
	v_min_f32_e32 v167, v169, v167
	v_max_f32_e32 v169, v171, v150
	v_min_f32_e32 v150, v171, v150
	v_max_f32_e32 v171, v149, v152
	v_min_f32_e32 v149, v149, v152
	v_max_f32_e32 v152, v153, v154
	v_min_f32_e32 v153, v153, v154
	v_max_f32_e32 v154, v156, v151
	v_min_f32_e32 v151, v156, v151
	v_max_f32_e32 v156, v158, v157
	v_min_f32_e32 v157, v158, v157
	v_max_f32_e32 v158, v155, v166
	v_min_f32_e32 v155, v155, v166
	v_max_f32_e32 v166, v167, v168
	v_min_f32_e32 v167, v167, v168
	v_max_f32_e32 v168, v170, v159
	v_min_f32_e32 v159, v170, v159
	v_max_f32_e32 v170, v169, v171
	v_min_f32_e32 v169, v169, v171
	v_max_f32_e32 v171, v150, v149
	v_min_f32_e32 v149, v150, v149
	v_max_f32_e32 v150, v151, v153
	v_min_f32_e32 v151, v151, v153
	v_max_f32_e32 v153, v154, v152
	v_min_f32_e32 v152, v154, v152
	v_max_f32_e32 v154, v156, v158
	v_min_f32_e32 v156, v156, v158
	v_max_f32_e32 v158, v157, v155
	v_min_f32_e32 v155, v157, v155
	v_max_f32_e32 v157, v159, v167
	v_min_f32_e32 v159, v159, v167
	v_max_f32_e32 v167, v168, v166
	v_min_f32_e32 v166, v168, v166
	v_max_f32_e32 v168, v170, v151
	v_min_f32_e32 v151, v170, v151
	v_max_f32_e32 v170, v169, v150
	v_min_f32_e32 v150, v169, v150
	v_max_f32_e32 v169, v171, v152
	v_min_f32_e32 v152, v171, v152
	v_max_f32_e32 v171, v149, v153
	v_min_f32_e32 v149, v149, v153
	v_max_f32_e32 v153, v159, v154
	v_min_f32_e32 v154, v159, v154
	v_max_f32_e32 v159, v157, v156
	v_min_f32_e32 v156, v157, v156
	v_max_f32_e32 v157, v166, v158
	v_min_f32_e32 v158, v166, v158
	v_max_f32_e32 v166, v167, v155
	v_min_f32_e32 v155, v167, v155
	v_max_f32_e32 v167, v168, v169
	v_min_f32_e32 v168, v168, v169
	v_max_f32_e32 v169, v170, v171
	v_min_f32_e32 v170, v170, v171
	v_max_f32_e32 v171, v151, v152
	v_min_f32_e32 v151, v151, v152
	v_max_f32_e32 v152, v150, v149
	v_min_f32_e32 v149, v150, v149
	v_max_f32_e32 v150, v158, v154
	v_min_f32_e32 v154, v158, v154
	v_max_f32_e32 v158, v155, v156
	v_min_f32_e32 v155, v155, v156
	v_max_f32_e32 v156, v157, v153
	v_min_f32_e32 v153, v157, v153
	v_max_f32_e32 v157, v166, v159
	v_min_f32_e32 v159, v166, v159
	v_max_f32_e32 v166, v167, v169
	v_min_f32_e32 v167, v167, v169
	v_max_f32_e32 v169, v168, v170
	v_min_f32_e32 v168, v168, v170
	v_max_f32_e32 v170, v171, v152
	v_min_f32_e32 v152, v171, v152
	v_max_f32_e32 v171, v151, v149
	v_min_f32_e32 v149, v151, v149
	v_max_f32_e32 v151, v155, v154
	v_min_f32_e32 v154, v155, v154
	v_max_f32_e32 v155, v158, v150
	v_min_f32_e32 v150, v158, v150
	v_max_f32_e32 v158, v159, v153
	v_min_f32_e32 v153, v159, v153
	v_max_f32_e32 v159, v157, v156
	v_min_f32_e32 v156, v157, v156
	v_max_f32_e32 v157, v166, v154
	v_min_f32_e32 v154, v166, v154
	v_max_f32_e32 v166, v167, v151
	v_min_f32_e32 v151, v167, v151
	v_max_f32_e32 v167, v169, v150
	v_min_f32_e32 v150, v169, v150
	v_max_f32_e32 v169, v168, v155
	v_min_f32_e32 v155, v168, v155
	v_max_f32_e32 v168, v170, v153
	v_min_f32_e32 v153, v170, v153
	v_max_f32_e32 v170, v152, v158
	v_min_f32_e32 v152, v152, v158
	v_max_f32_e32 v158, v171, v156
	v_min_f32_e32 v156, v171, v156
	v_max_f32_e32 v171, v149, v159
	v_min_f32_e32 v149, v149, v159
	v_max_f32_e32 v159, v157, v168
	v_min_f32_e32 v157, v157, v168
	v_max_f32_e32 v168, v166, v170
	v_min_f32_e32 v166, v166, v170
	v_max_f32_e32 v170, v167, v158
	v_min_f32_e32 v158, v167, v158
	v_max_f32_e32 v167, v169, v171
	v_min_f32_e32 v169, v169, v171
	v_max_f32_e32 v171, v154, v153
	v_min_f32_e32 v153, v154, v153
	v_max_f32_e32 v154, v151, v152
	v_min_f32_e32 v151, v151, v152
	v_max_f32_e32 v152, v150, v156
	v_min_f32_e32 v150, v150, v156
	v_max_f32_e32 v156, v155, v149
	v_min_f32_e32 v149, v155, v149
	v_max_f32_e32 v155, v159, v170
	v_min_f32_e32 v159, v159, v170
	v_max_f32_e32 v170, v168, v167
	v_min_f32_e32 v167, v168, v167
	v_max_f32_e32 v168, v157, v158
	v_min_f32_e32 v157, v157, v158
	v_max_f32_e32 v158, v166, v169
	v_min_f32_e32 v166, v166, v169
	v_max_f32_e32 v169, v171, v152
	v_min_f32_e32 v171, v171, v152
	v_max_f32_e32 v172, v154, v156
	v_min_f32_e32 v173, v154, v156
	v_max_f32_e32 v174, v153, v150
	v_min_f32_e32 v175, v153, v150
	v_max_f32_e32 v176, v151, v149
	v_min_f32_e32 v178, v151, v149
	v_max_f32_e32 v149, v155, v170
	v_min_f32_e32 v150, v155, v170
	v_max_f32_e32 v151, v159, v167
	v_min_f32_e32 v152, v159, v167
	v_max_f32_e32 v153, v168, v158
	v_min_f32_e32 v154, v168, v158
	v_max_f32_e32 v155, v157, v166
	v_min_f32_e32 v156, v157, v166
	v_max_f32_e32 v157, v169, v172
	v_min_f32_e32 v158, v169, v172
	v_max_f32_e32 v159, v171, v173
	v_min_f32_e32 v166, v171, v173
	v_max_f32_e32 v167, v174, v176
	v_min_f32_e32 v168, v174, v176
	v_max_f32_e32 v169, v175, v178
	s_cmp_lg_u32 s36, 0
	v_min_f32_e32 v170, v175, v178
	s_cbranch_scc1 .LBB0_219
; DI void gemm256_tile(const Params& p, int mode, int layer, const u16* R, const u16* Cc, int brow, int bcol, lchar* shm, int tid_in, int wid) {
;     ...
;         if (ch == 0) {
; #pragma unroll
;           for (int i = 0; i < 16; ++i) v[i] = wk[i];
	v_mov_b32_e32 v131, v170
	v_mov_b32_e32 v130, v169
	v_mov_b32_e32 v129, v168
	v_mov_b32_e32 v128, v167
	v_mov_b32_e32 v135, v166
	v_mov_b32_e32 v134, v159
	v_mov_b32_e32 v133, v158
	v_mov_b32_e32 v132, v157
	v_mov_b32_e32 v139, v156
	v_mov_b32_e32 v138, v155
	v_mov_b32_e32 v137, v154
	v_mov_b32_e32 v136, v153
	v_mov_b32_e32 v143, v152
	v_mov_b32_e32 v142, v151
	v_mov_b32_e32 v141, v150
	v_mov_b32_e32 v140, v149
	s_branch .LBB0_220

; #define LAS __attribute__((address_space(3)))
; DI void gemm256_tile(const Params& p, int mode, int layer, const u16* R, const u16* Cc, int brow, int bcol, lchar* shm, int tid_in, int wid) {
;     ...
;       if (kh == 1) {
; #pragma unroll
;         for (int q = 0; q < 4; ++q) *(LAS f32x4*)((lchar*)S + tok * 80 + 16 * q) = (f32x4){v[4 * q], v[4 * q + 1], v[4 * q + 2], v[4 * q + 3]};
;       }
;       __syncthreads();
;       if (kh == 0) {
;         float wk[16];
; #pragma unroll
;         for (int q = 0; q < 4; ++q) {
;           const f32x4 xv = *(const LAS f32x4*)((lchar*)S + tok * 80 + 16 * q);
;           wk[4 * q] = xv[0]; wk[4 * q + 1] = xv[1]; wk[4 * q + 2] = xv[2]; wk[4 * q + 3] = xv[3];
;         }
;         merge_top16(v, wk);
;       }
.LBB0_225:
	s_and_b64 vcc, exec, s[4:5]
	s_waitcnt lgkmcnt(0)
	s_barrier
	s_cbranch_vccnz .LBB0_227
	ds_read_b128 v[148:151], v166 offset:48
	ds_read_b128 v[152:155], v166 offset:32
	ds_read_b128 v[156:159], v166
	ds_read_b128 v[168:171], v166 offset:16
	s_waitcnt lgkmcnt(3)
	v_max_f32_e32 v143, v143, v148
	s_waitcnt lgkmcnt(2)
	v_max_f32_e32 v148, v155, v155
	v_max_f32_e32 v136, v136, v148
	v_max_f32_e32 v148, v154, v154
	v_max_f32_e32 v137, v137, v148
	v_max_f32_e32 v148, v153, v153
	v_max_f32_e32 v138, v138, v148
	v_max_f32_e32 v148, v152, v152
	v_max_f32_e32 v139, v139, v148
	s_waitcnt lgkmcnt(0)
	v_max_f32_e32 v148, v171, v171
	v_max_f32_e32 v132, v132, v148
	v_max_f32_e32 v148, v170, v170
	v_max_f32_e32 v133, v133, v148
	v_max_f32_e32 v148, v169, v169
	v_max_f32_e32 v134, v134, v148
	v_max_f32_e32 v148, v168, v168
	v_max_f32_e32 v135, v135, v148
	v_max_f32_e32 v148, v159, v159
	v_max_f32_e32 v128, v128, v148
	v_max_f32_e32 v148, v158, v158
	v_max_f32_e32 v129, v129, v148
	v_max_f32_e32 v148, v157, v157
	v_max_f32_e32 v130, v130, v148
	v_max_f32_e32 v148, v156, v156
	v_max_f32_e32 v140, v140, v151
	v_max_f32_e32 v141, v141, v150
	v_max_f32_e32 v142, v142, v149
	v_max_f32_e32 v131, v131, v148
	v_max_f32_e32 v148, v140, v132
	v_min_f32_e32 v132, v140, v132
	v_max_f32_e32 v140, v141, v133
	v_min_f32_e32 v133, v141, v133
	v_max_f32_e32 v141, v142, v134
	v_min_f32_e32 v134, v142, v134
	v_max_f32_e32 v142, v143, v135
	v_min_f32_e32 v135, v143, v135
	v_max_f32_e32 v143, v136, v128
	v_min_f32_e32 v128, v136, v128
	v_max_f32_e32 v136, v137, v129
	v_min_f32_e32 v129, v137, v129
	v_max_f32_e32 v137, v138, v130
	v_min_f32_e32 v130, v138, v130
	v_max_f32_e32 v138, v139, v131
	v_min_f32_e32 v131, v139, v131
	v_max_f32_e32 v139, v148, v143
	v_min_f32_e32 v143, v148, v143
	v_max_f32_e32 v148, v140, v136
	v_min_f32_e32 v136, v140, v136
	v_max_f32_e32 v140, v141, v137
	v_min_f32_e32 v137, v141, v137
	v_max_f32_e32 v141, v142, v138
	v_min_f32_e32 v138, v142, v138
	v_max_f32_e32 v142, v132, v128
	v_min_f32_e32 v128, v132, v128
	v_max_f32_e32 v132, v133, v129
	v_min_f32_e32 v129, v133, v129
	v_max_f32_e32 v133, v134, v130
	v_min_f32_e32 v130, v134, v130
	v_max_f32_e32 v134, v135, v131
	v_min_f32_e32 v131, v135, v131
	v_max_f32_e32 v135, v139, v140
	v_min_f32_e32 v139, v139, v140
	v_max_f32_e32 v149, v148, v141
	v_min_f32_e32 v148, v148, v141
	v_max_f32_e32 v150, v143, v137
	v_min_f32_e32 v151, v143, v137
	v_max_f32_e32 v137, v136, v138
	v_min_f32_e32 v152, v136, v138
	v_max_f32_e32 v153, v142, v133
	v_min_f32_e32 v154, v142, v133
	v_max_f32_e32 v133, v132, v134
	v_min_f32_e32 v155, v132, v134
	v_max_f32_e32 v156, v128, v130
	v_min_f32_e32 v157, v128, v130
	v_max_f32_e32 v130, v129, v131
	v_min_f32_e32 v131, v129, v131
	v_max_f32_e32 v140, v135, v149
	v_min_f32_e32 v141, v135, v149
	v_max_f32_e32 v142, v139, v148
	v_min_f32_e32 v143, v139, v148
	v_max_f32_e32 v136, v150, v137
	v_min_f32_e32 v137, v150, v137
	v_max_f32_e32 v138, v151, v152
	v_min_f32_e32 v139, v151, v152
	v_max_f32_e32 v132, v153, v133
	v_min_f32_e32 v133, v153, v133
	v_max_f32_e32 v134, v154, v155
	v_min_f32_e32 v135, v154, v155
	v_max_f32_e32 v128, v156, v130
	v_min_f32_e32 v129, v156, v130
	v_max_f32_e32 v130, v157, v131
	v_min_f32_e32 v131, v157, v131

; #define LAS __attribute__((address_space(3)))
; DI void merge_top16(float (&v)[16], const float (&w)[16]) {
; #pragma unroll
;   for (int i = 0; i < 16; ++i) v[i] = fmaxf(v[i], w[15 - i]);
;   bitonic_merge16(v);
; }
; DI void gemm256_tile(const Params& p, int mode, int layer, const u16* R, const u16* Cc, int brow, int bcol, lchar* shm, int tid_in, int wid) {
;     ...
;       for (int ch = 0; ch < 4; ++ch) {
;         float wk[16];
; #pragma unroll
;         for (int q = 0; q < 4; ++q) {
;           const int key = kh * 64 + ch * 16 + 4 * q;
;           const f32x4 xv = *(const LAS f32x4*)((lchar*)S + tok * 528 + key * 4);
; #pragma unroll
;           for (int e = 0; e < 4; ++e) wk[4 * q + e] = __uint_as_float((__float_as_uint(xv[e]) & ~127u) | (unsigned)(key + e));
;         }
;         bitonic_sort16(wk);
.LBB0_228:
	v_max_f32_e32 v156, v156, v183
	v_max_f32_e32 v157, v157, v182
	v_max_f32_e32 v158, v158, v181
	v_max_f32_e32 v159, v159, v180
	v_max_f32_e32 v152, v152, v179
	v_max_f32_e32 v153, v153, v178
	v_max_f32_e32 v154, v154, v176
	v_max_f32_e32 v155, v155, v175
	v_max_f32_e32 v148, v148, v174
	v_max_f32_e32 v149, v149, v173
	v_max_f32_e32 v150, v150, v172
	v_max_f32_e32 v151, v151, v171
	v_max_f32_e32 v144, v144, v170
	v_max_f32_e32 v145, v145, v169
	v_max_f32_e32 v146, v146, v168
	v_max_f32_e32 v147, v147, v167
	v_max_f32_e32 v167, v156, v148
	v_min_f32_e32 v148, v156, v148
	v_max_f32_e32 v156, v157, v149
	v_min_f32_e32 v149, v157, v149
	v_max_f32_e32 v157, v158, v150
	v_min_f32_e32 v150, v158, v150
	v_max_f32_e32 v158, v159, v151
	v_min_f32_e32 v151, v159, v151
	v_max_f32_e32 v159, v152, v144
	v_min_f32_e32 v144, v152, v144
	v_max_f32_e32 v152, v153, v145
	v_min_f32_e32 v145, v153, v145
	v_max_f32_e32 v153, v154, v146
	v_min_f32_e32 v146, v154, v146
	v_max_f32_e32 v154, v155, v147
	v_min_f32_e32 v147, v155, v147
	v_max_f32_e32 v155, v167, v159
	v_min_f32_e32 v159, v167, v159
	v_max_f32_e32 v167, v156, v152
	v_min_f32_e32 v152, v156, v152
	v_max_f32_e32 v156, v157, v153
	v_min_f32_e32 v153, v157, v153
	v_max_f32_e32 v157, v158, v154
	v_min_f32_e32 v154, v158, v154
	v_max_f32_e32 v158, v148, v144
	v_min_f32_e32 v144, v148, v144
	v_max_f32_e32 v148, v149, v145
	v_min_f32_e32 v145, v149, v145
	v_max_f32_e32 v149, v150, v146
	v_min_f32_e32 v146, v150, v146
	v_max_f32_e32 v150, v151, v147
	v_min_f32_e32 v147, v151, v147
	v_max_f32_e32 v151, v155, v156
	v_min_f32_e32 v155, v155, v156
	v_max_f32_e32 v168, v167, v157
	v_min_f32_e32 v167, v167, v157
	v_max_f32_e32 v169, v159, v153
	v_min_f32_e32 v170, v159, v153
	v_max_f32_e32 v153, v152, v154
	v_min_f32_e32 v171, v152, v154
	v_max_f32_e32 v172, v158, v149
	v_min_f32_e32 v173, v158, v149
	v_max_f32_e32 v149, v148, v150
	v_min_f32_e32 v174, v148, v150
	v_max_f32_e32 v175, v144, v146
	v_min_f32_e32 v176, v144, v146
	v_max_f32_e32 v146, v145, v147
	v_min_f32_e32 v147, v145, v147
	v_max_f32_e32 v156, v151, v168
	v_min_f32_e32 v157, v151, v168
	v_max_f32_e32 v158, v155, v167
	v_min_f32_e32 v159, v155, v167
	v_max_f32_e32 v152, v169, v153
	v_min_f32_e32 v153, v169, v153
	v_max_f32_e32 v154, v170, v171
	v_min_f32_e32 v155, v170, v171
	v_max_f32_e32 v148, v172, v149
	v_min_f32_e32 v149, v172, v149
	v_max_f32_e32 v150, v173, v174
	v_min_f32_e32 v151, v173, v174
	v_max_f32_e32 v144, v175, v146
	v_min_f32_e32 v145, v175, v146
	v_max_f32_e32 v146, v176, v147
	v_min_f32_e32 v147, v176, v147
	s_add_i32 s36, s36, 16
	s_cmp_lg_u32 s36, 64
	v_add_u32_e32 v165, 64, v165
	s_cbranch_scc0 .LBB0_231
.LBB0_229:
	ds_read_b128 v[168:171], v165
	ds_read_b128 v[172:175], v165 offset:16
	ds_read_b128 v[178:181], v165 offset:32
	ds_read_b128 v[182:185], v165 offset:48
	s_add_i32 s28, s49, s36
	s_add_i32 s29, s28, 4
	s_waitcnt lgkmcnt(1)
	v_and_b32_e32 v176, 0xffffff80, v179
	v_and_b32_e32 v167, 0xffffff80, v168
	v_and_b32_e32 v168, 0xffffff80, v169
	v_or_b32_e32 v167, s28, v167
	v_or3_b32 v168, s28, v168, 1
	v_and_b32_e32 v169, 0xffffff80, v170
	v_and_b32_e32 v170, 0xffffff80, v171
	v_or3_b32 v169, s28, v169, 2
	v_or3_b32 v170, s28, v170, 3
	v_and_b32_e32 v171, 0xffffff80, v172
	v_and_b32_e32 v172, 0xffffff80, v173
	v_or_b32_e32 v171, s29, v171
	v_or3_b32 v172, s28, v172, 5
	v_and_b32_e32 v173, 0xffffff80, v174
	v_and_b32_e32 v174, 0xffffff80, v175
	v_and_b32_e32 v175, 0xffffff80, v178
	v_and_b32_e32 v178, 0xffffff80, v180
	s_waitcnt lgkmcnt(0)
; DI void ce_desc(float& hi, float& lo) { const float a = hi, b = lo; hi = fmaxf(a, b); lo = fminf(a, b); }
; DI void bitonic_sort16(float (&v)[16]) {
; #pragma unroll
;   for (int k = 2; k <= 16; k <<= 1)
; #pragma unroll
;     for (int j = k >> 1; j > 0; j >>= 1)
; #pragma unroll
;       for (int i = 0; i < 16; ++i) {
;         const int l = i ^ j;
;         if (l > i) { if ((i & k) == 0 || k == 16) ce_desc(v[i], v[l]); else ce_desc(v[l], v[i]); }
;       }
; }
; DI void gemm256_tile(const Params& p, int mode, int layer, const u16* R, const u16* Cc, int brow, int bcol, lchar* shm, int tid_in, int wid) {
;     ...
;         bitonic_sort16(wk);
;         if (ch == 0) {
; #pragma unroll
;           for (int i = 0; i < 16; ++i) v[i] = wk[i];
	v_and_b32_e32 v180, 0xffffff80, v182
	v_and_b32_e32 v182, 0xffffff80, v184
	v_max_f32_e32 v184, v167, v168
	v_min_f32_e32 v167, v167, v168
	v_max_f32_e32 v168, v169, v169
	v_max_f32_e32 v169, v170, v170
	v_or3_b32 v173, s28, v173, 6
	v_or3_b32 v174, s28, v174, 7
	s_add_i32 s29, s28, 8
	v_max_f32_e32 v170, v169, v168
	v_min_f32_e32 v168, v169, v168
	v_max_f32_e32 v169, v172, v172
	v_or_b32_e32 v175, s29, v175
	v_or3_b32 v176, s28, v176, 9
	v_and_b32_e32 v179, 0xffffff80, v181
	v_max_f32_e32 v172, v171, v169
	v_min_f32_e32 v169, v171, v169
	v_max_f32_e32 v171, v173, v173
	v_max_f32_e32 v173, v174, v174
	v_or3_b32 v178, s28, v178, 10
	v_or3_b32 v179, s28, v179, 11
	s_add_i32 s29, s28, 12
	v_and_b32_e32 v181, 0xffffff80, v183
	v_max_f32_e32 v174, v173, v171
	v_min_f32_e32 v171, v173, v171
	v_max_f32_e32 v173, v176, v176
	v_or_b32_e32 v180, s29, v180
	v_or3_b32 v181, s28, v181, 13
	v_and_b32_e32 v183, 0xffffff80, v185
	v_max_f32_e32 v176, v175, v173
	v_min_f32_e32 v173, v175, v173
	v_max_f32_e32 v175, v178, v178
	v_max_f32_e32 v178, v179, v179
	v_or3_b32 v182, s28, v182, 14
	v_or3_b32 v183, s28, v183, 15
	v_max_f32_e32 v179, v178, v175
	v_min_f32_e32 v175, v178, v175
	v_max_f32_e32 v178, v181, v181
	v_max_f32_e32 v181, v180, v178
	v_min_f32_e32 v178, v180, v178
	v_max_f32_e32 v180, v182, v182
	v_max_f32_e32 v182, v183, v183
	v_max_f32_e32 v183, v182, v180
	v_min_f32_e32 v180, v182, v180
	v_max_f32_e32 v182, v184, v168
	v_min_f32_e32 v168, v184, v168
	v_max_f32_e32 v184, v167, v170
	v_min_f32_e32 v167, v167, v170
	v_max_f32_e32 v170, v171, v172
	v_min_f32_e32 v171, v171, v172
	v_max_f32_e32 v172, v174, v169
	v_min_f32_e32 v169, v174, v169
	v_max_f32_e32 v174, v176, v175
	v_min_f32_e32 v175, v176, v175
	v_max_f32_e32 v176, v173, v179
	v_min_f32_e32 v173, v173, v179
	v_max_f32_e32 v179, v180, v181
	v_min_f32_e32 v180, v180, v181
	v_max_f32_e32 v181, v183, v178
	v_min_f32_e32 v178, v183, v178
	v_max_f32_e32 v183, v182, v184
	v_min_f32_e32 v182, v182, v184
	v_max_f32_e32 v184, v168, v167
	v_min_f32_e32 v167, v168, v167
	v_max_f32_e32 v168, v169, v171
	v_min_f32_e32 v169, v169, v171
	v_max_f32_e32 v171, v172, v170
	v_min_f32_e32 v170, v172, v170
	v_max_f32_e32 v172, v174, v176
	v_min_f32_e32 v174, v174, v176
	v_max_f32_e32 v176, v175, v173
	v_min_f32_e32 v173, v175, v173
	v_max_f32_e32 v175, v178, v180
	v_min_f32_e32 v178, v178, v180
	v_max_f32_e32 v180, v181, v179
	v_min_f32_e32 v179, v181, v179
	v_max_f32_e32 v181, v183, v169
	v_min_f32_e32 v169, v183, v169
	v_max_f32_e32 v183, v182, v168
	v_min_f32_e32 v168, v182, v168
	v_max_f32_e32 v182, v184, v170
	v_min_f32_e32 v170, v184, v170
	v_max_f32_e32 v184, v167, v171
	v_min_f32_e32 v167, v167, v171
	v_max_f32_e32 v171, v178, v172
	v_min_f32_e32 v172, v178, v172
	v_max_f32_e32 v178, v175, v174
	v_min_f32_e32 v174, v175, v174
	v_max_f32_e32 v175, v179, v176
	v_min_f32_e32 v176, v179, v176
	v_max_f32_e32 v179, v180, v173
	v_min_f32_e32 v173, v180, v173
	v_max_f32_e32 v180, v181, v182
	v_min_f32_e32 v181, v181, v182
	v_max_f32_e32 v182, v183, v184
	v_min_f32_e32 v183, v183, v184
	v_max_f32_e32 v184, v169, v170
	v_min_f32_e32 v169, v169, v170
	v_max_f32_e32 v170, v168, v167
	v_min_f32_e32 v167, v168, v167
	v_max_f32_e32 v168, v176, v172
	v_min_f32_e32 v172, v176, v172
	v_max_f32_e32 v176, v173, v174
	v_min_f32_e32 v173, v173, v174
	v_max_f32_e32 v174, v175, v171
	v_min_f32_e32 v171, v175, v171
	v_max_f32_e32 v175, v179, v178
	v_min_f32_e32 v178, v179, v178
	v_max_f32_e32 v179, v180, v182
	v_min_f32_e32 v180, v180, v182
	v_max_f32_e32 v182, v181, v183
	v_min_f32_e32 v181, v181, v183
	v_max_f32_e32 v183, v184, v170
	v_min_f32_e32 v170, v184, v170
	v_max_f32_e32 v184, v169, v167
	v_min_f32_e32 v167, v169, v167
	v_max_f32_e32 v169, v173, v172
	v_min_f32_e32 v172, v173, v172
	v_max_f32_e32 v173, v176, v168
	v_min_f32_e32 v168, v176, v168
	v_max_f32_e32 v176, v178, v171
	v_min_f32_e32 v171, v178, v171
	v_max_f32_e32 v178, v175, v174
	v_min_f32_e32 v174, v175, v174
	v_max_f32_e32 v175, v179, v172
	v_min_f32_e32 v172, v179, v172
	v_max_f32_e32 v179, v180, v169
	v_min_f32_e32 v169, v180, v169
	v_max_f32_e32 v180, v182, v168
	v_min_f32_e32 v168, v182, v168
	v_max_f32_e32 v182, v181, v173
	v_min_f32_e32 v173, v181, v173
	v_max_f32_e32 v181, v183, v171
	v_min_f32_e32 v171, v183, v171
	v_max_f32_e32 v183, v170, v176
	v_min_f32_e32 v170, v170, v176
	v_max_f32_e32 v176, v184, v174
	v_min_f32_e32 v174, v184, v174
	v_max_f32_e32 v184, v167, v178
	v_min_f32_e32 v167, v167, v178
	v_max_f32_e32 v178, v175, v181
	v_min_f32_e32 v175, v175, v181
	v_max_f32_e32 v181, v179, v183
	v_min_f32_e32 v179, v179, v183
	v_max_f32_e32 v183, v180, v176
	v_min_f32_e32 v176, v180, v176
	v_max_f32_e32 v180, v182, v184
	v_min_f32_e32 v182, v182, v184
	v_max_f32_e32 v184, v172, v171
	v_min_f32_e32 v171, v172, v171
	v_max_f32_e32 v172, v169, v170
	v_min_f32_e32 v169, v169, v170
	v_max_f32_e32 v170, v168, v174
	v_min_f32_e32 v168, v168, v174
	v_max_f32_e32 v174, v173, v167
	v_min_f32_e32 v167, v173, v167
	v_max_f32_e32 v173, v178, v183
	v_min_f32_e32 v178, v178, v183
	v_max_f32_e32 v183, v181, v180
	v_min_f32_e32 v180, v181, v180
	v_max_f32_e32 v181, v175, v176
	v_min_f32_e32 v175, v175, v176
	v_max_f32_e32 v176, v179, v182
	v_min_f32_e32 v179, v179, v182
	v_max_f32_e32 v182, v184, v170
	v_min_f32_e32 v184, v184, v170
	v_max_f32_e32 v185, v172, v174
	v_min_f32_e32 v186, v172, v174
	v_max_f32_e32 v187, v171, v168
	v_min_f32_e32 v188, v171, v168
	v_max_f32_e32 v189, v169, v167
	v_min_f32_e32 v190, v169, v167
	v_max_f32_e32 v167, v173, v183
	v_min_f32_e32 v168, v173, v183
	v_max_f32_e32 v169, v178, v180
	v_min_f32_e32 v170, v178, v180
	v_max_f32_e32 v171, v181, v176
	v_min_f32_e32 v172, v181, v176
	v_max_f32_e32 v173, v175, v179
	v_min_f32_e32 v174, v175, v179
	v_max_f32_e32 v175, v182, v185
	v_min_f32_e32 v176, v182, v185
	v_max_f32_e32 v178, v184, v186
	v_min_f32_e32 v179, v184, v186
	v_max_f32_e32 v180, v187, v189
	v_min_f32_e32 v181, v187, v189
	v_max_f32_e32 v182, v188, v190
	s_cmp_eq_u32 s36, 0
	v_min_f32_e32 v183, v188, v190
	s_cbranch_scc0 .LBB0_228
	v_mov_b32_e32 v147, v183
	v_mov_b32_e32 v146, v182
	v_mov_b32_e32 v145, v181
	v_mov_b32_e32 v144, v180
	v_mov_b32_e32 v151, v179
	v_mov_b32_e32 v150, v178
	v_mov_b32_e32 v149, v176
	v_mov_b32_e32 v148, v175
	v_mov_b32_e32 v155, v174
	v_mov_b32_e32 v154, v173
	v_mov_b32_e32 v153, v172
	v_mov_b32_e32 v152, v171
	v_mov_b32_e32 v159, v170
	v_mov_b32_e32 v158, v169
	v_mov_b32_e32 v157, v168
	v_mov_b32_e32 v156, v167
	s_add_i32 s36, s36, 16
	s_cmp_lg_u32 s36, 64
	v_add_u32_e32 v165, 64, v165
	s_cbranch_scc1 .LBB0_229

; #define LAS __attribute__((address_space(3)))
; DI void gemm256_tile(const Params& p, int mode, int layer, const u16* R, const u16* Cc, int brow, int bcol, lchar* shm, int tid_in, int wid) {
;     ...
;       if (kh == 1) {
; #pragma unroll
;         for (int q = 0; q < 4; ++q) *(LAS f32x4*)((lchar*)S + tok * 80 + 16 * q) = (f32x4){v[4 * q], v[4 * q + 1], v[4 * q + 2], v[4 * q + 3]};
;       }
;       __syncthreads();
;       if (kh == 0) {
;         float wk[16];
; #pragma unroll
;         for (int q = 0; q < 4; ++q) {
;           const f32x4 xv = *(const LAS f32x4*)((lchar*)S + tok * 80 + 16 * q);
;           wk[4 * q] = xv[0]; wk[4 * q + 1] = xv[1]; wk[4 * q + 2] = xv[2]; wk[4 * q + 3] = xv[3];
;         }
;         merge_top16(v, wk);
;       }
; #pragma unroll
;       for (int j = 0; j < 16; ++j) { if (ai == 0) L0[j] = v[j]; else L1[j] = v[j]; }
;     }
;     __syncthreads();
;     LAS unsigned* LL = (LAS unsigned*)shm;
;     if (kh == 0) {
; #pragma unroll
;       for (int j = 0; j < 16; ++j) { LL[tok * 32 + ((j + tok) & 31)] = __float_as_uint(L0[j]); LL[tok * 32 + ((16 + j + tok) & 31)] = __float_as_uint(L1[j]); }
.LBB0_233:
	s_and_b64 vcc, exec, s[4:5]
	s_waitcnt lgkmcnt(0)
	s_barrier
	s_cbranch_vccnz .LBB0_235
	ds_read_b128 v[168:171], v166 offset:48
	ds_read_b128 v[172:175], v166 offset:32
	ds_read_b128 v[178:181], v166
	ds_read_b128 v[182:185], v166 offset:16
	s_waitcnt lgkmcnt(3)
	v_max_f32_e32 v165, v171, v171
	v_max_f32_e32 v156, v156, v165
	v_max_f32_e32 v165, v170, v170
	v_max_f32_e32 v157, v157, v165
	v_max_f32_e32 v165, v169, v169
	v_max_f32_e32 v158, v158, v165
	v_max_f32_e32 v165, v168, v168
	v_max_f32_e32 v159, v159, v165
	s_waitcnt lgkmcnt(2)
	v_max_f32_e32 v165, v175, v175
	v_max_f32_e32 v152, v152, v165
	v_max_f32_e32 v165, v174, v174
	v_max_f32_e32 v153, v153, v165
	v_max_f32_e32 v165, v173, v173
	v_max_f32_e32 v154, v154, v165
	v_max_f32_e32 v165, v172, v172
	v_max_f32_e32 v155, v155, v165
	s_waitcnt lgkmcnt(0)
	v_max_f32_e32 v165, v185, v185
	v_max_f32_e32 v148, v148, v165
	v_max_f32_e32 v165, v184, v184
	v_max_f32_e32 v149, v149, v165
	v_max_f32_e32 v165, v183, v183
	v_max_f32_e32 v150, v150, v165
	v_max_f32_e32 v165, v182, v182
	v_max_f32_e32 v151, v151, v165
	v_max_f32_e32 v165, v181, v181
	v_max_f32_e32 v144, v144, v165
	v_max_f32_e32 v165, v180, v180
	v_max_f32_e32 v145, v145, v165
	v_max_f32_e32 v165, v179, v179
	v_max_f32_e32 v146, v146, v165
	v_max_f32_e32 v165, v178, v178
	v_max_f32_e32 v147, v147, v165
	v_max_f32_e32 v165, v156, v148
	v_min_f32_e32 v148, v156, v148
	v_max_f32_e32 v156, v157, v149
	v_min_f32_e32 v149, v157, v149
	v_max_f32_e32 v157, v158, v150
	v_min_f32_e32 v150, v158, v150
	v_max_f32_e32 v158, v159, v151
	v_min_f32_e32 v151, v159, v151
	v_max_f32_e32 v159, v152, v144
	v_min_f32_e32 v144, v152, v144
	v_max_f32_e32 v152, v153, v145
	v_min_f32_e32 v145, v153, v145
	v_max_f32_e32 v153, v154, v146
	v_min_f32_e32 v146, v154, v146
	v_max_f32_e32 v154, v155, v147
	v_min_f32_e32 v147, v155, v147
	v_max_f32_e32 v155, v165, v159
	v_min_f32_e32 v159, v165, v159
	v_max_f32_e32 v165, v156, v152
	v_min_f32_e32 v152, v156, v152
	v_max_f32_e32 v156, v157, v153
	v_min_f32_e32 v153, v157, v153
	v_max_f32_e32 v157, v158, v154
	v_min_f32_e32 v154, v158, v154
	v_max_f32_e32 v158, v148, v144
	v_min_f32_e32 v144, v148, v144
	v_max_f32_e32 v148, v149, v145
	v_min_f32_e32 v145, v149, v145
	v_max_f32_e32 v149, v150, v146
	v_min_f32_e32 v146, v150, v146
	v_max_f32_e32 v150, v151, v147
	v_min_f32_e32 v147, v151, v147
	v_max_f32_e32 v151, v155, v156
	v_min_f32_e32 v155, v155, v156
	v_max_f32_e32 v167, v165, v157
	v_min_f32_e32 v165, v165, v157
	v_max_f32_e32 v168, v159, v153
	v_min_f32_e32 v169, v159, v153
	v_max_f32_e32 v153, v152, v154
	v_min_f32_e32 v170, v152, v154
	v_max_f32_e32 v171, v158, v149
	v_min_f32_e32 v172, v158, v149
	v_max_f32_e32 v149, v148, v150
	v_min_f32_e32 v173, v148, v150
	v_max_f32_e32 v174, v144, v146
	v_min_f32_e32 v175, v144, v146
	v_max_f32_e32 v146, v145, v147
	v_min_f32_e32 v147, v145, v147
	v_max_f32_e32 v156, v151, v167
	v_min_f32_e32 v157, v151, v167
	v_max_f32_e32 v158, v155, v165
	v_min_f32_e32 v159, v155, v165
	v_max_f32_e32 v152, v168, v153
	v_min_f32_e32 v153, v168, v153
	v_max_f32_e32 v154, v169, v170
	v_min_f32_e32 v155, v169, v170
	v_max_f32_e32 v148, v171, v149
	v_min_f32_e32 v149, v171, v149
	v_max_f32_e32 v150, v172, v173
	v_min_f32_e32 v151, v172, v173
	v_max_f32_e32 v144, v174, v146
	v_min_f32_e32 v145, v174, v146
	v_max_f32_e32 v146, v175, v147
	v_min_f32_e32 v147, v175, v147
.LBB0_235:
	s_and_b64 vcc, exec, s[90:91]
	s_barrier
	s_cbranch_vccz .LBB0_237
	v_mad_u32_u24 v165, v164, 48, v166
	v_and_b32_e32 v167, 31, v163
	v_lshl_add_u32 v167, v167, 2, v165
	ds_write_b32 v167, v140
	v_bitop3_b32 v167, v163, 31, 16 bitop3:0x48
	v_lshl_add_u32 v167, v167, 2, v165
	ds_write_b32 v167, v156
	v_add_u32_e32 v167, 1, v163
	v_and_b32_e32 v167, 31, v167
	v_xor_b32_e32 v166, 16, v163
	v_lshl_add_u32 v167, v167, 2, v165
	ds_write_b32 v167, v141
	v_add_u32_e32 v167, 1, v166
	v_and_b32_e32 v167, 31, v167
	v_lshl_add_u32 v167, v167, 2, v165
	ds_write_b32 v167, v157
	v_add_u32_e32 v167, 2, v163
	v_and_b32_e32 v167, 31, v167
	v_lshl_add_u32 v167, v167, 2, v165
	ds_write_b32 v167, v142
	v_add_u32_e32 v167, 2, v166
	v_and_b32_e32 v167, 31, v167
	v_lshl_add_u32 v167, v167, 2, v165
	ds_write_b32 v167, v158
	v_add_u32_e32 v167, 3, v163
	v_and_b32_e32 v167, 31, v167
	v_lshl_add_u32 v167, v167, 2, v165
	ds_write_b32 v167, v143
	v_add_u32_e32 v167, 3, v166
	v_and_b32_e32 v167, 31, v167
	v_lshl_add_u32 v167, v167, 2, v165
	ds_write_b32 v167, v159
	v_add_u32_e32 v167, 4, v163
	v_and_b32_e32 v167, 31, v167
	v_lshl_add_u32 v167, v167, 2, v165
	ds_write_b32 v167, v136
	v_add_u32_e32 v167, 4, v166
	v_and_b32_e32 v167, 31, v167
	v_lshl_add_u32 v167, v167, 2, v165
	ds_write_b32 v167, v152
	v_add_u32_e32 v167, 5, v163
	v_and_b32_e32 v167, 31, v167
	v_lshl_add_u32 v167, v167, 2, v165
	ds_write_b32 v167, v137
	v_add_u32_e32 v167, 5, v166
	v_and_b32_e32 v167, 31, v167
	v_lshl_add_u32 v167, v167, 2, v165
	ds_write_b32 v167, v153
	v_add_u32_e32 v167, 6, v163
	v_and_b32_e32 v167, 31, v167
	v_lshl_add_u32 v167, v167, 2, v165
	ds_write_b32 v167, v138
	v_add_u32_e32 v167, 6, v166
	v_and_b32_e32 v167, 31, v167
	v_lshl_add_u32 v167, v167, 2, v165
	ds_write_b32 v167, v154
	v_add_u32_e32 v167, 7, v163
	v_and_b32_e32 v167, 31, v167
	v_lshl_add_u32 v167, v167, 2, v165
	ds_write_b32 v167, v139
	v_add_u32_e32 v167, 7, v166
	v_and_b32_e32 v167, 31, v167
	v_lshl_add_u32 v167, v167, 2, v165
	ds_write_b32 v167, v155
	v_add_u32_e32 v167, 8, v163
	v_and_b32_e32 v167, 31, v167
	v_lshl_add_u32 v167, v167, 2, v165
	ds_write_b32 v167, v132
	v_add_u32_e32 v167, 8, v166
	v_and_b32_e32 v167, 31, v167
	v_lshl_add_u32 v167, v167, 2, v165
; DI void gemm256_tile(const Params& p, int mode, int layer, const u16* R, const u16* Cc, int brow, int bcol, lchar* shm, int tid_in, int wid) {
;     ...
;       for (int j = 0; j < 16; ++j) { LL[tok * 32 + ((j + tok) & 31)] = __float_as_uint(L0[j]); LL[tok * 32 + ((16 + j + tok) & 31)] = __float_as_uint(L1[j]); }
;       float s1[16], s2[16], v[16];
; #pragma unroll
;       for (int j = 0; j < 16; ++j) { s1[j] = __uint_as_float(__float_as_uint(L0[j]) & ~127u); s2[j] = __uint_as_float(__float_as_uint(L1[j]) & ~127u); v[j] = -3.0e38f; }
; #pragma unroll
;       for (int ch = 0; ch < 4; ++ch) {
;         float wk[16];
; #pragma unroll
;         for (int i = 0; i < 16; ++i) {
;           constexpr unsigned char PAIRS[64] = {0, 1, 2, 3, 4, 5, 6, 7, 8, 9, 10, 11, 12, 13, 14, 15, 16, 17, 18, 19, 20, 21, 22, 23, 32, 33, 34, 35, 36, 48, 49, 50, 51, 64, 65, 66, 80, 81, 96, 97, 112, 113, 128, 144, 160, 176, 192, 208, 224, 240, 255, 255, 255, 255, 255, 255, 255, 255, 255, 255, 255, 255, 255, 255};
;           const int code = PAIRS[ch * 16 + i];
;           if (code == 255) { wk[i] = -3.0e38f; }
;           else { const float sm = s1[code >> 4] + s2[code & 15]; wk[i] = __uint_as_float((__float_as_uint(sm) & ~255u) | (unsigned)code); }
;         }
;         if (ch == 0) {
; #pragma unroll
;           for (int i = 0; i < 16; ++i) v[i] = wk[i];
;         } else {
;           bitonic_sort16(wk);
;           merge_top16(v, wk);
	ds_write_b32 v167, v148
	v_add_u32_e32 v167, 9, v163
	v_and_b32_e32 v167, 31, v167
	v_lshl_add_u32 v167, v167, 2, v165
	ds_write_b32 v167, v133
	v_add_u32_e32 v167, 9, v166
	v_and_b32_e32 v167, 31, v167
	v_lshl_add_u32 v167, v167, 2, v165
	ds_write_b32 v167, v149
	v_add_u32_e32 v167, 10, v163
	v_and_b32_e32 v167, 31, v167
	v_lshl_add_u32 v167, v167, 2, v165
	ds_write_b32 v167, v134
	v_add_u32_e32 v167, 10, v166
	v_and_b32_e32 v167, 31, v167
	v_lshl_add_u32 v167, v167, 2, v165
	ds_write_b32 v167, v150
	v_add_u32_e32 v167, 11, v163
	v_and_b32_e32 v167, 31, v167
	v_lshl_add_u32 v167, v167, 2, v165
	ds_write_b32 v167, v135
	v_add_u32_e32 v167, 11, v166
	v_and_b32_e32 v167, 31, v167
	v_lshl_add_u32 v167, v167, 2, v165
	ds_write_b32 v167, v151
	v_add_u32_e32 v167, 12, v163
	v_and_b32_e32 v167, 31, v167
	v_lshl_add_u32 v167, v167, 2, v165
	ds_write_b32 v167, v128
	v_add_u32_e32 v167, 12, v166
	v_and_b32_e32 v167, 31, v167
	v_lshl_add_u32 v167, v167, 2, v165
	ds_write_b32 v167, v144
	v_add_u32_e32 v167, 13, v163
	v_and_b32_e32 v167, 31, v167
	v_lshl_add_u32 v167, v167, 2, v165
	ds_write_b32 v167, v129
	v_add_u32_e32 v167, 13, v166
	v_and_b32_e32 v167, 31, v167
	v_lshl_add_u32 v167, v167, 2, v165
	ds_write_b32 v167, v145
	v_add_u32_e32 v167, 14, v163
	v_and_b32_e32 v167, 31, v167
	v_lshl_add_u32 v167, v167, 2, v165
	ds_write_b32 v167, v130
	v_add_u32_e32 v167, 14, v166
	v_and_b32_e32 v167, 31, v167
	v_lshl_add_u32 v167, v167, 2, v165
	ds_write_b32 v167, v146
	v_add_u32_e32 v167, 15, v163
	v_add_u32_e32 v166, 15, v166
	v_and_b32_e32 v167, 31, v167
	v_and_b32_e32 v166, 31, v166
	v_lshl_add_u32 v167, v167, 2, v165
	v_lshl_add_u32 v166, v166, 2, v165
	ds_write_b32 v167, v131
	ds_write_b32 v166, v147
	v_and_b32_e32 v166, 0xffffff80, v140
	v_and_b32_e32 v140, 0xffffff80, v156
	v_and_b32_e32 v141, 0xffffff80, v141
	v_and_b32_e32 v156, 0xffffff80, v157
	v_and_b32_e32 v157, 0xffffff80, v158
	v_and_b32_e32 v158, 0xffffff80, v159
	v_and_b32_e32 v152, 0xffffff80, v152
	v_and_b32_e32 v153, 0xffffff80, v153
	v_and_b32_e32 v154, 0xffffff80, v154
	v_and_b32_e32 v155, 0xffffff80, v155
	v_and_b32_e32 v148, 0xffffff80, v148
	v_and_b32_e32 v149, 0xffffff80, v149
	v_and_b32_e32 v150, 0xffffff80, v150
	v_and_b32_e32 v151, 0xffffff80, v151
	v_and_b32_e32 v159, 0xffffff80, v128
	v_and_b32_e32 v144, 0xffffff80, v144
	v_and_b32_e32 v167, 0xffffff80, v129
	v_and_b32_e32 v145, 0xffffff80, v145
	v_and_b32_e32 v129, 0xffffff80, v130
	v_and_b32_e32 v130, 0xffffff80, v146
	v_and_b32_e32 v128, 0xffffff80, v131
	v_and_b32_e32 v131, 0xffffff80, v147
	v_add_f32_e32 v146, v166, v140
	v_add_f32_e32 v147, v166, v156
	v_add_f32_e32 v168, v166, v157
	v_add_f32_e32 v169, v166, v158
	v_add_f32_e32 v170, v166, v152
	v_add_f32_e32 v171, v166, v153
	v_add_f32_e32 v172, v166, v154
	v_add_f32_e32 v173, v166, v155
	v_add_f32_e32 v148, v166, v148
	v_add_f32_e32 v149, v166, v149
	v_add_f32_e32 v150, v166, v150
	v_add_f32_e32 v151, v166, v151
	v_add_f32_e32 v144, v166, v144
	v_add_f32_e32 v145, v166, v145
	v_add_f32_e32 v130, v166, v130
	v_add_f32_e32 v131, v166, v131
	v_add_f32_e32 v166, v141, v140
	v_add_f32_e32 v174, v141, v156
	v_and_or_b32 v166, v166, s87, 16
	v_and_or_b32 v174, v174, s87, 17
	v_add_f32_e32 v175, v141, v157
	v_add_f32_e32 v176, v141, v158
	v_and_b32_e32 v142, 0xffffff80, v142
	v_and_or_b32 v175, v175, s87, 18
	v_and_or_b32 v176, v176, s87, 19
	v_add_f32_e32 v178, v141, v152
	v_add_f32_e32 v153, v141, v153
	v_add_f32_e32 v154, v141, v154
	v_add_f32_e32 v141, v141, v155
	v_and_b32_e32 v143, 0xffffff80, v143
	v_and_or_b32 v178, v178, s87, 20
	v_and_or_b32 v153, v153, s87, 21
	v_and_or_b32 v154, v154, s87, 22
	v_and_or_b32 v141, v141, s87, 23
	v_add_f32_e32 v155, v142, v140
	v_add_f32_e32 v179, v142, v156
	v_max_f32_e32 v184, v166, v174
	v_min_f32_e32 v166, v166, v174
	v_max_f32_e32 v174, v175, v175
	v_max_f32_e32 v175, v176, v176
	v_and_or_b32 v155, v155, s87, 32
	v_and_or_b32 v179, v179, s87, 33
	v_add_f32_e32 v180, v142, v157
	v_add_f32_e32 v181, v142, v158
	v_add_f32_e32 v142, v142, v152
	v_add_f32_e32 v152, v143, v140
	v_max_f32_e32 v176, v175, v174
	v_min_f32_e32 v174, v175, v174
	v_max_f32_e32 v175, v178, v178
	v_and_or_b32 v180, v180, s87, 34
	v_and_or_b32 v181, v181, s87, 35
	v_and_or_b32 v142, v142, s87, 36
	v_and_or_b32 v152, v152, s87, 48
	v_add_f32_e32 v182, v143, v156
	v_add_f32_e32 v183, v143, v157
	v_max_f32_e32 v178, v175, v153
	v_min_f32_e32 v153, v175, v153
	v_max_f32_e32 v175, v141, v154
	v_min_f32_e32 v141, v141, v154
	v_max_f32_e32 v154, v179, v179
	v_and_or_b32 v182, v182, s87, 49
	v_and_or_b32 v183, v183, s87, 50
	v_max_f32_e32 v179, v155, v154
	v_min_f32_e32 v154, v155, v154
	v_max_f32_e32 v155, v180, v180
	v_max_f32_e32 v180, v181, v181
	v_max_f32_e32 v181, v180, v155
	v_min_f32_e32 v155, v180, v155
	v_max_f32_e32 v180, v142, v152
	v_min_f32_e32 v142, v142, v152
	v_max_f32_e32 v152, v182, v182
	v_max_f32_e32 v182, v183, v183
	v_max_f32_e32 v183, v182, v152
	v_min_f32_e32 v152, v182, v152
	v_max_f32_e32 v182, v184, v174
	v_min_f32_e32 v174, v184, v174
	v_max_f32_e32 v184, v166, v176
	v_min_f32_e32 v166, v166, v176
	v_max_f32_e32 v176, v141, v178
	v_min_f32_e32 v141, v141, v178
	v_max_f32_e32 v178, v175, v153
	v_min_f32_e32 v153, v175, v153
	v_max_f32_e32 v175, v179, v155
	v_min_f32_e32 v155, v179, v155
	v_max_f32_e32 v179, v154, v181
	v_min_f32_e32 v154, v154, v181
	v_max_f32_e32 v181, v152, v180
	v_min_f32_e32 v152, v152, v180
	v_max_f32_e32 v180, v183, v142
	v_min_f32_e32 v142, v183, v142
	v_max_f32_e32 v183, v182, v184
	v_min_f32_e32 v182, v182, v184
	v_max_f32_e32 v184, v174, v166
	v_min_f32_e32 v166, v174, v166
	v_max_f32_e32 v174, v153, v141
; DI void gemm256_tile(const Params& p, int mode, int layer, const u16* R, const u16* Cc, int brow, int bcol, lchar* shm, int tid_in, int wid) {
;     ...
;       for (int ch = 0; ch < 4; ++ch) {
;         float wk[16];
; #pragma unroll
;         for (int i = 0; i < 16; ++i) {
;           constexpr unsigned char PAIRS[64] = {0, 1, 2, 3, 4, 5, 6, 7, 8, 9, 10, 11, 12, 13, 14, 15, 16, 17, 18, 19, 20, 21, 22, 23, 32, 33, 34, 35, 36, 48, 49, 50, 51, 64, 65, 66, 80, 81, 96, 97, 112, 113, 128, 144, 160, 176, 192, 208, 224, 240, 255, 255, 255, 255, 255, 255, 255, 255, 255, 255, 255, 255, 255, 255};
;           const int code = PAIRS[ch * 16 + i];
;           if (code == 255) { wk[i] = -3.0e38f; }
;           else { const float sm = s1[code >> 4] + s2[code & 15]; wk[i] = __uint_as_float((__float_as_uint(sm) & ~255u) | (unsigned)code); }
;         }
;         if (ch == 0) {
; #pragma unroll
;           for (int i = 0; i < 16; ++i) v[i] = wk[i];
;         } else {
;           bitonic_sort16(wk);
;           merge_top16(v, wk);
;         }
	v_min_f32_e32 v141, v153, v141
	v_max_f32_e32 v153, v178, v176
	v_min_f32_e32 v176, v178, v176
	v_max_f32_e32 v178, v175, v179
	v_min_f32_e32 v175, v175, v179
	v_max_f32_e32 v179, v155, v154
	v_min_f32_e32 v154, v155, v154
	v_max_f32_e32 v155, v142, v152
	v_min_f32_e32 v142, v142, v152
	v_max_f32_e32 v152, v180, v181
	v_min_f32_e32 v180, v180, v181
	v_max_f32_e32 v181, v183, v141
	v_min_f32_e32 v141, v183, v141
	v_max_f32_e32 v183, v182, v174
	v_min_f32_e32 v174, v182, v174
	v_max_f32_e32 v182, v184, v176
	v_min_f32_e32 v176, v184, v176
	v_max_f32_e32 v184, v166, v153
	v_min_f32_e32 v153, v166, v153
	v_max_f32_e32 v166, v142, v178
	v_min_f32_e32 v142, v142, v178
	v_max_f32_e32 v178, v155, v175
	v_min_f32_e32 v155, v155, v175
	v_max_f32_e32 v175, v180, v179
	v_min_f32_e32 v179, v180, v179
	v_max_f32_e32 v180, v152, v154
	v_min_f32_e32 v152, v152, v154
	v_max_f32_e32 v154, v181, v182
	v_min_f32_e32 v181, v181, v182
	v_max_f32_e32 v182, v183, v184
	v_min_f32_e32 v183, v183, v184
	v_max_f32_e32 v184, v141, v176
	v_min_f32_e32 v141, v141, v176
	v_max_f32_e32 v176, v174, v153
	v_min_f32_e32 v153, v174, v153
	v_max_f32_e32 v174, v179, v142
	v_min_f32_e32 v142, v179, v142
	v_max_f32_e32 v179, v152, v155
	v_min_f32_e32 v152, v152, v155
	v_max_f32_e32 v155, v175, v166
	v_min_f32_e32 v166, v175, v166
	v_max_f32_e32 v175, v180, v178
	v_min_f32_e32 v178, v180, v178
	v_max_f32_e32 v180, v154, v182
	v_min_f32_e32 v154, v154, v182
	v_max_f32_e32 v182, v181, v183
	v_min_f32_e32 v181, v181, v183
	v_max_f32_e32 v183, v184, v176
	v_min_f32_e32 v176, v184, v176
	v_max_f32_e32 v184, v141, v153
	v_min_f32_e32 v141, v141, v153
	v_max_f32_e32 v153, v152, v142
	v_min_f32_e32 v142, v152, v142
	v_max_f32_e32 v152, v179, v174
	v_min_f32_e32 v174, v179, v174
	v_max_f32_e32 v179, v178, v166
	v_min_f32_e32 v166, v178, v166
	v_max_f32_e32 v178, v175, v155
	v_min_f32_e32 v155, v175, v155
	v_max_f32_e32 v175, v180, v142
	v_min_f32_e32 v142, v180, v142
	v_max_f32_e32 v180, v154, v153
	v_min_f32_e32 v153, v154, v153
	v_max_f32_e32 v154, v182, v174
	v_min_f32_e32 v174, v182, v174
	v_max_f32_e32 v182, v181, v152
	v_min_f32_e32 v152, v181, v152
	v_max_f32_e32 v181, v183, v166
	v_min_f32_e32 v166, v183, v166
	v_max_f32_e32 v183, v176, v179
	v_min_f32_e32 v176, v176, v179
	v_max_f32_e32 v179, v184, v155
	v_min_f32_e32 v155, v184, v155
	v_max_f32_e32 v184, v141, v178
	v_min_f32_e32 v141, v141, v178
	v_max_f32_e32 v178, v175, v181
	v_min_f32_e32 v175, v175, v181
	v_max_f32_e32 v181, v180, v183
	v_min_f32_e32 v180, v180, v183
	v_max_f32_e32 v183, v154, v179
	v_min_f32_e32 v154, v154, v179
	v_max_f32_e32 v179, v182, v184
	v_min_f32_e32 v182, v182, v184
	v_and_b32_e32 v136, 0xffffff80, v136
	v_and_b32_e32 v137, 0xffffff80, v137
	v_and_or_b32 v151, v151, s87, 11
	v_max_f32_e32 v184, v142, v166
	v_min_f32_e32 v142, v142, v166
	v_max_f32_e32 v166, v153, v176
	v_min_f32_e32 v153, v153, v176
	v_max_f32_e32 v176, v174, v155
	v_min_f32_e32 v155, v174, v155
	v_max_f32_e32 v174, v152, v141
	v_min_f32_e32 v141, v152, v141
	v_max_f32_e32 v152, v178, v183
	v_min_f32_e32 v178, v178, v183
	v_max_f32_e32 v183, v181, v179
	v_min_f32_e32 v179, v181, v179
	v_max_f32_e32 v181, v175, v154
	v_min_f32_e32 v154, v175, v154
	v_max_f32_e32 v175, v180, v182
	v_and_b32_e32 v138, 0xffffff80, v138
	v_and_or_b32 v171, v171, s87, 5
	v_min_f32_e32 v180, v180, v182
	v_max_f32_e32 v182, v184, v176
	v_min_f32_e32 v176, v184, v176
	v_max_f32_e32 v184, v166, v174
	v_min_f32_e32 v166, v166, v174
	v_min_f32_e32 v186, v181, v175
	v_max3_f32 v151, v151, v181, v175
	v_add_f32_e32 v143, v143, v158
	v_add_f32_e32 v158, v136, v140
	v_add_f32_e32 v175, v136, v156
	v_add_f32_e32 v136, v136, v157
	v_add_f32_e32 v157, v137, v140
	v_add_f32_e32 v137, v137, v156
	v_and_b32_e32 v139, 0xffffff80, v139
	v_and_b32_e32 v132, 0xffffff80, v132
	v_and_b32_e32 v133, 0xffffff80, v133
	v_and_or_b32 v145, v145, s87, 13
	v_min_f32_e32 v189, v176, v166
	v_max3_f32 v166, v171, v176, v166
	v_and_or_b32 v143, v143, s87, 51
	v_and_or_b32 v158, v158, s87, 64
	v_and_b32_e32 v175, 0xffffff00, v175
	v_and_b32_e32 v136, 0xffffff00, v136
	v_and_b32_e32 v157, 0xffffff00, v157
	v_and_b32_e32 v137, 0xffffff00, v137
	v_add_f32_e32 v176, v138, v140
	v_add_f32_e32 v138, v138, v156
	v_and_b32_e32 v134, 0xffffff80, v134
	v_and_b32_e32 v135, 0xffffff80, v135
	v_min_f32_e32 v185, v178, v179
	v_max3_f32 v145, v145, v178, v179
	v_or_b32_e32 v175, 0x41, v175
	v_or_b32_e32 v136, 0x42, v136
	v_or_b32_e32 v157, 0x50, v157
	v_or_b32_e32 v137, 0x51, v137
	v_and_b32_e32 v176, 0xffffff00, v176
	v_and_b32_e32 v138, 0xffffff00, v138
	v_add_f32_e32 v178, v139, v140
	v_add_f32_e32 v139, v139, v156
	v_add_f32_e32 v132, v132, v140
	v_add_f32_e32 v133, v133, v140
	v_or_b32_e32 v176, 0x60, v176
	v_or_b32_e32 v138, 0x61, v138
	v_and_b32_e32 v178, 0xffffff00, v178
	v_and_b32_e32 v139, 0xffffff00, v139
	v_and_b32_e32 v132, 0xffffff00, v132
	v_and_b32_e32 v133, 0xffffff00, v133
	v_add_f32_e32 v134, v134, v140
	v_add_f32_e32 v135, v135, v140
	v_add_f32_e32 v156, v159, v140
	v_add_f32_e32 v159, v167, v140
	v_max_f32_e32 v167, v143, v158
	v_min_f32_e32 v143, v143, v158
	v_max_f32_e32 v158, v175, v175
	v_or_b32_e32 v178, 0x70, v178
	v_or_b32_e32 v139, 0x71, v139
	v_or_b32_e32 v132, 0x80, v132
	v_or_b32_e32 v133, 0x90, v133
	v_and_b32_e32 v134, 0xffffff00, v134
	v_and_b32_e32 v135, 0xffffff00, v135
	v_max_f32_e32 v175, v136, v158
	v_min_f32_e32 v136, v136, v158
	v_max_f32_e32 v158, v157, v137
	v_min_f32_e32 v137, v157, v137
	v_max_f32_e32 v157, v176, v176
	v_or_b32_e32 v134, 0xa0, v134
	v_or_b32_e32 v135, 0xb0, v135
	v_and_b32_e32 v156, 0xffffff00, v156
	v_and_b32_e32 v159, 0xffffff00, v159
; DI void gemm256_tile(const Params& p, int mode, int layer, const u16* R, const u16* Cc, int brow, int bcol, lchar* shm, int tid_in, int wid) {
;     ...
;       for (int ch = 0; ch < 4; ++ch) {
;         float wk[16];
; #pragma unroll
;         for (int i = 0; i < 16; ++i) {
;           constexpr unsigned char PAIRS[64] = {0, 1, 2, 3, 4, 5, 6, 7, 8, 9, 10, 11, 12, 13, 14, 15, 16, 17, 18, 19, 20, 21, 22, 23, 32, 33, 34, 35, 36, 48, 49, 50, 51, 64, 65, 66, 80, 81, 96, 97, 112, 113, 128, 144, 160, 176, 192, 208, 224, 240, 255, 255, 255, 255, 255, 255, 255, 255, 255, 255, 255, 255, 255, 255};
;           const int code = PAIRS[ch * 16 + i];
;           if (code == 255) { wk[i] = -3.0e38f; }
;           else { const float sm = s1[code >> 4] + s2[code & 15]; wk[i] = __uint_as_float((__float_as_uint(sm) & ~255u) | (unsigned)code); }
;         }
;         if (ch == 0) {
; #pragma unroll
;           for (int i = 0; i < 16; ++i) v[i] = wk[i];
;         } else {
;           bitonic_sort16(wk);
;           merge_top16(v, wk);
;         }
	v_max_f32_e32 v176, v138, v157
	v_min_f32_e32 v138, v138, v157
	v_max_f32_e32 v157, v178, v178
	v_or_b32_e32 v156, 0xc0, v156
	v_or_b32_e32 v159, 0xd0, v159
	v_max_f32_e32 v178, v157, v139
	v_min_f32_e32 v139, v157, v139
	v_max_f32_e32 v157, v133, v132
	v_min_f32_e32 v132, v133, v132
	v_max_f32_e32 v133, v135, v135
	v_max_f32_e32 v135, v134, v133
	v_min_f32_e32 v133, v134, v133
	v_max_f32_e32 v134, v156, v156
	v_max_f32_e32 v156, v159, v159
	v_max_f32_e32 v159, v156, v134
	v_min_f32_e32 v134, v156, v134
	v_max_f32_e32 v156, v167, v136
	v_min_f32_e32 v136, v167, v136
	v_max_f32_e32 v167, v143, v175
	v_min_f32_e32 v143, v143, v175
	v_max_f32_e32 v175, v138, v158
	v_min_f32_e32 v138, v138, v158
	v_max_f32_e32 v158, v176, v137
	v_min_f32_e32 v137, v176, v137
	v_max_f32_e32 v176, v178, v132
	v_min_f32_e32 v132, v178, v132
	v_max_f32_e32 v178, v139, v157
	v_min_f32_e32 v139, v139, v157
	v_max_f32_e32 v157, v134, v135
	v_min_f32_e32 v134, v134, v135
	v_max_f32_e32 v135, v159, v133
	v_min_f32_e32 v133, v159, v133
	v_max_f32_e32 v159, v156, v167
	v_min_f32_e32 v156, v156, v167
	v_max_f32_e32 v167, v136, v143
	v_min_f32_e32 v136, v136, v143
	v_max_f32_e32 v143, v137, v138
	v_min_f32_e32 v137, v137, v138
	v_max_f32_e32 v138, v158, v175
	v_min_f32_e32 v158, v158, v175
	v_max_f32_e32 v175, v176, v178
	v_min_f32_e32 v176, v176, v178
	v_max_f32_e32 v178, v132, v139
	v_min_f32_e32 v132, v132, v139
	v_max_f32_e32 v139, v133, v134
	v_min_f32_e32 v133, v133, v134
	v_max_f32_e32 v134, v135, v157
	v_min_f32_e32 v135, v135, v157
	v_and_b32_e32 v146, 0xffffff00, v146
	v_and_or_b32 v147, v147, s87, 1
	v_and_or_b32 v168, v168, s87, 2
	v_and_or_b32 v169, v169, s87, 3
	v_and_or_b32 v170, v170, s87, 4
	v_and_or_b32 v172, v172, s87, 6
	v_and_or_b32 v148, v148, s87, 8
	v_and_or_b32 v150, v150, s87, 10
	v_and_or_b32 v144, v144, s87, 12
	v_and_or_b32 v130, v130, s87, 14
	v_max_f32_e32 v174, v142, v155
	v_min_f32_e32 v142, v142, v155
	v_max_f32_e32 v155, v153, v141
	v_min_f32_e32 v141, v153, v141
	v_max_f32_e32 v157, v159, v137
	v_min_f32_e32 v137, v159, v137
	v_max_f32_e32 v159, v156, v143
	v_min_f32_e32 v143, v156, v143
	v_max_f32_e32 v156, v167, v158
	v_min_f32_e32 v158, v167, v158
	v_max_f32_e32 v167, v136, v138
	v_min_f32_e32 v136, v136, v138
	v_max_f32_e32 v138, v133, v175
	v_min_f32_e32 v133, v133, v175
	v_max_f32_e32 v175, v139, v176
	v_min_f32_e32 v139, v139, v176
	v_max_f32_e32 v176, v135, v178
	v_min_f32_e32 v135, v135, v178
	v_max_f32_e32 v178, v134, v132
	v_min_f32_e32 v132, v134, v132
	v_and_or_b32 v173, v173, s87, 7
	v_and_or_b32 v149, v149, s87, 9
	v_and_or_b32 v131, v131, s87, 15
	v_min_f32_e32 v153, v152, v183
	v_min_f32_e32 v187, v154, v180
	v_min_f32_e32 v188, v182, v184
	v_min_f32_e32 v190, v174, v155
	v_min_f32_e32 v191, v142, v141
	v_max3_f32 v141, v147, v142, v141
	v_max_f32_e32 v142, v168, v168
	v_max3_f32 v147, v169, v174, v155
	v_max_f32_e32 v155, v170, v170
	v_max_f32_e32 v168, v172, v172
	v_max_f32_e32 v134, v157, v156
	v_min_f32_e32 v156, v157, v156
	v_max_f32_e32 v157, v159, v167
	v_min_f32_e32 v159, v159, v167
	v_max_f32_e32 v167, v137, v158
	v_min_f32_e32 v137, v137, v158
	v_max_f32_e32 v158, v143, v136
	v_min_f32_e32 v136, v143, v136
	v_max_f32_e32 v143, v135, v133
	v_min_f32_e32 v133, v135, v133
	v_max_f32_e32 v135, v132, v139
	v_min_f32_e32 v132, v132, v139
	v_max_f32_e32 v139, v176, v138
	v_min_f32_e32 v138, v176, v138
	v_max_f32_e32 v176, v178, v175
	v_min_f32_e32 v175, v178, v175
	v_max_f32_e32 v146, v146, v191
	v_max_f32_e32 v142, v142, v190
	v_max_f32_e32 v155, v155, v189
	v_max_f32_e32 v168, v168, v188
	v_max3_f32 v169, v173, v182, v184
	v_max_f32_e32 v148, v148, v187
	v_max3_f32 v149, v149, v154, v180
	v_max_f32_e32 v150, v150, v186
	v_max_f32_e32 v144, v144, v185
	v_max_f32_e32 v130, v130, v153
	v_max3_f32 v131, v131, v152, v183
	v_max_f32_e32 v178, v134, v157
	v_min_f32_e32 v134, v134, v157
	v_max_f32_e32 v157, v156, v159
	v_min_f32_e32 v156, v156, v159
	v_max_f32_e32 v159, v167, v158
	v_min_f32_e32 v158, v167, v158
	v_max_f32_e32 v167, v137, v136
	v_min_f32_e32 v136, v137, v136
	v_max_f32_e32 v137, v132, v133
	v_min_f32_e32 v132, v132, v133
	v_max_f32_e32 v133, v135, v143
	v_min_f32_e32 v135, v135, v143
	v_max_f32_e32 v143, v175, v138
	v_min_f32_e32 v138, v175, v138
	v_max_f32_e32 v175, v176, v139
	v_min_f32_e32 v139, v176, v139
	v_add_f32_e32 v129, v129, v140
	v_add_f32_e32 v128, v128, v140
	v_max_f32_e32 v152, v146, v148
	v_min_f32_e32 v146, v146, v148
	v_max_f32_e32 v148, v141, v149
	v_min_f32_e32 v141, v141, v149
	v_max_f32_e32 v149, v142, v150
	v_min_f32_e32 v142, v142, v150
	v_max_f32_e32 v150, v147, v151
	v_min_f32_e32 v147, v147, v151
	v_max_f32_e32 v151, v155, v144
	v_min_f32_e32 v144, v155, v144
	v_max_f32_e32 v153, v166, v145
	v_max_f32_e32 v154, v168, v130
	v_max_f32_e32 v155, v169, v131
	v_max_f32_e32 v176, v178, v132
	v_min_f32_e32 v132, v178, v132
	v_max_f32_e32 v178, v134, v137
	v_min_f32_e32 v134, v134, v137
	v_max_f32_e32 v137, v157, v135
	v_min_f32_e32 v135, v157, v135
	v_max_f32_e32 v157, v156, v133
	v_min_f32_e32 v133, v156, v133
	v_max_f32_e32 v156, v159, v138
	v_min_f32_e32 v138, v159, v138
	v_max_f32_e32 v159, v158, v143
	v_min_f32_e32 v143, v158, v143
	v_max_f32_e32 v158, v167, v139
	v_min_f32_e32 v139, v167, v139
	v_max_f32_e32 v167, v136, v175
	v_min_f32_e32 v136, v136, v175
	v_and_b32_e32 v129, 0xffffff00, v129
	v_and_b32_e32 v128, 0xffffff00, v128
	v_min_f32_e32 v145, v166, v145
	v_min_f32_e32 v130, v168, v130
	v_min_f32_e32 v131, v169, v131
	v_max_f32_e32 v166, v152, v151
	v_min_f32_e32 v151, v152, v151
	v_max_f32_e32 v152, v148, v153
	v_min_f32_e32 v148, v148, v153
	v_max_f32_e32 v153, v149, v154
; DI void gemm256_tile(const Params& p, int mode, int layer, const u16* R, const u16* Cc, int brow, int bcol, lchar* shm, int tid_in, int wid) {
;     ...
;       for (int ch = 0; ch < 4; ++ch) {
;         float wk[16];
; #pragma unroll
;         for (int i = 0; i < 16; ++i) {
;           constexpr unsigned char PAIRS[64] = {0, 1, 2, 3, 4, 5, 6, 7, 8, 9, 10, 11, 12, 13, 14, 15, 16, 17, 18, 19, 20, 21, 22, 23, 32, 33, 34, 35, 36, 48, 49, 50, 51, 64, 65, 66, 80, 81, 96, 97, 112, 113, 128, 144, 160, 176, 192, 208, 224, 240, 255, 255, 255, 255, 255, 255, 255, 255, 255, 255, 255, 255, 255, 255};
;           const int code = PAIRS[ch * 16 + i];
;           if (code == 255) { wk[i] = -3.0e38f; }
;           else { const float sm = s1[code >> 4] + s2[code & 15]; wk[i] = __uint_as_float((__float_as_uint(sm) & ~255u) | (unsigned)code); }
;         }
;         if (ch == 0) {
; #pragma unroll
;           for (int i = 0; i < 16; ++i) v[i] = wk[i];
;         } else {
;           bitonic_sort16(wk);
;           merge_top16(v, wk);
;         }
	v_min_f32_e32 v149, v149, v154
	v_max_f32_e32 v154, v150, v155
	v_max_f32_e32 v175, v176, v156
	v_min_f32_e32 v156, v176, v156
	v_max_f32_e32 v176, v178, v159
	v_min_f32_e32 v159, v178, v159
	v_max_f32_e32 v178, v137, v158
	v_min_f32_e32 v137, v137, v158
	v_max_f32_e32 v158, v157, v167
	v_min_f32_e32 v157, v157, v167
	v_max_f32_e32 v167, v132, v138
	v_min_f32_e32 v132, v132, v138
	v_max_f32_e32 v138, v134, v143
	v_min_f32_e32 v134, v134, v143
	v_max_f32_e32 v143, v135, v139
	v_min_f32_e32 v135, v135, v139
	v_max_f32_e32 v139, v133, v136
	v_or_b32_e32 v129, 0xe0, v129
	v_or_b32_e32 v128, 0xf0, v128
	v_min_f32_e32 v150, v150, v155
	v_max_f32_e32 v155, v146, v144
	v_min_f32_e32 v144, v146, v144
	v_max_f32_e32 v146, v141, v145
	v_min_f32_e32 v141, v141, v145
	v_max_f32_e32 v145, v142, v130
	v_min_f32_e32 v130, v142, v130
	v_max_f32_e32 v142, v147, v131
	v_min_f32_e32 v131, v147, v131
	v_max_f32_e32 v147, v166, v153
	v_min_f32_e32 v153, v166, v153
	v_max_f32_e32 v166, v152, v154
	v_min_f32_e32 v133, v133, v136
	v_max_f32_e32 v136, v175, v178
	v_min_f32_e32 v175, v175, v178
	v_max_f32_e32 v178, v176, v158
	v_min_f32_e32 v158, v176, v158
	v_max_f32_e32 v176, v156, v137
	v_min_f32_e32 v137, v156, v137
	v_max_f32_e32 v156, v159, v157
	v_min_f32_e32 v157, v159, v157
	v_max_f32_e32 v159, v167, v143
	v_min_f32_e32 v143, v167, v143
	v_max_f32_e32 v167, v138, v139
	v_min_f32_e32 v152, v152, v154
	v_max_f32_e32 v154, v151, v149
	v_min_f32_e32 v149, v151, v149
	v_max_f32_e32 v151, v148, v150
	v_min_f32_e32 v148, v148, v150
	v_max_f32_e32 v150, v155, v145
	v_min_f32_e32 v145, v155, v145
	v_max_f32_e32 v155, v146, v142
	v_min_f32_e32 v142, v146, v142
	v_max_f32_e32 v146, v144, v130
	v_min_f32_e32 v130, v144, v130
	v_max_f32_e32 v144, v141, v131
	v_min_f32_e32 v131, v141, v131
	v_min_f32_e32 v141, v147, v166
	v_min_f32_e32 v138, v138, v139
	v_max_f32_e32 v139, v132, v135
	v_min_f32_e32 v132, v132, v135
	v_max_f32_e32 v135, v134, v133
	v_min_f32_e32 v133, v134, v133
	v_min_f32_e32 v181, v137, v157
	v_min_f32_e32 v182, v159, v167
	v_max_f32_e32 v140, v129, v128
	v_min_f32_e32 v128, v129, v128
	v_min_f32_e32 v170, v149, v148
	v_min_f32_e32 v171, v150, v155
	v_min_f32_e32 v172, v145, v142
	v_min_f32_e32 v173, v146, v144
	v_min_f32_e32 v179, v175, v158
	v_min_f32_e32 v180, v176, v156
	v_min_f32_e32 v185, v132, v133
	v_max3_f32 v132, v141, v132, v133
	v_max3_f32 v141, v149, v148, v182
	v_max3_f32 v148, v150, v155, v181
	v_max_f32_e32 v155, 0xff61b1e6, v140
	v_max_f32_e32 v129, 0xff61b1e6, v128
	v_min_f32_e32 v140, 0xff61b1e6, v140
	v_min_f32_e32 v128, 0xff61b1e6, v128
	v_min_f32_e32 v169, v154, v151
	v_max3_f32 v142, v145, v142, v180
	v_max3_f32 v145, v172, v176, v156
	v_max3_f32 v144, v146, v144, v179
	v_max3_f32 v146, v173, v175, v158
	v_max_f32_e32 v156, v155, v129
	v_max_f32_e32 v158, v140, v128
	v_min_f32_e32 v129, v155, v129
	v_min_f32_e32 v128, v140, v128
	v_min_f32_e32 v183, v143, v138
	v_max3_f32 v138, v169, v143, v138
	v_max3_f32 v143, v170, v159, v167
	v_max3_f32 v137, v171, v137, v157
	v_max_f32_e32 v157, 0xff61b1e6, v156
	v_max_f32_e32 v159, 0xff61b1e6, v158
	v_max_f32_e32 v155, 0xff61b1e6, v129
	v_max_f32_e32 v140, 0xff61b1e6, v128
	v_min_f32_e32 v156, 0xff61b1e6, v156
	v_min_f32_e32 v158, 0xff61b1e6, v158
	v_min_f32_e32 v129, 0xff61b1e6, v129
	v_min_f32_e32 v128, 0xff61b1e6, v128
	v_min_f32_e32 v168, v153, v152
	v_max3_f32 v147, v147, v166, v185
	v_max_f32_e32 v166, v157, v159
	v_max_f32_e32 v167, v155, v140
	v_max_f32_e32 v170, v156, v158
	v_max_f32_e32 v171, v129, v128
	v_min_f32_e32 v157, v157, v159
	v_min_f32_e32 v140, v155, v140
	v_min_f32_e32 v156, v156, v158
	v_min_f32_e32 v128, v129, v128
	v_min_f32_e32 v174, v130, v131
	v_min_f32_e32 v134, v136, v178
	v_min_f32_e32 v184, v139, v135
	v_max3_f32 v135, v168, v139, v135
	v_max_f32_e32 v168, v166, v167
	v_max_f32_e32 v172, v170, v171
	v_max_f32_e32 v155, v157, v140
	v_max_f32_e32 v129, v156, v128
	v_min_f32_e32 v166, v166, v167
	v_min_f32_e32 v170, v170, v171
	v_min_f32_e32 v140, v157, v140
	v_min_f32_e32 v128, v156, v128
	v_max3_f32 v133, v153, v152, v184
	v_max3_f32 v139, v154, v151, v183
	v_max3_f32 v130, v130, v131, v134
	v_max3_f32 v131, v174, v136, v178
	v_min_f32_e32 v169, 0xff61b1e6, v168
	v_min_f32_e32 v173, 0xff61b1e6, v172
	v_min_f32_e32 v159, 0xff61b1e6, v155
	v_min_f32_e32 v158, 0xff61b1e6, v129
	v_min_f32_e32 v167, 0xff61b1e6, v166
	v_min_f32_e32 v171, 0xff61b1e6, v170
	v_min_f32_e32 v157, 0xff61b1e6, v140
	v_min_f32_e32 v156, 0xff61b1e6, v128
	v_max_f32_e32 v134, v147, v148
	v_min_f32_e32 v136, v147, v148
	v_max_f32_e32 v147, v132, v137
	v_min_f32_e32 v132, v132, v137
	v_max_f32_e32 v137, v133, v142
	v_min_f32_e32 v133, v133, v142
	v_max_f32_e32 v142, v135, v145
	v_min_f32_e32 v135, v135, v145
	v_max_f32_e32 v145, v139, v144
	v_min_f32_e32 v139, v139, v144
	v_max_f32_e32 v144, v138, v146
	v_min_f32_e32 v138, v138, v146
	v_max_f32_e32 v146, v141, v130
	v_min_f32_e32 v130, v141, v130
	v_max_f32_e32 v141, v143, v131
	v_min_f32_e32 v174, v169, v173
	v_min_f32_e32 v175, v159, v158
	v_min_f32_e32 v178, v167, v171
	v_min_f32_e32 v179, v157, v156
	v_min_f32_e32 v131, v143, v131
	v_max_f32_e32 v143, v134, v145
	v_min_f32_e32 v134, v134, v145
	v_max_f32_e32 v145, v147, v144
	v_min_f32_e32 v144, v147, v144
	v_max_f32_e32 v147, v137, v146
	v_min_f32_e32 v137, v137, v146
	v_max_f32_e32 v146, v142, v141
	v_min_f32_e32 v176, v174, v175
	v_min_f32_e32 v180, v178, v179
	v_max_f32_e32 v169, v169, v173
	v_max_f32_e32 v158, v159, v158
	v_max_f32_e32 v167, v167, v171
	v_max_f32_e32 v156, v157, v156
	v_min_f32_e32 v141, v142, v141
	v_max_f32_e32 v142, v136, v139
	v_min_f32_e32 v136, v136, v139
; DI float fast_exp2(float x) { return __builtin_amdgcn_exp2f(x); }
; DI void gemm256_tile(const Params& p, int mode, int layer, const u16* R, const u16* Cc, int brow, int bcol, lchar* shm, int tid_in, int wid) {
;     ...
;           bitonic_sort16(wk);
;           merge_top16(v, wk);
;         }
;       }
;       float e[16], sum = 0.f;
;       const float mx = __uint_as_float(__float_as_uint(v[0]) & ~255u);
; #pragma unroll
;       for (int j = 0; j < 16; ++j) { e[j] = fast_exp2((__uint_as_float(__float_as_uint(v[j]) & ~255u) - mx) * LOG2E); sum += e[j]; }
	v_max_f32_e32 v139, v132, v138
	v_min_f32_e32 v132, v132, v138
	v_max_f32_e32 v138, v133, v130
	v_min_f32_e32 v130, v133, v130
	v_max_f32_e32 v133, v135, v131
	v_min_f32_e32 v131, v135, v131
	v_max_f32_e32 v135, v143, v147
	v_min_f32_e32 v143, v143, v147
	v_max_f32_e32 v147, v145, v146
	v_min_f32_e32 v181, v176, v180
	v_min_f32_e32 v159, v169, v158
	v_min_f32_e32 v157, v167, v156
	v_min_f32_e32 v145, v145, v146
	v_max_f32_e32 v146, v134, v137
	v_min_f32_e32 v134, v134, v137
	v_max_f32_e32 v137, v144, v141
	v_min_f32_e32 v141, v144, v141
	v_max_f32_e32 v144, v142, v138
	v_min_f32_e32 v138, v142, v138
	v_max_f32_e32 v142, v139, v133
	v_min_f32_e32 v133, v139, v133
	v_max_f32_e32 v139, v136, v130
	v_min_f32_e32 v130, v136, v130
	v_max_f32_e32 v136, v132, v131
	v_min_f32_e32 v131, v132, v131
	v_min_f32_e32 v132, v135, v147
	v_max3_f32 v135, v135, v147, v181
	v_max_f32_e32 v147, 0xff61b1e6, v168
	v_max_f32_e32 v168, 0xff61b1e6, v172
	v_max_f32_e32 v155, 0xff61b1e6, v155
	v_max_f32_e32 v129, 0xff61b1e6, v129
	v_max_f32_e32 v166, 0xff61b1e6, v166
	v_max_f32_e32 v170, 0xff61b1e6, v170
	v_min_f32_e32 v171, v159, v157
	v_min_f32_e32 v149, v146, v137
	v_min_f32_e32 v172, v147, v168
	v_min_f32_e32 v181, v155, v129
	v_min_f32_e32 v183, v166, v170
	v_max_f32_e32 v140, 0xff61b1e6, v140
	v_max_f32_e32 v128, 0xff61b1e6, v128
	v_max3_f32 v137, v146, v137, v171
	v_max_f32_e32 v146, v147, v168
	v_max_f32_e32 v129, v155, v129
	v_max_f32_e32 v155, v166, v170
	v_max_f32_e32 v168, v174, v175
	v_max_f32_e32 v170, v178, v179
	v_min_f32_e32 v184, v140, v128
	v_max_f32_e32 v128, v140, v128
	v_min_f32_e32 v171, v168, v170
	v_max_f32_e32 v158, v169, v158
	v_max_f32_e32 v156, v167, v156
	v_min_f32_e32 v148, v143, v145
	v_min_f32_e32 v182, v172, v181
	v_min_f32_e32 v185, v183, v184
	v_min_f32_e32 v147, v146, v129
	v_min_f32_e32 v140, v155, v128
	v_max3_f32 v143, v143, v145, v171
	v_max_f32_e32 v145, v172, v181
	v_max_f32_e32 v171, v183, v184
	v_min_f32_e32 v167, v158, v156
	v_max_f32_e32 v129, v146, v129
	v_max_f32_e32 v128, v155, v128
	v_min_f32_e32 v150, v134, v141
	v_min_f32_e32 v151, v144, v142
	v_min_f32_e32 v152, v138, v133
	v_min_f32_e32 v153, v139, v136
	v_min_f32_e32 v154, v130, v131
	v_min_f32_e32 v186, v182, v185
	v_min_f32_e32 v166, v147, v140
	v_min_f32_e32 v172, v145, v171
	v_max3_f32 v134, v134, v141, v167
	v_min_f32_e32 v141, v129, v128
	v_max3_f32 v142, v144, v142, v186
	v_max3_f32 v136, v139, v136, v166
	v_max3_f32 v133, v138, v133, v172
	v_max3_f32 v130, v130, v131, v141
	v_max3_f32 v132, v132, v176, v180
	v_max3_f32 v151, v151, v182, v185
	v_max3_f32 v149, v149, v159, v157
	v_max3_f32 v140, v153, v147, v140
	v_max3_f32 v148, v148, v168, v170
	v_max3_f32 v145, v152, v145, v171
	v_max3_f32 v150, v150, v158, v156
	v_max3_f32 v128, v154, v129, v128
	v_min_f32_e32 v144, v135, v142
	v_min_f32_e32 v139, v137, v136
	v_min_f32_e32 v138, v143, v133
	v_min_f32_e32 v131, v134, v130
	v_min_f32_e32 v155, v132, v151
	v_min_f32_e32 v147, v149, v140
	v_min_f32_e32 v152, v148, v145
	v_min_f32_e32 v129, v150, v128
	v_min_f32_e32 v166, v144, v139
	v_min_f32_e32 v141, v138, v131
	v_min_f32_e32 v153, v155, v147
	v_min_f32_e32 v154, v152, v129
	v_min_f32_e32 v146, v166, v141
	v_min_f32_e32 v156, v153, v154
	v_min_f32_e32 v157, v146, v156
	v_max_f32_e32 v156, v146, v156
	v_max_f32_e32 v141, v166, v141
	v_max_f32_e32 v146, v153, v154
	v_min_f32_e32 v153, v141, v146
	v_max_f32_e32 v154, v141, v146
	v_max_f32_e32 v139, v144, v139
	v_max_f32_e32 v131, v138, v131
	v_max_f32_e32 v141, v155, v147
	v_max_f32_e32 v129, v152, v129
	v_min_f32_e32 v138, v139, v131
	v_min_f32_e32 v144, v141, v129
	v_max_f32_e32 v131, v139, v131
	v_max_f32_e32 v129, v141, v129
	v_min_f32_e32 v158, v131, v129
	v_max_f32_e32 v159, v131, v129
	v_max_f32_e32 v129, v135, v142
	v_max_f32_e32 v131, v137, v136
	v_max_f32_e32 v133, v143, v133
	v_max_f32_e32 v130, v134, v130
	v_max_f32_e32 v132, v132, v151
	v_max_f32_e32 v137, v149, v140
	v_max_f32_e32 v139, v148, v145
	v_max_f32_e32 v128, v150, v128
	v_min_f32_e32 v152, v138, v144
	v_max_f32_e32 v155, v138, v144
	v_min_f32_e32 v135, v129, v131
	v_min_f32_e32 v134, v133, v130
	v_min_f32_e32 v138, v132, v137
	v_min_f32_e32 v140, v139, v128
	v_max_f32_e32 v129, v129, v131
	v_max_f32_e32 v130, v133, v130
	v_max_f32_e32 v132, v132, v137
	v_max_f32_e32 v128, v139, v128
	v_min_f32_e32 v131, v129, v130
	v_min_f32_e32 v133, v132, v128
	v_max_f32_e32 v129, v129, v130
	v_max_f32_e32 v128, v132, v128
	v_max_f32_e32 v169, v129, v128
	v_max_f32_e32 v167, v131, v133
	v_min_f32_e32 v168, v129, v128
	v_and_b32_e32 v145, 0xffffff00, v169
	v_and_b32_e32 v129, 0xffffff00, v168
	v_and_b32_e32 v130, 0xffffff00, v167
	v_sub_f32_e32 v128, v145, v145
	v_min_f32_e32 v166, v131, v133
	v_mul_f32_e32 v128, 0x3fb8aa3b, v128
	v_sub_f32_e32 v129, v129, v145
	v_sub_f32_e32 v130, v130, v145
	v_and_b32_e32 v131, 0xffffff00, v166
	v_exp_f32_e32 v128, v128
	v_mul_f32_e32 v129, 0x3fb8aa3b, v129
	v_mul_f32_e32 v130, 0x3fb8aa3b, v130
	v_exp_f32_e32 v129, v129
	v_exp_f32_e32 v132, v130
	v_sub_f32_e32 v130, v131, v145
	v_mul_f32_e32 v130, 0x3fb8aa3b, v130
	v_exp_f32_e32 v133, v130
	v_min_f32_e32 v136, v135, v134
	v_max_f32_e32 v134, v135, v134
	v_max_f32_e32 v135, v138, v140
	v_add_f32_e32 v130, 0, v128
	v_min_f32_e32 v141, v138, v140
	v_max_f32_e32 v151, v134, v135
	v_add_f32_e32 v130, v129, v130
	v_max_f32_e32 v149, v136, v141
	v_min_f32_e32 v150, v134, v135
	v_and_b32_e32 v134, 0xffffff00, v151
	v_add_f32_e32 v130, v132, v130
	v_min_f32_e32 v148, v136, v141
	v_and_b32_e32 v135, 0xffffff00, v150
	v_and_b32_e32 v136, 0xffffff00, v149
	v_add_f32_e32 v147, v133, v130
	v_sub_f32_e32 v130, v134, v145
; DI float fast_exp2(float x) { return __builtin_amdgcn_exp2f(x); }
; DI void gemm256_tile(const Params& p, int mode, int layer, const u16* R, const u16* Cc, int brow, int bcol, lchar* shm, int tid_in, int wid) {
;     ...
;       for (int j = 0; j < 16; ++j) { e[j] = fast_exp2((__uint_as_float(__float_as_uint(v[j]) & ~255u) - mx) * LOG2E); sum += e[j]; }
;       const float inv = 1.0f / sum;
;       const int hd = brow >> 8;
;       u16* di = W_IDX(p) + (size_t)(bcol + tok) * 128 + hd * 16;
;       float* dg = W_G(p) + (size_t)(bcol + tok) * 128 + hd * 16;
;       unsigned eid[16];
; #pragma unroll
;       for (int k = 0; k < 16; ++k) {
;         const unsigned code = __float_as_uint(v[k]) & 255u;
;         const unsigned i1 = LL[tok * 32 + (((code >> 4) + tok) & 31)] & 127u, i2 = LL[tok * 32 + ((16 + (code & 15u) + tok) & 31)] & 127u;
;         eid[k] = i1 * 128u + i2;
	v_mul_f32_e32 v130, 0x3fb8aa3b, v130
	v_sub_f32_e32 v131, v135, v145
	v_sub_f32_e32 v134, v136, v145
	v_and_b32_e32 v137, 0xffffff00, v148
	v_exp_f32_e32 v130, v130
	v_mul_f32_e32 v131, 0x3fb8aa3b, v131
	v_mul_f32_e32 v134, 0x3fb8aa3b, v134
	v_exp_f32_e32 v131, v131
	v_exp_f32_e32 v136, v134
	v_sub_f32_e32 v134, v137, v145
	v_mul_f32_e32 v134, 0x3fb8aa3b, v134
	v_exp_f32_e32 v137, v134
	v_add_f32_e32 v134, v130, v147
	v_add_f32_e32 v134, v131, v134
	v_and_b32_e32 v138, 0xffffff00, v159
	v_add_f32_e32 v134, v136, v134
	v_and_b32_e32 v139, 0xffffff00, v158
	v_and_b32_e32 v140, 0xffffff00, v155
	v_add_f32_e32 v147, v137, v134
	v_sub_f32_e32 v134, v138, v145
	v_mul_f32_e32 v134, 0x3fb8aa3b, v134
	v_sub_f32_e32 v135, v139, v145
	v_sub_f32_e32 v138, v140, v145
	v_and_b32_e32 v141, 0xffffff00, v152
	v_exp_f32_e32 v134, v134
	v_mul_f32_e32 v135, 0x3fb8aa3b, v135
	v_mul_f32_e32 v138, 0x3fb8aa3b, v138
	v_exp_f32_e32 v135, v135
	v_exp_f32_e32 v140, v138
	v_sub_f32_e32 v138, v141, v145
	v_mul_f32_e32 v138, 0x3fb8aa3b, v138
	v_exp_f32_e32 v141, v138
	v_add_f32_e32 v138, v134, v147
	v_add_f32_e32 v138, v135, v138
	v_and_b32_e32 v142, 0xffffff00, v154
	v_add_f32_e32 v138, v140, v138
	v_and_b32_e32 v143, 0xffffff00, v153
	v_add_f32_e32 v147, v141, v138
	v_sub_f32_e32 v138, v142, v145
	v_and_b32_e32 v144, 0xffffff00, v156
	v_mul_f32_e32 v138, 0x3fb8aa3b, v138
	v_sub_f32_e32 v139, v143, v145
	v_and_b32_e32 v146, 0xffffff00, v157
	v_exp_f32_e32 v138, v138
	v_mul_f32_e32 v139, 0x3fb8aa3b, v139
	v_sub_f32_e32 v142, v144, v145
	v_exp_f32_e32 v139, v139
	v_mul_f32_e32 v142, 0x3fb8aa3b, v142
	v_sub_f32_e32 v143, v146, v145
	v_exp_f32_e32 v142, v142
	v_mul_f32_e32 v143, 0x3fb8aa3b, v143
	v_exp_f32_e32 v143, v143
	v_add_f32_e32 v144, v138, v147
	v_add_f32_e32 v144, v139, v144
	v_add_f32_e32 v144, v142, v144
	v_add_f32_e32 v170, v143, v144
	v_or_b32_e32 v144, s78, v164
	v_bfe_u32 v164, v169, 4, 4
	v_or_b32_e32 v169, 16, v169
	v_bfe_u32 v171, v168, 4, 4
	v_or_b32_e32 v168, 16, v168
	v_bfe_u32 v172, v167, 4, 4
	v_or_b32_e32 v167, 16, v167
	v_bfe_u32 v173, v166, 4, 4
	v_or_b32_e32 v166, 16, v166
	v_add_u32_e32 v164, v164, v163
	v_add_u32_e32 v169, v169, v163
	v_add_u32_e32 v171, v171, v163
	v_add_u32_e32 v168, v168, v163
	v_add_u32_e32 v172, v172, v163
	v_add_u32_e32 v167, v167, v163
	v_add_u32_e32 v173, v173, v163
	v_add_u32_e32 v166, v166, v163
	v_and_b32_e32 v164, 31, v164
	v_and_b32_e32 v169, 31, v169
	v_and_b32_e32 v171, 31, v171
	v_and_b32_e32 v168, 31, v168
	v_and_b32_e32 v172, 31, v172
	v_and_b32_e32 v167, 31, v167
	v_and_b32_e32 v173, 31, v173
	v_and_b32_e32 v166, 31, v166
	v_lshl_add_u32 v164, v164, 2, v165
	v_lshl_add_u32 v169, v169, 2, v165
	v_lshl_add_u32 v171, v171, 2, v165
	v_lshl_add_u32 v168, v168, 2, v165
	v_lshl_add_u32 v172, v172, 2, v165
	v_lshl_add_u32 v167, v167, 2, v165
	v_lshl_add_u32 v173, v173, 2, v165
	v_lshl_add_u32 v166, v166, 2, v165
	ds_read_b32 v164, v164
	ds_read_b32 v169, v169
	ds_read_b32 v171, v171
	ds_read_b32 v168, v168
	ds_read_b32 v172, v172
	ds_read_b32 v167, v167
	ds_read_b32 v173, v173
	ds_read_b32 v166, v166
	s_waitcnt lgkmcnt(6)
	v_and_b32_e32 v169, 0x7f, v169
	v_lshlrev_b32_e32 v164, 7, v164
	v_and_or_b32 v164, v164, s40, v169
	s_waitcnt lgkmcnt(4)
	v_and_b32_e32 v168, 0x7f, v168
	v_lshlrev_b32_e32 v169, 7, v171
	v_and_or_b32 v168, v169, s40, v168
	s_waitcnt lgkmcnt(2)
	v_and_b32_e32 v167, 0x7f, v167
	v_lshlrev_b32_e32 v169, 7, v172
	v_and_or_b32 v167, v169, s40, v167
	s_waitcnt lgkmcnt(0)
	v_and_b32_e32 v166, 0x7f, v166
	v_lshlrev_b32_e32 v169, 7, v173
	v_and_or_b32 v166, v169, s40, v166
	v_bfe_u32 v169, v151, 4, 4
	v_or_b32_e32 v151, 16, v151
	v_bfe_u32 v171, v150, 4, 4
	v_or_b32_e32 v150, 16, v150
	v_bfe_u32 v172, v149, 4, 4
	v_or_b32_e32 v149, 16, v149
	v_bfe_u32 v173, v148, 4, 4
	v_or_b32_e32 v148, 16, v148
	v_add_u32_e32 v169, v169, v163
	v_add_u32_e32 v151, v151, v163
	v_add_u32_e32 v171, v171, v163
	v_add_u32_e32 v150, v150, v163
	v_add_u32_e32 v172, v172, v163
	v_add_u32_e32 v149, v149, v163
	v_add_u32_e32 v173, v173, v163
	v_add_u32_e32 v148, v148, v163
	v_and_b32_e32 v169, 31, v169
	v_and_b32_e32 v151, 31, v151
	v_and_b32_e32 v171, 31, v171
	v_and_b32_e32 v150, 31, v150
	v_and_b32_e32 v172, 31, v172
	v_and_b32_e32 v149, 31, v149
	v_and_b32_e32 v173, 31, v173
	v_and_b32_e32 v148, 31, v148
	v_lshl_add_u32 v169, v169, 2, v165
	v_lshl_add_u32 v151, v151, 2, v165
	v_lshl_add_u32 v171, v171, 2, v165
	v_lshl_add_u32 v150, v150, 2, v165
	v_lshl_add_u32 v172, v172, 2, v165
	v_lshl_add_u32 v149, v149, 2, v165
	v_lshl_add_u32 v173, v173, 2, v165
	v_lshl_add_u32 v148, v148, 2, v165
	ds_read_b32 v169, v169
	ds_read_b32 v151, v151
	ds_read_b32 v171, v171
	ds_read_b32 v150, v150
	ds_read_b32 v172, v172
	ds_read_b32 v149, v149
	ds_read_b32 v173, v173
	ds_read_b32 v148, v148
	s_waitcnt lgkmcnt(6)
	v_and_b32_e32 v151, 0x7f, v151
	v_lshlrev_b32_e32 v169, 7, v169
	v_and_or_b32 v169, v169, s40, v151
	s_waitcnt lgkmcnt(4)
	v_and_b32_e32 v150, 0x7f, v150
	v_lshlrev_b32_e32 v151, 7, v171
	v_and_or_b32 v171, v151, s40, v150
	s_waitcnt lgkmcnt(2)
	v_and_b32_e32 v149, 0x7f, v149
	v_lshlrev_b32_e32 v150, 7, v172
	v_and_or_b32 v149, v150, s40, v149
	s_waitcnt lgkmcnt(0)
; DI void gemm256_tile(const Params& p, int mode, int layer, const u16* R, const u16* Cc, int brow, int bcol, lchar* shm, int tid_in, int wid) {
;     ...
;       const float inv = 1.0f / sum;
;       const int hd = brow >> 8;
;       u16* di = W_IDX(p) + (size_t)(bcol + tok) * 128 + hd * 16;
;       float* dg = W_G(p) + (size_t)(bcol + tok) * 128 + hd * 16;
;       unsigned eid[16];
; #pragma unroll
;       for (int k = 0; k < 16; ++k) {
;         const unsigned code = __float_as_uint(v[k]) & 255u;
;         const unsigned i1 = LL[tok * 32 + (((code >> 4) + tok) & 31)] & 127u, i2 = LL[tok * 32 + ((16 + (code & 15u) + tok) & 31)] & 127u;
;         eid[k] = i1 * 128u + i2;
;       }
; #pragma unroll
;       for (int q = 0; q < 4; ++q) *(f32x4*)(dg + 4 * q) = (f32x4){e[4 * q] * inv, e[4 * q + 1] * inv, e[4 * q + 2] * inv, e[4 * q + 3] * inv};
; #pragma unroll
;       for (int q = 0; q < 2; ++q)
;         *(u32x4*)(di + 8 * q) = (u32x4){eid[8 * q] | (eid[8 * q + 1] << 16), eid[8 * q + 2] | (eid[8 * q + 3] << 16), eid[8 * q + 4] | (eid[8 * q + 5] << 16), eid[8 * q + 6] | (eid[8 * q + 7] << 16)};
	v_and_b32_e32 v148, 0x7f, v148
	v_lshlrev_b32_e32 v150, 7, v173
	v_and_or_b32 v172, v150, s40, v148
	v_bfe_u32 v148, v159, 4, 4
	v_or_b32_e32 v150, 16, v159
	v_bfe_u32 v151, v158, 4, 4
	v_or_b32_e32 v158, 16, v158
	v_bfe_u32 v159, v155, 4, 4
	v_or_b32_e32 v155, 16, v155
	v_bfe_u32 v173, v152, 4, 4
	v_or_b32_e32 v152, 16, v152
	v_add_u32_e32 v148, v148, v163
	v_add_u32_e32 v150, v150, v163
	v_add_u32_e32 v151, v151, v163
	v_add_u32_e32 v158, v158, v163
	v_add_u32_e32 v159, v159, v163
	v_add_u32_e32 v155, v155, v163
	v_add_u32_e32 v173, v173, v163
	v_add_u32_e32 v152, v152, v163
	v_and_b32_e32 v148, 31, v148
	v_and_b32_e32 v150, 31, v150
	v_and_b32_e32 v151, 31, v151
	v_and_b32_e32 v158, 31, v158
	v_and_b32_e32 v159, 31, v159
	v_and_b32_e32 v155, 31, v155
	v_and_b32_e32 v173, 31, v173
	v_and_b32_e32 v152, 31, v152
	v_lshl_add_u32 v148, v148, 2, v165
	v_lshl_add_u32 v150, v150, 2, v165
	v_lshl_add_u32 v151, v151, 2, v165
	v_lshl_add_u32 v158, v158, 2, v165
	v_lshl_add_u32 v159, v159, 2, v165
	v_lshl_add_u32 v155, v155, 2, v165
	v_lshl_add_u32 v173, v173, 2, v165
	v_lshl_add_u32 v152, v152, 2, v165
	ds_read_b32 v148, v148
	ds_read_b32 v150, v150
	ds_read_b32 v151, v151
	ds_read_b32 v158, v158
	ds_read_b32 v159, v159
	ds_read_b32 v155, v155
	ds_read_b32 v173, v173
	ds_read_b32 v152, v152
	s_waitcnt lgkmcnt(6)
	v_and_b32_e32 v150, 0x7f, v150
	v_lshlrev_b32_e32 v148, 7, v148
	v_and_or_b32 v174, v148, s40, v150
	s_waitcnt lgkmcnt(4)
	v_and_b32_e32 v148, 0x7f, v158
	v_lshlrev_b32_e32 v150, 7, v151
	v_and_or_b32 v158, v150, s40, v148
	s_waitcnt lgkmcnt(2)
	v_and_b32_e32 v148, 0x7f, v155
	v_lshlrev_b32_e32 v150, 7, v159
	v_and_or_b32 v155, v150, s40, v148
	s_waitcnt lgkmcnt(0)
	v_and_b32_e32 v148, 0x7f, v152
	v_lshlrev_b32_e32 v150, 7, v173
	v_and_or_b32 v159, v150, s40, v148
	v_bfe_u32 v148, v154, 4, 4
	v_or_b32_e32 v150, 16, v154
	v_bfe_u32 v151, v153, 4, 4
	v_or_b32_e32 v152, 16, v153
	v_bfe_u32 v153, v156, 4, 4
	v_or_b32_e32 v154, 16, v156
	v_bfe_u32 v156, v157, 4, 4
	v_or_b32_e32 v157, 16, v157
	v_add_u32_e32 v148, v148, v163
	v_add_u32_e32 v150, v150, v163
	v_add_u32_e32 v151, v151, v163
	v_add_u32_e32 v152, v152, v163
	v_add_u32_e32 v153, v153, v163
	v_add_u32_e32 v154, v154, v163
	v_add_u32_e32 v156, v156, v163
	v_add_u32_e32 v157, v157, v163
	v_and_b32_e32 v148, 31, v148
	v_and_b32_e32 v150, 31, v150
	v_and_b32_e32 v151, 31, v151
	v_and_b32_e32 v152, 31, v152
	v_and_b32_e32 v153, 31, v153
	v_and_b32_e32 v154, 31, v154
	v_and_b32_e32 v156, 31, v156
	v_and_b32_e32 v157, 31, v157
	v_lshl_add_u32 v148, v148, 2, v165
	v_lshl_add_u32 v150, v150, 2, v165
	v_lshl_add_u32 v151, v151, 2, v165
	v_lshl_add_u32 v152, v152, 2, v165
	v_lshl_add_u32 v153, v153, 2, v165
	v_lshl_add_u32 v154, v154, 2, v165
	v_lshl_add_u32 v156, v156, 2, v165
	v_lshl_add_u32 v157, v157, 2, v165
	ds_read_b32 v148, v148
	ds_read_b32 v150, v150
	ds_read_b32 v151, v151
	ds_read_b32 v152, v152
	ds_read_b32 v153, v153
	ds_read_b32 v154, v154
	ds_read_b32 v156, v156
	ds_read_b32 v157, v157
	s_waitcnt lgkmcnt(6)
	v_and_b32_e32 v150, 0x7f, v150
	v_lshlrev_b32_e32 v148, 7, v148
	v_ashrrev_i32_e32 v145, 31, v144
	v_readlane_b32 s4, v255, 30
	v_and_or_b32 v163, v148, s40, v150
	s_waitcnt lgkmcnt(4)
	v_and_b32_e32 v148, 0x7f, v152
	v_lshlrev_b32_e32 v150, 7, v151
	v_lshlrev_b64 v[146:147], 9, v[144:145]
	v_readlane_b32 s5, v255, 31
	v_and_or_b32 v165, v150, s40, v148
	s_waitcnt lgkmcnt(2)
	v_and_b32_e32 v148, 0x7f, v154
	v_lshlrev_b32_e32 v150, 7, v153
	v_lshl_add_u64 v[146:147], s[4:5], 0, v[146:147]
	v_and_or_b32 v154, v150, s40, v148
	v_div_scale_f32 v148, s[4:5], v170, v170, 1.0
	v_rcp_f32_e32 v150, v148
	s_waitcnt lgkmcnt(0)
	v_and_b32_e32 v151, 0x7f, v157
	v_lshlrev_b32_e32 v152, 7, v156
	v_and_or_b32 v156, v152, s40, v151
	v_fma_f32 v151, -v148, v150, 1.0
	v_fmac_f32_e32 v150, v151, v150
	v_div_scale_f32 v151, vcc, 1.0, v170, 1.0
	v_mul_f32_e32 v152, v151, v150
	v_fma_f32 v153, -v148, v152, v151
	v_fmac_f32_e32 v152, v153, v150
	v_fma_f32 v148, -v148, v152, v151
	s_lshl_b32 s0, s13, 4
	v_div_fmas_f32 v148, v148, v150, v152
	s_ashr_i32 s1, s0, 31
	v_div_fixup_f32 v148, v148, v170, 1.0
	v_lshlrev_b64 v[144:145], 8, v[144:145]
	v_lshl_add_u64 v[152:153], s[0:1], 2, v[146:147]
	v_pk_mul_f32 v[146:147], v[132:133], v[148:149] op_sel_hi:[1,0]
	v_pk_mul_f32 v[132:133], v[136:137], v[148:149] op_sel_hi:[1,0]
	v_pk_mul_f32 v[130:131], v[130:131], v[148:149] op_sel_hi:[1,0]
	v_lshl_add_u64 v[150:151], s[66:67], 0, v[144:145]
	v_pk_mul_f32 v[144:145], v[128:129], v[148:149] op_sel_hi:[1,0]
	global_store_dwordx4 v[152:153], v[130:133], off offset:16
	v_pk_mul_f32 v[128:129], v[134:135], v[148:149] op_sel_hi:[1,0]
	global_store_dwordx4 v[152:153], v[144:147], off
	v_pk_mul_f32 v[130:131], v[140:141], v[148:149] op_sel_hi:[1,0]
	global_store_dwordx4 v[152:153], v[128:131], off offset:32
	v_lshl_add_u64 v[132:133], s[0:1], 1, v[150:151]
	s_nop 0
	v_pk_mul_f32 v[130:131], v[142:143], v[148:149] op_sel_hi:[1,0]
	v_pk_mul_f32 v[128:129], v[138:139], v[148:149] op_sel_hi:[1,0]
	global_store_dwordx4 v[152:153], v[128:131], off offset:48
	s_nop 1
	v_lshl_or_b32 v128, v168, 16, v164
	v_lshl_or_b32 v129, v166, 16, v167
	v_lshl_or_b32 v130, v171, 16, v169
	v_lshl_or_b32 v131, v172, 16, v149
	global_store_dwordx4 v[132:133], v[128:131], off
	s_nop 1
	v_lshl_or_b32 v128, v158, 16, v174
	v_lshl_or_b32 v129, v159, 16, v155
	v_lshl_or_b32 v130, v165, 16, v163
	v_lshl_or_b32 v131, v156, 16, v154
	global_store_dwordx4 v[132:133], v[128:131], off offset:16

; #define DPP_MAX(v, ctrl) fmaxf((v), __int_as_float(__builtin_amdgcn_update_dpp(0, __float_as_int(v), (ctrl), 0xf, 0xf, true)))
; DI float wave_max_nonneg(float v) {
;   v = DPP_MAX(v, 0xB1); v = DPP_MAX(v, 0x4E); v = DPP_MAX(v, 0x141); v = DPP_MAX(v, 0x140);
;   const int iv = __float_as_int(v);
;   return fmaxf(fmaxf(__int_as_float(__builtin_amdgcn_readlane(iv, 0)), __int_as_float(__builtin_amdgcn_readlane(iv, 16))),
;                fmaxf(__int_as_float(__builtin_amdgcn_readlane(iv, 32)), __int_as_float(__builtin_amdgcn_readlane(iv, 48))));
; DI void convert_tables(const Params& p, int layer, int lane, int slot, int nslots) {
;     ...
;     const float* src = (isv ? P_PEER_V(p) : P_PEER_U(p)) + ((size_t)layer * PEER_N + e) * DM + 16 * lane;
;     f32x4 a[4];
; #pragma unroll
;     for (int k = 0; k < 4; ++k) a[k] = *(const f32x4*)(src + 4 * k);
;     float am = 0.f;
; #pragma unroll
;     for (int k = 0; k < 4; ++k) am = fmaxf(am, fmaxf(fmaxf(fabsf(a[k][0]), fabsf(a[k][1])), fmaxf(fabsf(a[k][2]), fabsf(a[k][3]))));
;     am = wave_max_nonneg(am);
;     const float top = isv ? 224.0f : 127.0f;
;     const float sc = am > 0.f ? top / am : 1.0f;
;     if (lane == 0) (isv ? W_SV(p) : W_SU(p))[e] = am > 0.f ? am / top : 1.0f;
.LBB0_251:
	s_cmpk_lt_i32 s12, 0x4000
	s_cselect_b64 s[56:57], -1, 0
	s_add_i32 s10, s12, 0xffffc000
	s_cmpk_gt_i32 s12, 0x3fff
	s_cselect_b64 s[4:5], -1, 0
	s_and_b64 s[6:7], s[4:5], exec
	v_readlane_b32 s24, v253, 6
	s_cselect_b32 s10, s10, s12
	v_readlane_b32 s26, v253, 8
	v_readlane_b32 s27, v253, 9
	v_readlane_b32 s28, v253, 10
	v_readlane_b32 s29, v253, 11
	s_cselect_b32 s6, s29, s27
	s_cselect_b32 s7, s28, s26
	s_ashr_i32 s11, s10, 31
	s_add_u32 s13, s7, s8
	s_addc_u32 s21, s6, s9
	s_lshl_b64 s[6:7], s[10:11], 12
	s_add_u32 s6, s13, s6
	s_addc_u32 s7, s21, s7
	global_load_dwordx4 v[0:3], v18, s[6:7] offset:48
	s_waitcnt lgkmcnt(0)
	global_load_dwordx4 v[4:7], v18, s[6:7] offset:32
	global_load_dwordx4 v[8:11], v18, s[6:7] offset:16
	global_load_dwordx4 v[12:15], v18, s[6:7]
	v_readlane_b32 s25, v253, 7
	v_readlane_b32 s30, v253, 12
	v_readlane_b32 s31, v253, 13
	s_waitcnt vmcnt(0)
	v_max_f32_e64 v22, |v2|, |v2|
	v_max_f32_e64 v21, |v10|, |v10|
	v_max_f32_e64 v19, |v15|, |v15|
	v_max_f32_e64 v20, |v14|, |v14|
	v_max_f32_e32 v19, v20, v19
	v_max_f32_e64 v20, |v11|, |v11|
	v_max_f32_e32 v20, v21, v20
	v_max3_f32 v19, |v12|, |v13|, v19
	v_max3_f32 v20, |v8|, |v9|, v20
	v_max3_f32 v19, v19, 0, v20
	v_max_f32_e64 v20, |v7|, |v7|
	v_max_f32_e64 v21, |v6|, |v6|
	v_max_f32_e32 v20, v21, v20
	v_max_f32_e64 v21, |v3|, |v3|
	v_max_f32_e32 v21, v22, v21
	v_max3_f32 v20, |v4|, |v5|, v20
	v_max3_f32 v21, |v0|, |v1|, v21
	v_max3_f32 v19, v19, v20, v21
	s_nop 1
	v_mov_b32_dpp v20, v19 quad_perm:[1,0,3,2] row_mask:0xf bank_mask:0xf bound_ctrl:1
	v_max_f32_e32 v19, v19, v20
	s_nop 1
	v_mov_b32_dpp v20, v19 quad_perm:[2,3,0,1] row_mask:0xf bank_mask:0xf bound_ctrl:1
	v_max_f32_e32 v19, v19, v20
	s_nop 1
	v_mov_b32_dpp v20, v19 row_half_mirror row_mask:0xf bank_mask:0xf bound_ctrl:1
	v_max_f32_e32 v19, v19, v20
	s_nop 1
	v_mov_b32_dpp v20, v19 row_mirror row_mask:0xf bank_mask:0xf bound_ctrl:1
	v_max_f32_e32 v19, v19, v20
	s_nop 0
	v_readlane_b32 s13, v19, 32
	v_readlane_b32 s21, v19, 48
	v_readlane_b32 s6, v19, 0
	v_readlane_b32 s7, v19, 16
	v_max_f32_e64 v19, s21, s21
	v_max_f32_e64 v20, s13, s13
	v_max_f32_e32 v19, v20, v19
	v_mov_b32_e32 v20, s7
	v_max3_f32 v19, s6, v20, v19
	v_cndmask_b32_e64 v20, v194, v252, s[4:5]
	v_cmp_lt_f32_e64 s[6:7], 0, v19
	s_and_saveexec_b64 s[78:79], s[0:1]
	s_cbranch_execz .LBB0_253
	v_div_scale_f32 v21, s[28:29], v20, v20, v19
	v_rcp_f32_e32 v22, v21
	v_div_scale_f32 v23, vcc, v19, v20, v19
	s_and_b64 s[4:5], s[4:5], exec
	v_fma_f32 v24, -v21, v22, 1.0
	v_fmac_f32_e32 v22, v24, v22
	v_mul_f32_e32 v24, v23, v22
	v_fma_f32 v25, -v21, v24, v23
	s_mov_b32 s4, 0x6210000
	v_fmac_f32_e32 v24, v25, v22
	s_cselect_b32 s4, s4, 0x6200000
	v_fma_f32 v21, -v21, v24, v23
	s_add_u32 s13, s34, s4
	v_div_fmas_f32 v21, v21, v22, v24
	s_addc_u32 s21, s35, 0
	s_lshl_b64 s[4:5], s[10:11], 2
	v_div_fixup_f32 v21, v21, v20, v19
	s_add_u32 s4, s13, s4
	v_cndmask_b32_e64 v21, 1.0, v21, s[6:7]
	s_addc_u32 s5, s21, s5
	global_store_dword v177, v21, s[4:5]
